# g1_remove_vmcnt0_drains_in_gemm_kloops
# speedup vs baseline: 1.0444x; 1.0444x over previous
; #define PG8_STAGE(bufoff, gbase, voff) do { _Pragma("unroll") for (int _i = 0; _i < 2; ++_i) \
;         __builtin_amdgcn_global_load_lds((const unsigned*)((const char*)(gbase) + (voff)[_i]), (PG8_LAS unsigned*)(lds + (bufoff) + ldsw + _i * 8192), 16, 0, 0); } while (0)
; #define PG8_LDA(dst, b, h) do { _Pragma("unroll") for (int m = 0; m < 4; ++m) _Pragma("unroll") for (int k = 0; k < 2; ++k) dst[m][k] = *(const PG8_LAS bf16x8*)(lds + PG8_SA(b, h) + aoff + m * 2048 + k * 1024); } while (0)
; #define PG8_LDB(dst, b, h) do { _Pragma("unroll") for (int n = 0; n < 2; ++n) _Pragma("unroll") for (int k = 0; k < 2; ++k) dst[n][k] = *(const PG8_LAS bf16x8*)(lds + PG8_SB(b, h) + boff + n * 2048 + k * 1024); } while (0)
; #define PG8_MMA(ai, bj, At, Bt) do { __builtin_amdgcn_s_setprio(1); _Pragma("unroll") for (int m = 0; m < 4; ++m) _Pragma("unroll") for (int n = 0; n < 2; ++n) _Pragma("unroll") for (int k = 0; k < 2; ++k) \
;         acc[ai][bj][m][n] = __builtin_amdgcn_mfma_f32_16x16x32_bf16(Bt[n][k], At[m][k], acc[ai][bj][m][n], 0, 0, 0); __builtin_amdgcn_s_setprio(0); } while (0)
; #define PG8_WAIT_V(n) asm volatile("s_waitcnt vmcnt(" #n ")" ::: "memory")
; #define PG8_WAIT_L(n) asm volatile("s_waitcnt lgkmcnt(" #n ")" ::: "memory")
; #define PG8_BAR __builtin_amdgcn_s_barrier()
; #define PG8_SCHED __builtin_amdgcn_sched_barrier(0)
; template <class Epi, class Sched, bool ALIGN_EPI = false, bool SP2 = false>
; __device__ __forceinline__ void gemm_phase(PG8_LAS unsigned char* lds, const Gemm g, const Sched& S, const Epi& E) {
;     ...
;             const bool last = (t == nt - 2);
;             const char* a1 = cA + (size_t)(t + 1) * kstep;
;             const char* a2 = last ? nA : cA + (size_t)(t + 2) * kstep; const char* b2 = last ? nB : cB + (size_t)(t + 2) * kstep;
;             const char* a3 = a2 + kstep; const char* b3 = b2 + kstep;
;             if (last && has_next) S.a_ready(nxt);
;             if constexpr (SP2) {
;             PG8_LDB(B0, 0, 0); PG8_LDB(B1, 0, 1); PG8_SCHED; PG8_LDA(At, 0, 0); PG8_STAGE(PG8_SA(1, 1), a1 + hstepA, voffA);
;             PG8_WAIT_V(8); PG8_WAIT_L(0); PG8_BAR; PG8_MMA(0, 0, At, B0); PG8_MMA(0, 1, At, B1); PG8_BAR; PG8_SCHED;
;             PG8_LDA(At, 0, 1); PG8_STAGE(PG8_SB(0, 0), b2, voffB); PG8_STAGE(PG8_SB(0, 1), b2 + hstepB, voffB); PG8_STAGE(PG8_SA(0, 0), a2, voffA);
.LBB0_183:
	ds_read_b128 v[146:149], v154
	ds_read_b128 v[170:173], v155
	ds_read_b128 v[174:177], v156
	ds_read_b128 v[178:181], v157
	ds_read_b128 v[182:185], v158
	ds_read_b128 v[186:189], v159
	ds_read_b128 v[190:193], v160
	ds_read_b128 v[194:197], v161
	s_add_u32 s22, s20, 0xfffc0080
	s_addc_u32 s23, s21, -1
	s_cmp_eq_u32 s64, 12
	s_cselect_b32 s25, s1, s23
	s_cselect_b32 s24, s5, s22
	s_cselect_b32 s23, s13, s63
	s_cselect_b32 s22, s15, s62
	s_mov_b32 m0, s46
	v_lshl_add_u64 v[150:151], s[20:21], 0, v[138:139]
	ds_read_b128 v[198:201], v152
	ds_read_b128 v[202:205], v152 offset:1024
	ds_read_b128 v[206:209], v152 offset:2048
	ds_read_b128 v[210:213], v152 offset:3072
	ds_read_b128 v[214:217], v152 offset:4096
	ds_read_b128 v[218:221], v152 offset:5120
	ds_read_b128 v[222:225], v152 offset:6144
	ds_read_b128 v[226:229], v152 offset:7168
	global_load_lds_dwordx4 v[150:151], off
	v_lshl_add_u64 v[150:151], s[20:21], 0, v[140:141]
	s_mov_b32 m0, s47
	s_nop 0
	global_load_lds_dwordx4 v[150:151], off
	s_waitcnt vmcnt(8)
	s_waitcnt lgkmcnt(0)
	s_barrier
	s_setprio 1
	s_waitcnt lgkmcnt(0)
	v_mfma_f32_16x16x32_bf16 v[124:127], v[146:149], v[198:201], v[124:127]
	v_mfma_f32_16x16x32_bf16 v[120:123], v[174:177], v[198:201], v[120:123]
	v_mfma_f32_16x16x32_bf16 v[108:111], v[146:149], v[206:209], v[108:111]
	v_mfma_f32_16x16x32_bf16 v[104:107], v[174:177], v[206:209], v[104:107]
	v_mfma_f32_16x16x32_bf16 v[92:95], v[146:149], v[214:217], v[92:95]
	v_mfma_f32_16x16x32_bf16 v[88:91], v[174:177], v[214:217], v[88:91]
	v_mfma_f32_16x16x32_bf16 v[76:79], v[146:149], v[222:225], v[76:79]
	v_mfma_f32_16x16x32_bf16 v[72:75], v[174:177], v[222:225], v[72:75]
	v_mfma_f32_16x16x32_bf16 v[124:127], v[170:173], v[202:205], v[124:127]
	v_mfma_f32_16x16x32_bf16 v[120:123], v[178:181], v[202:205], v[120:123]
	v_mfma_f32_16x16x32_bf16 v[108:111], v[170:173], v[210:213], v[108:111]
	v_mfma_f32_16x16x32_bf16 v[104:107], v[178:181], v[210:213], v[104:107]
	v_mfma_f32_16x16x32_bf16 v[92:95], v[170:173], v[218:221], v[92:95]
	v_mfma_f32_16x16x32_bf16 v[88:91], v[178:181], v[218:221], v[88:91]
	v_mfma_f32_16x16x32_bf16 v[76:79], v[170:173], v[226:229], v[76:79]
	v_mfma_f32_16x16x32_bf16 v[72:75], v[178:181], v[226:229], v[72:75]
	s_setprio 0
	s_setprio 1
	v_mfma_f32_16x16x32_bf16 v[116:119], v[182:185], v[198:201], v[116:119]
	v_mfma_f32_16x16x32_bf16 v[112:115], v[190:193], v[198:201], v[112:115]
	v_mfma_f32_16x16x32_bf16 v[100:103], v[182:185], v[206:209], v[100:103]
	v_mfma_f32_16x16x32_bf16 v[96:99], v[190:193], v[206:209], v[96:99]
	v_mfma_f32_16x16x32_bf16 v[84:87], v[182:185], v[214:217], v[84:87]
	v_mfma_f32_16x16x32_bf16 v[80:83], v[190:193], v[214:217], v[80:83]
	v_mfma_f32_16x16x32_bf16 v[68:71], v[182:185], v[222:225], v[68:71]
	v_mfma_f32_16x16x32_bf16 v[64:67], v[190:193], v[222:225], v[64:67]
	v_mfma_f32_16x16x32_bf16 v[116:119], v[186:189], v[202:205], v[116:119]
	v_mfma_f32_16x16x32_bf16 v[112:115], v[194:197], v[202:205], v[112:115]
	v_mfma_f32_16x16x32_bf16 v[100:103], v[186:189], v[210:213], v[100:103]
	v_mfma_f32_16x16x32_bf16 v[96:99], v[194:197], v[210:213], v[96:99]
	v_mfma_f32_16x16x32_bf16 v[84:87], v[186:189], v[218:221], v[84:87]
	v_mfma_f32_16x16x32_bf16 v[80:83], v[194:197], v[218:221], v[80:83]
	v_mfma_f32_16x16x32_bf16 v[68:71], v[186:189], v[226:229], v[68:71]
	v_mfma_f32_16x16x32_bf16 v[64:67], v[194:197], v[226:229], v[64:67]
	s_setprio 0
	s_barrier
	s_mov_b32 m0, s28
	v_lshl_add_u64 v[150:151], s[22:23], 0, v[132:133]
	s_add_u32 s56, s22, 0x40000
	ds_read_b128 v[198:201], v152 offset:16384
	ds_read_b128 v[202:205], v152 offset:17408
	ds_read_b128 v[206:209], v152 offset:18432
	ds_read_b128 v[210:213], v152 offset:19456
	ds_read_b128 v[214:217], v152 offset:20480
	ds_read_b128 v[218:221], v152 offset:21504
	ds_read_b128 v[222:225], v152 offset:22528
	ds_read_b128 v[226:229], v152 offset:23552
	global_load_lds_dwordx4 v[150:151], off
	v_lshl_add_u64 v[230:231], s[22:23], 0, v[136:137]
	s_mov_b32 m0, s29
	s_addc_u32 s57, s23, 0
	global_load_lds_dwordx4 v[230:231], off
	v_lshl_add_u64 v[232:233], s[56:57], 0, v[132:133]
	s_mov_b32 m0, s30
	v_lshl_add_u64 v[234:235], s[24:25], 0, v[134:135]
	global_load_lds_dwordx4 v[232:233], off
	v_lshl_add_u64 v[232:233], s[56:57], 0, v[136:137]
	s_mov_b32 m0, s31
	s_nop 0
	global_load_lds_dwordx4 v[232:233], off
	v_lshl_add_u64 v[232:233], s[24:25], 0, v[130:131]
	s_mov_b32 m0, s27
	s_nop 0
	global_load_lds_dwordx4 v[232:233], off
	s_mov_b32 m0, s33
	s_nop 0
	global_load_lds_dwordx4 v[234:235], off
	s_waitcnt vmcnt(8)
	s_waitcnt lgkmcnt(0)
	s_barrier
; #define PG8_STAGE(bufoff, gbase, voff) do { _Pragma("unroll") for (int _i = 0; _i < 2; ++_i) \
;         __builtin_amdgcn_global_load_lds((const unsigned*)((const char*)(gbase) + (voff)[_i]), (PG8_LAS unsigned*)(lds + (bufoff) + ldsw + _i * 8192), 16, 0, 0); } while (0)
; #define PG8_LDA(dst, b, h) do { _Pragma("unroll") for (int m = 0; m < 4; ++m) _Pragma("unroll") for (int k = 0; k < 2; ++k) dst[m][k] = *(const PG8_LAS bf16x8*)(lds + PG8_SA(b, h) + aoff + m * 2048 + k * 1024); } while (0)
; #define PG8_LDB(dst, b, h) do { _Pragma("unroll") for (int n = 0; n < 2; ++n) _Pragma("unroll") for (int k = 0; k < 2; ++k) dst[n][k] = *(const PG8_LAS bf16x8*)(lds + PG8_SB(b, h) + boff + n * 2048 + k * 1024); } while (0)
; #define PG8_MMA(ai, bj, At, Bt) do { __builtin_amdgcn_s_setprio(1); _Pragma("unroll") for (int m = 0; m < 4; ++m) _Pragma("unroll") for (int n = 0; n < 2; ++n) _Pragma("unroll") for (int k = 0; k < 2; ++k) \
;         acc[ai][bj][m][n] = __builtin_amdgcn_mfma_f32_16x16x32_bf16(Bt[n][k], At[m][k], acc[ai][bj][m][n], 0, 0, 0); __builtin_amdgcn_s_setprio(0); } while (0)
; #define PG8_WAIT_V(n) asm volatile("s_waitcnt vmcnt(" #n ")" ::: "memory")
; #define PG8_WAIT_L(n) asm volatile("s_waitcnt lgkmcnt(" #n ")" ::: "memory")
; #define PG8_BAR __builtin_amdgcn_s_barrier()
; #define PG8_SCHED __builtin_amdgcn_sched_barrier(0)
; template <class Epi, class Sched, bool ALIGN_EPI = false, bool SP2 = false>
; __device__ __forceinline__ void gemm_phase(PG8_LAS unsigned char* lds, const Gemm g, const Sched& S, const Epi& E) {
;     ...
;             PG8_WAIT_V(8); PG8_WAIT_L(0); PG8_BAR; PG8_MMA(1, 0, At, B0); PG8_MMA(1, 1, At, B1); PG8_BAR; PG8_SCHED;
;             PG8_LDB(B0, 1, 0); PG8_LDB(B1, 1, 1); PG8_SCHED; PG8_LDA(At, 1, 0); PG8_STAGE(PG8_SA(0, 1), a2 + hstepA, voffA);
;             PG8_WAIT_V(8); PG8_WAIT_L(0); PG8_BAR; PG8_MMA(0, 0, At, B0); PG8_MMA(0, 1, At, B1); PG8_BAR; PG8_SCHED;
	s_setprio 1
	s_waitcnt lgkmcnt(0)
	v_mfma_f32_16x16x32_bf16 v[60:63], v[146:149], v[198:201], v[60:63]
	v_mfma_f32_16x16x32_bf16 v[56:59], v[174:177], v[198:201], v[56:59]
	v_mfma_f32_16x16x32_bf16 v[44:47], v[146:149], v[206:209], v[44:47]
	v_mfma_f32_16x16x32_bf16 v[40:43], v[174:177], v[206:209], v[40:43]
	v_mfma_f32_16x16x32_bf16 v[28:31], v[146:149], v[214:217], v[28:31]
	v_mfma_f32_16x16x32_bf16 v[24:27], v[174:177], v[214:217], v[24:27]
	v_mfma_f32_16x16x32_bf16 v[12:15], v[146:149], v[222:225], v[12:15]
	v_mfma_f32_16x16x32_bf16 v[8:11], v[174:177], v[222:225], v[8:11]
	v_mfma_f32_16x16x32_bf16 v[60:63], v[170:173], v[202:205], v[60:63]
	v_mfma_f32_16x16x32_bf16 v[56:59], v[178:181], v[202:205], v[56:59]
	v_mfma_f32_16x16x32_bf16 v[44:47], v[170:173], v[210:213], v[44:47]
	v_mfma_f32_16x16x32_bf16 v[40:43], v[178:181], v[210:213], v[40:43]
	v_mfma_f32_16x16x32_bf16 v[28:31], v[170:173], v[218:221], v[28:31]
	v_mfma_f32_16x16x32_bf16 v[24:27], v[178:181], v[218:221], v[24:27]
	v_mfma_f32_16x16x32_bf16 v[12:15], v[170:173], v[226:229], v[12:15]
	v_mfma_f32_16x16x32_bf16 v[8:11], v[178:181], v[226:229], v[8:11]
	s_setprio 0
	s_setprio 1
	v_mfma_f32_16x16x32_bf16 v[52:55], v[182:185], v[198:201], v[52:55]
	v_mfma_f32_16x16x32_bf16 v[48:51], v[190:193], v[198:201], v[48:51]
	v_mfma_f32_16x16x32_bf16 v[36:39], v[182:185], v[206:209], v[36:39]
	v_mfma_f32_16x16x32_bf16 v[32:35], v[190:193], v[206:209], v[32:35]
	v_mfma_f32_16x16x32_bf16 v[20:23], v[182:185], v[214:217], v[20:23]
	v_mfma_f32_16x16x32_bf16 v[16:19], v[190:193], v[214:217], v[16:19]
	v_mfma_f32_16x16x32_bf16 v[4:7], v[182:185], v[222:225], v[4:7]
	v_mfma_f32_16x16x32_bf16 v[0:3], v[190:193], v[222:225], v[0:3]
	v_mfma_f32_16x16x32_bf16 v[52:55], v[186:189], v[202:205], v[52:55]
	v_mfma_f32_16x16x32_bf16 v[48:51], v[194:197], v[202:205], v[48:51]
	v_mfma_f32_16x16x32_bf16 v[36:39], v[186:189], v[210:213], v[36:39]
	v_mfma_f32_16x16x32_bf16 v[32:35], v[194:197], v[210:213], v[32:35]
	v_mfma_f32_16x16x32_bf16 v[20:23], v[186:189], v[218:221], v[20:23]
	v_mfma_f32_16x16x32_bf16 v[16:19], v[194:197], v[218:221], v[16:19]
	v_mfma_f32_16x16x32_bf16 v[4:7], v[186:189], v[226:229], v[4:7]
	v_mfma_f32_16x16x32_bf16 v[0:3], v[194:197], v[226:229], v[0:3]
	s_setprio 0
	s_barrier
	ds_read_b128 v[146:149], v162
	ds_read_b128 v[170:173], v163
	ds_read_b128 v[174:177], v164
	ds_read_b128 v[178:181], v165
	ds_read_b128 v[182:185], v166
	ds_read_b128 v[186:189], v167
	ds_read_b128 v[190:193], v168
	ds_read_b128 v[194:197], v169
	s_add_u32 s24, s24, 0x40000
	s_addc_u32 s25, s25, 0
	s_mov_b32 m0, s34
	v_lshl_add_u64 v[236:237], s[24:25], 0, v[130:131]
	ds_read_b128 v[198:201], v152 offset:32768
	ds_read_b128 v[202:205], v152 offset:33792
	ds_read_b128 v[206:209], v152 offset:34816
	ds_read_b128 v[210:213], v152 offset:35840
	ds_read_b128 v[214:217], v152 offset:36864
	ds_read_b128 v[218:221], v152 offset:37888
	ds_read_b128 v[222:225], v152 offset:38912
	ds_read_b128 v[226:229], v152 offset:39936
	global_load_lds_dwordx4 v[236:237], off
	v_lshl_add_u64 v[236:237], s[24:25], 0, v[134:135]
	s_mov_b32 m0, s35
	s_nop 0
	global_load_lds_dwordx4 v[236:237], off
	s_waitcnt vmcnt(8)
	s_waitcnt lgkmcnt(0)
	s_barrier
	s_setprio 1
	s_waitcnt lgkmcnt(0)
	v_mfma_f32_16x16x32_bf16 v[124:127], v[146:149], v[198:201], v[124:127]
	v_mfma_f32_16x16x32_bf16 v[120:123], v[174:177], v[198:201], v[120:123]
	v_mfma_f32_16x16x32_bf16 v[108:111], v[146:149], v[206:209], v[108:111]
	v_mfma_f32_16x16x32_bf16 v[104:107], v[174:177], v[206:209], v[104:107]
	v_mfma_f32_16x16x32_bf16 v[92:95], v[146:149], v[214:217], v[92:95]
	v_mfma_f32_16x16x32_bf16 v[88:91], v[174:177], v[214:217], v[88:91]
	v_mfma_f32_16x16x32_bf16 v[76:79], v[146:149], v[222:225], v[76:79]
	v_mfma_f32_16x16x32_bf16 v[72:75], v[174:177], v[222:225], v[72:75]
	v_mfma_f32_16x16x32_bf16 v[124:127], v[170:173], v[202:205], v[124:127]
	v_mfma_f32_16x16x32_bf16 v[120:123], v[178:181], v[202:205], v[120:123]
	v_mfma_f32_16x16x32_bf16 v[108:111], v[170:173], v[210:213], v[108:111]
	v_mfma_f32_16x16x32_bf16 v[104:107], v[178:181], v[210:213], v[104:107]
	v_mfma_f32_16x16x32_bf16 v[92:95], v[170:173], v[218:221], v[92:95]
	v_mfma_f32_16x16x32_bf16 v[88:91], v[178:181], v[218:221], v[88:91]
	v_mfma_f32_16x16x32_bf16 v[76:79], v[170:173], v[226:229], v[76:79]
	v_mfma_f32_16x16x32_bf16 v[72:75], v[178:181], v[226:229], v[72:75]
	s_setprio 0
	s_setprio 1
	v_mfma_f32_16x16x32_bf16 v[116:119], v[182:185], v[198:201], v[116:119]
	v_mfma_f32_16x16x32_bf16 v[112:115], v[190:193], v[198:201], v[112:115]
	v_mfma_f32_16x16x32_bf16 v[100:103], v[182:185], v[206:209], v[100:103]
	v_mfma_f32_16x16x32_bf16 v[96:99], v[190:193], v[206:209], v[96:99]
	v_mfma_f32_16x16x32_bf16 v[84:87], v[182:185], v[214:217], v[84:87]
	v_mfma_f32_16x16x32_bf16 v[80:83], v[190:193], v[214:217], v[80:83]
	v_mfma_f32_16x16x32_bf16 v[68:71], v[182:185], v[222:225], v[68:71]
	v_mfma_f32_16x16x32_bf16 v[64:67], v[190:193], v[222:225], v[64:67]
	v_mfma_f32_16x16x32_bf16 v[116:119], v[186:189], v[202:205], v[116:119]
	v_mfma_f32_16x16x32_bf16 v[112:115], v[194:197], v[202:205], v[112:115]
	v_mfma_f32_16x16x32_bf16 v[100:103], v[186:189], v[210:213], v[100:103]
	v_mfma_f32_16x16x32_bf16 v[96:99], v[194:197], v[210:213], v[96:99]
	v_mfma_f32_16x16x32_bf16 v[84:87], v[186:189], v[218:221], v[84:87]
	v_mfma_f32_16x16x32_bf16 v[80:83], v[194:197], v[218:221], v[80:83]
	v_mfma_f32_16x16x32_bf16 v[68:71], v[186:189], v[226:229], v[68:71]
	v_mfma_f32_16x16x32_bf16 v[64:67], v[194:197], v[226:229], v[64:67]
	s_setprio 0
	s_barrier
; #define PG8_STAGE(bufoff, gbase, voff) do { _Pragma("unroll") for (int _i = 0; _i < 2; ++_i) \
;         __builtin_amdgcn_global_load_lds((const unsigned*)((const char*)(gbase) + (voff)[_i]), (PG8_LAS unsigned*)(lds + (bufoff) + ldsw + _i * 8192), 16, 0, 0); } while (0)
; #define PG8_LDA(dst, b, h) do { _Pragma("unroll") for (int m = 0; m < 4; ++m) _Pragma("unroll") for (int k = 0; k < 2; ++k) dst[m][k] = *(const PG8_LAS bf16x8*)(lds + PG8_SA(b, h) + aoff + m * 2048 + k * 1024); } while (0)
; #define PG8_MMA(ai, bj, At, Bt) do { __builtin_amdgcn_s_setprio(1); _Pragma("unroll") for (int m = 0; m < 4; ++m) _Pragma("unroll") for (int n = 0; n < 2; ++n) _Pragma("unroll") for (int k = 0; k < 2; ++k) \
;         acc[ai][bj][m][n] = __builtin_amdgcn_mfma_f32_16x16x32_bf16(Bt[n][k], At[m][k], acc[ai][bj][m][n], 0, 0, 0); __builtin_amdgcn_s_setprio(0); } while (0)
; #define PG8_WAIT_V(n) asm volatile("s_waitcnt vmcnt(" #n ")" ::: "memory")
; #define PG8_WAIT_L(n) asm volatile("s_waitcnt lgkmcnt(" #n ")" ::: "memory")
; #define PG8_BAR __builtin_amdgcn_s_barrier()
; #define PG8_SCHED __builtin_amdgcn_sched_barrier(0)
; template <class Epi, class Sched, bool ALIGN_EPI = false, bool SP2 = false>
; __device__ __forceinline__ void gemm_phase(PG8_LAS unsigned char* lds, const Gemm g, const Sched& S, const Epi& E) {
;     ...
;         for (int t = 0; t < nt; t += 2) {
;     ...
;             PG8_LDA(At, 1, 1); PG8_STAGE(PG8_SB(1, 0), b3, voffB); PG8_STAGE(PG8_SB(1, 1), b3 + hstepB, voffB); PG8_STAGE(PG8_SA(1, 0), a3, voffA);
;             PG8_WAIT_V(8); PG8_WAIT_L(0); PG8_BAR; PG8_MMA(1, 0, At, B0); PG8_MMA(1, 1, At, B1); PG8_BAR; PG8_SCHED;
	s_mov_b32 m0, s36
	v_lshl_add_u64 v[150:151], v[150:151], 0, s[8:9]
	s_add_u32 s22, s22, 0x40080
	ds_read_b128 v[198:201], v152 offset:49152
	ds_read_b128 v[202:205], v152 offset:50176
	ds_read_b128 v[206:209], v152 offset:51200
	ds_read_b128 v[210:213], v152 offset:52224
	ds_read_b128 v[214:217], v152 offset:53248
	ds_read_b128 v[218:221], v152 offset:54272
	ds_read_b128 v[222:225], v152 offset:55296
	ds_read_b128 v[226:229], v152 offset:56320
	global_load_lds_dwordx4 v[150:151], off
	v_lshl_add_u64 v[150:151], v[230:231], 0, s[8:9]
	s_mov_b32 m0, s37
	s_addc_u32 s23, s23, 0
	global_load_lds_dwordx4 v[150:151], off
	v_lshl_add_u64 v[150:151], s[22:23], 0, v[132:133]
	s_mov_b32 m0, s40
	s_nop 0
	global_load_lds_dwordx4 v[150:151], off
	v_lshl_add_u64 v[150:151], s[22:23], 0, v[136:137]
	s_mov_b32 m0, s41
	s_nop 0
	global_load_lds_dwordx4 v[150:151], off
	v_lshl_add_u64 v[150:151], v[232:233], 0, s[8:9]
	s_mov_b32 m0, s38
	s_nop 0
	global_load_lds_dwordx4 v[150:151], off
	v_lshl_add_u64 v[150:151], v[234:235], 0, s[8:9]
	s_mov_b32 m0, s39
	s_nop 0
	global_load_lds_dwordx4 v[150:151], off
	s_waitcnt vmcnt(8)
	s_waitcnt lgkmcnt(0)
	s_barrier
	s_setprio 1
	s_waitcnt lgkmcnt(0)
	v_mfma_f32_16x16x32_bf16 v[60:63], v[146:149], v[198:201], v[60:63]
	v_mfma_f32_16x16x32_bf16 v[56:59], v[174:177], v[198:201], v[56:59]
	v_mfma_f32_16x16x32_bf16 v[44:47], v[146:149], v[206:209], v[44:47]
	v_mfma_f32_16x16x32_bf16 v[40:43], v[174:177], v[206:209], v[40:43]
	v_mfma_f32_16x16x32_bf16 v[28:31], v[146:149], v[214:217], v[28:31]
	v_mfma_f32_16x16x32_bf16 v[24:27], v[174:177], v[214:217], v[24:27]
	v_mfma_f32_16x16x32_bf16 v[12:15], v[146:149], v[222:225], v[12:15]
	v_mfma_f32_16x16x32_bf16 v[8:11], v[174:177], v[222:225], v[8:11]
	v_mfma_f32_16x16x32_bf16 v[60:63], v[170:173], v[202:205], v[60:63]
	v_mfma_f32_16x16x32_bf16 v[56:59], v[178:181], v[202:205], v[56:59]
	v_mfma_f32_16x16x32_bf16 v[44:47], v[170:173], v[210:213], v[44:47]
	v_mfma_f32_16x16x32_bf16 v[40:43], v[178:181], v[210:213], v[40:43]
	v_mfma_f32_16x16x32_bf16 v[28:31], v[170:173], v[218:221], v[28:31]
	v_mfma_f32_16x16x32_bf16 v[24:27], v[178:181], v[218:221], v[24:27]
	v_mfma_f32_16x16x32_bf16 v[12:15], v[170:173], v[226:229], v[12:15]
	v_mfma_f32_16x16x32_bf16 v[8:11], v[178:181], v[226:229], v[8:11]
	s_setprio 0
	s_setprio 1
	v_mfma_f32_16x16x32_bf16 v[52:55], v[182:185], v[198:201], v[52:55]
	v_mfma_f32_16x16x32_bf16 v[48:51], v[190:193], v[198:201], v[48:51]
	v_mfma_f32_16x16x32_bf16 v[36:39], v[182:185], v[206:209], v[36:39]
	v_mfma_f32_16x16x32_bf16 v[32:35], v[190:193], v[206:209], v[32:35]
	v_mfma_f32_16x16x32_bf16 v[20:23], v[182:185], v[214:217], v[20:23]
	v_mfma_f32_16x16x32_bf16 v[16:19], v[190:193], v[214:217], v[16:19]
	v_mfma_f32_16x16x32_bf16 v[4:7], v[182:185], v[222:225], v[4:7]
	v_mfma_f32_16x16x32_bf16 v[0:3], v[190:193], v[222:225], v[0:3]
	v_mfma_f32_16x16x32_bf16 v[52:55], v[186:189], v[202:205], v[52:55]
	v_mfma_f32_16x16x32_bf16 v[48:51], v[194:197], v[202:205], v[48:51]
	v_mfma_f32_16x16x32_bf16 v[36:39], v[186:189], v[210:213], v[36:39]
	v_mfma_f32_16x16x32_bf16 v[32:35], v[194:197], v[210:213], v[32:35]
	v_mfma_f32_16x16x32_bf16 v[20:23], v[186:189], v[218:221], v[20:23]
	v_mfma_f32_16x16x32_bf16 v[16:19], v[194:197], v[218:221], v[16:19]
	v_mfma_f32_16x16x32_bf16 v[4:7], v[186:189], v[226:229], v[4:7]
	v_mfma_f32_16x16x32_bf16 v[0:3], v[194:197], v[226:229], v[0:3]
	s_setprio 0
	s_barrier
	s_add_i32 s64, s64, 2
	s_add_u32 s20, s20, 0x100
	s_addc_u32 s21, s21, 0
	s_add_u32 s62, s62, 0x100
	s_addc_u32 s63, s63, 0
	s_cmp_gt_u32 s64, 13
	s_cbranch_scc0 .LBB0_183
	s_and_b64 vcc, exec, s[10:11]
	s_cbranch_vccz .LBB0_186
	s_barrier

; #define PG8_STAGE(bufoff, gbase, voff) do { _Pragma("unroll") for (int _i = 0; _i < 2; ++_i) \
;         __builtin_amdgcn_global_load_lds((const unsigned*)((const char*)(gbase) + (voff)[_i]), (PG8_LAS unsigned*)(lds + (bufoff) + ldsw + _i * 8192), 16, 0, 0); } while (0)
; #define PG8_LDA(dst, b, h) do { _Pragma("unroll") for (int m = 0; m < 4; ++m) _Pragma("unroll") for (int k = 0; k < 2; ++k) dst[m][k] = *(const PG8_LAS bf16x8*)(lds + PG8_SA(b, h) + aoff + m * 2048 + k * 1024); } while (0)
; #define PG8_LDB(dst, b, h) do { _Pragma("unroll") for (int n = 0; n < 2; ++n) _Pragma("unroll") for (int k = 0; k < 2; ++k) dst[n][k] = *(const PG8_LAS bf16x8*)(lds + PG8_SB(b, h) + boff + n * 2048 + k * 1024); } while (0)
; #define PG8_MMA(ai, bj, At, Bt) do { __builtin_amdgcn_s_setprio(1); _Pragma("unroll") for (int m = 0; m < 4; ++m) _Pragma("unroll") for (int n = 0; n < 2; ++n) _Pragma("unroll") for (int k = 0; k < 2; ++k) \
;         acc[ai][bj][m][n] = __builtin_amdgcn_mfma_f32_16x16x32_bf16(Bt[n][k], At[m][k], acc[ai][bj][m][n], 0, 0, 0); __builtin_amdgcn_s_setprio(0); } while (0)
; #define PG8_WAIT_V(n) asm volatile("s_waitcnt vmcnt(" #n ")" ::: "memory")
; #define PG8_WAIT_L(n) asm volatile("s_waitcnt lgkmcnt(" #n ")" ::: "memory")
; #define PG8_BAR __builtin_amdgcn_s_barrier()
; #define PG8_SCHED __builtin_amdgcn_sched_barrier(0)
; template <class Epi, class Sched, bool ALIGN_EPI = false, bool SP2 = false>
; __device__ __forceinline__ void gemm_phase(PG8_LAS unsigned char* lds, const Gemm g, const Sched& S, const Epi& E) {
;     ...
;             const bool last = (t == nt - 2);
;             const char* a1 = cA + (size_t)(t + 1) * kstep;
;             const char* a2 = last ? nA : cA + (size_t)(t + 2) * kstep; const char* b2 = last ? nB : cB + (size_t)(t + 2) * kstep;
;             const char* a3 = a2 + kstep; const char* b3 = b2 + kstep;
;             if (last && has_next) S.a_ready(nxt);
;             if constexpr (SP2) {
;             PG8_LDB(B0, 0, 0); PG8_LDB(B1, 0, 1); PG8_SCHED; PG8_LDA(At, 0, 0); PG8_STAGE(PG8_SA(1, 1), a1 + hstepA, voffA);
;             PG8_WAIT_V(8); PG8_WAIT_L(0); PG8_BAR; PG8_MMA(0, 0, At, B0); PG8_MMA(0, 1, At, B1); PG8_BAR; PG8_SCHED;
;             PG8_LDA(At, 0, 1); PG8_STAGE(PG8_SB(0, 0), b2, voffB); PG8_STAGE(PG8_SB(0, 1), b2 + hstepB, voffB); PG8_STAGE(PG8_SA(0, 0), a2, voffA);
.LBB0_864:
	ds_read_b128 v[148:151], v163
	ds_read_b128 v[152:155], v164
	ds_read_b128 v[156:159], v165
	ds_read_b128 v[180:183], v166
	ds_read_b128 v[184:187], v167
	ds_read_b128 v[188:191], v168
	ds_read_b128 v[192:195], v169
	ds_read_b128 v[196:199], v170
	s_add_u32 s0, s20, 0x100
	s_addc_u32 s1, s21, 0
	s_cmp_eq_u32 s73, 28
	s_cselect_b32 s25, s15, s1
	s_cselect_b32 s24, s14, s0
	s_cselect_b32 s23, s13, s72
	s_cselect_b32 s22, s19, s65
	s_mov_b32 m0, s54
	v_lshl_add_u64 v[232:233], s[20:21], 0, v[140:141]
	ds_read_b128 v[200:203], v161
	ds_read_b128 v[204:207], v161 offset:1024
	ds_read_b128 v[208:211], v161 offset:2048
	ds_read_b128 v[212:215], v161 offset:3072
	ds_read_b128 v[216:219], v161 offset:4096
	ds_read_b128 v[220:223], v161 offset:5120
	ds_read_b128 v[224:227], v161 offset:6144
	ds_read_b128 v[228:231], v161 offset:7168
	global_load_lds_dwordx4 v[232:233], off
	v_lshl_add_u64 v[232:233], s[20:21], 0, v[142:143]
	s_mov_b32 m0, s55
	s_nop 0
	global_load_lds_dwordx4 v[232:233], off
	s_waitcnt vmcnt(8)
	s_waitcnt lgkmcnt(0)
	s_barrier
	s_setprio 1
	s_waitcnt lgkmcnt(0)
	v_mfma_f32_16x16x32_bf16 v[124:127], v[148:151], v[200:203], v[124:127]
	v_mfma_f32_16x16x32_bf16 v[120:123], v[156:159], v[200:203], v[120:123]
	v_mfma_f32_16x16x32_bf16 v[108:111], v[148:151], v[208:211], v[108:111]
	v_mfma_f32_16x16x32_bf16 v[104:107], v[156:159], v[208:211], v[104:107]
	v_mfma_f32_16x16x32_bf16 v[92:95], v[148:151], v[216:219], v[92:95]
	v_mfma_f32_16x16x32_bf16 v[88:91], v[156:159], v[216:219], v[88:91]
	v_mfma_f32_16x16x32_bf16 v[76:79], v[148:151], v[224:227], v[76:79]
	v_mfma_f32_16x16x32_bf16 v[72:75], v[156:159], v[224:227], v[72:75]
	v_mfma_f32_16x16x32_bf16 v[124:127], v[152:155], v[204:207], v[124:127]
	v_mfma_f32_16x16x32_bf16 v[120:123], v[180:183], v[204:207], v[120:123]
	v_mfma_f32_16x16x32_bf16 v[108:111], v[152:155], v[212:215], v[108:111]
	v_mfma_f32_16x16x32_bf16 v[104:107], v[180:183], v[212:215], v[104:107]
	v_mfma_f32_16x16x32_bf16 v[92:95], v[152:155], v[220:223], v[92:95]
	v_mfma_f32_16x16x32_bf16 v[88:91], v[180:183], v[220:223], v[88:91]
	v_mfma_f32_16x16x32_bf16 v[76:79], v[152:155], v[228:231], v[76:79]
	v_mfma_f32_16x16x32_bf16 v[72:75], v[180:183], v[228:231], v[72:75]
	s_setprio 0
	s_setprio 1
	v_mfma_f32_16x16x32_bf16 v[116:119], v[184:187], v[200:203], v[116:119]
	v_mfma_f32_16x16x32_bf16 v[112:115], v[192:195], v[200:203], v[112:115]
	v_mfma_f32_16x16x32_bf16 v[100:103], v[184:187], v[208:211], v[100:103]
	v_mfma_f32_16x16x32_bf16 v[96:99], v[192:195], v[208:211], v[96:99]
	v_mfma_f32_16x16x32_bf16 v[84:87], v[184:187], v[216:219], v[84:87]
	v_mfma_f32_16x16x32_bf16 v[80:83], v[192:195], v[216:219], v[80:83]
	v_mfma_f32_16x16x32_bf16 v[68:71], v[184:187], v[224:227], v[68:71]
	v_mfma_f32_16x16x32_bf16 v[64:67], v[192:195], v[224:227], v[64:67]
	v_mfma_f32_16x16x32_bf16 v[116:119], v[188:191], v[204:207], v[116:119]
	v_mfma_f32_16x16x32_bf16 v[112:115], v[196:199], v[204:207], v[112:115]
	v_mfma_f32_16x16x32_bf16 v[100:103], v[188:191], v[212:215], v[100:103]
	v_mfma_f32_16x16x32_bf16 v[96:99], v[196:199], v[212:215], v[96:99]
	v_mfma_f32_16x16x32_bf16 v[84:87], v[188:191], v[220:223], v[84:87]
	v_mfma_f32_16x16x32_bf16 v[80:83], v[196:199], v[220:223], v[80:83]
	v_mfma_f32_16x16x32_bf16 v[68:71], v[188:191], v[228:231], v[68:71]
	v_mfma_f32_16x16x32_bf16 v[64:67], v[196:199], v[228:231], v[64:67]
	s_setprio 0
	s_barrier
	s_mov_b32 m0, s30
	v_lshl_add_u64 v[232:233], s[22:23], 0, v[132:133]
	s_add_u32 s20, s22, 0x80000
	ds_read_b128 v[200:203], v161 offset:16384
	ds_read_b128 v[204:207], v161 offset:17408
	ds_read_b128 v[208:211], v161 offset:18432
	ds_read_b128 v[212:215], v161 offset:19456
	ds_read_b128 v[216:219], v161 offset:20480
	ds_read_b128 v[220:223], v161 offset:21504
	ds_read_b128 v[224:227], v161 offset:22528
	ds_read_b128 v[228:231], v161 offset:23552
	global_load_lds_dwordx4 v[232:233], off
	v_lshl_add_u64 v[234:235], s[22:23], 0, v[136:137]
	s_mov_b32 m0, s31
	s_addc_u32 s21, s23, 0
	global_load_lds_dwordx4 v[234:235], off
	v_lshl_add_u64 v[236:237], s[20:21], 0, v[132:133]
	s_mov_b32 m0, s33
	v_lshl_add_u64 v[238:239], s[24:25], 0, v[134:135]
	global_load_lds_dwordx4 v[236:237], off
	v_lshl_add_u64 v[236:237], s[20:21], 0, v[136:137]
	s_mov_b32 m0, s34
	s_nop 0
	global_load_lds_dwordx4 v[236:237], off
	v_lshl_add_u64 v[236:237], s[24:25], 0, v[130:131]
	s_mov_b32 m0, s29
	s_nop 0
	global_load_lds_dwordx4 v[236:237], off
	s_mov_b32 m0, s35
	s_nop 0
	global_load_lds_dwordx4 v[238:239], off
	s_waitcnt vmcnt(8)
	s_waitcnt lgkmcnt(0)
	s_barrier
; #define PG8_STAGE(bufoff, gbase, voff) do { _Pragma("unroll") for (int _i = 0; _i < 2; ++_i) \
;         __builtin_amdgcn_global_load_lds((const unsigned*)((const char*)(gbase) + (voff)[_i]), (PG8_LAS unsigned*)(lds + (bufoff) + ldsw + _i * 8192), 16, 0, 0); } while (0)
; #define PG8_LDA(dst, b, h) do { _Pragma("unroll") for (int m = 0; m < 4; ++m) _Pragma("unroll") for (int k = 0; k < 2; ++k) dst[m][k] = *(const PG8_LAS bf16x8*)(lds + PG8_SA(b, h) + aoff + m * 2048 + k * 1024); } while (0)
; #define PG8_LDB(dst, b, h) do { _Pragma("unroll") for (int n = 0; n < 2; ++n) _Pragma("unroll") for (int k = 0; k < 2; ++k) dst[n][k] = *(const PG8_LAS bf16x8*)(lds + PG8_SB(b, h) + boff + n * 2048 + k * 1024); } while (0)
; #define PG8_MMA(ai, bj, At, Bt) do { __builtin_amdgcn_s_setprio(1); _Pragma("unroll") for (int m = 0; m < 4; ++m) _Pragma("unroll") for (int n = 0; n < 2; ++n) _Pragma("unroll") for (int k = 0; k < 2; ++k) \
;         acc[ai][bj][m][n] = __builtin_amdgcn_mfma_f32_16x16x32_bf16(Bt[n][k], At[m][k], acc[ai][bj][m][n], 0, 0, 0); __builtin_amdgcn_s_setprio(0); } while (0)
; #define PG8_WAIT_V(n) asm volatile("s_waitcnt vmcnt(" #n ")" ::: "memory")
; #define PG8_WAIT_L(n) asm volatile("s_waitcnt lgkmcnt(" #n ")" ::: "memory")
; #define PG8_BAR __builtin_amdgcn_s_barrier()
; #define PG8_SCHED __builtin_amdgcn_sched_barrier(0)
; template <class Epi, class Sched, bool ALIGN_EPI = false, bool SP2 = false>
; __device__ __forceinline__ void gemm_phase(PG8_LAS unsigned char* lds, const Gemm g, const Sched& S, const Epi& E) {
;     ...
;             PG8_WAIT_V(8); PG8_WAIT_L(0); PG8_BAR; PG8_MMA(1, 0, At, B0); PG8_MMA(1, 1, At, B1); PG8_BAR; PG8_SCHED;
;             PG8_LDB(B0, 1, 0); PG8_LDB(B1, 1, 1); PG8_SCHED; PG8_LDA(At, 1, 0); PG8_STAGE(PG8_SA(0, 1), a2 + hstepA, voffA);
;             PG8_WAIT_V(8); PG8_WAIT_L(0); PG8_BAR; PG8_MMA(0, 0, At, B0); PG8_MMA(0, 1, At, B1); PG8_BAR; PG8_SCHED;
	s_setprio 1
	s_waitcnt lgkmcnt(0)
	v_mfma_f32_16x16x32_bf16 v[60:63], v[148:151], v[200:203], v[60:63]
	v_mfma_f32_16x16x32_bf16 v[56:59], v[156:159], v[200:203], v[56:59]
	v_mfma_f32_16x16x32_bf16 v[44:47], v[148:151], v[208:211], v[44:47]
	v_mfma_f32_16x16x32_bf16 v[40:43], v[156:159], v[208:211], v[40:43]
	v_mfma_f32_16x16x32_bf16 v[28:31], v[148:151], v[216:219], v[28:31]
	v_mfma_f32_16x16x32_bf16 v[24:27], v[156:159], v[216:219], v[24:27]
	v_mfma_f32_16x16x32_bf16 v[12:15], v[148:151], v[224:227], v[12:15]
	v_mfma_f32_16x16x32_bf16 v[8:11], v[156:159], v[224:227], v[8:11]
	v_mfma_f32_16x16x32_bf16 v[60:63], v[152:155], v[204:207], v[60:63]
	v_mfma_f32_16x16x32_bf16 v[56:59], v[180:183], v[204:207], v[56:59]
	v_mfma_f32_16x16x32_bf16 v[44:47], v[152:155], v[212:215], v[44:47]
	v_mfma_f32_16x16x32_bf16 v[40:43], v[180:183], v[212:215], v[40:43]
	v_mfma_f32_16x16x32_bf16 v[28:31], v[152:155], v[220:223], v[28:31]
	v_mfma_f32_16x16x32_bf16 v[24:27], v[180:183], v[220:223], v[24:27]
	v_mfma_f32_16x16x32_bf16 v[12:15], v[152:155], v[228:231], v[12:15]
	v_mfma_f32_16x16x32_bf16 v[8:11], v[180:183], v[228:231], v[8:11]
	s_setprio 0
	s_setprio 1
	v_mfma_f32_16x16x32_bf16 v[52:55], v[184:187], v[200:203], v[52:55]
	v_mfma_f32_16x16x32_bf16 v[48:51], v[192:195], v[200:203], v[48:51]
	v_mfma_f32_16x16x32_bf16 v[36:39], v[184:187], v[208:211], v[36:39]
	v_mfma_f32_16x16x32_bf16 v[32:35], v[192:195], v[208:211], v[32:35]
	v_mfma_f32_16x16x32_bf16 v[20:23], v[184:187], v[216:219], v[20:23]
	v_mfma_f32_16x16x32_bf16 v[16:19], v[192:195], v[216:219], v[16:19]
	v_mfma_f32_16x16x32_bf16 v[4:7], v[184:187], v[224:227], v[4:7]
	v_mfma_f32_16x16x32_bf16 v[0:3], v[192:195], v[224:227], v[0:3]
	v_mfma_f32_16x16x32_bf16 v[52:55], v[188:191], v[204:207], v[52:55]
	v_mfma_f32_16x16x32_bf16 v[48:51], v[196:199], v[204:207], v[48:51]
	v_mfma_f32_16x16x32_bf16 v[36:39], v[188:191], v[212:215], v[36:39]
	v_mfma_f32_16x16x32_bf16 v[32:35], v[196:199], v[212:215], v[32:35]
	v_mfma_f32_16x16x32_bf16 v[20:23], v[188:191], v[220:223], v[20:23]
	v_mfma_f32_16x16x32_bf16 v[16:19], v[196:199], v[220:223], v[16:19]
	v_mfma_f32_16x16x32_bf16 v[4:7], v[188:191], v[228:231], v[4:7]
	v_mfma_f32_16x16x32_bf16 v[0:3], v[196:199], v[228:231], v[0:3]
	s_setprio 0
	s_barrier
	ds_read_b128 v[148:151], v171
	ds_read_b128 v[152:155], v172
	ds_read_b128 v[156:159], v173
	ds_read_b128 v[180:183], v174
	ds_read_b128 v[184:187], v175
	ds_read_b128 v[188:191], v176
	ds_read_b128 v[192:195], v177
	ds_read_b128 v[196:199], v178
	s_add_u32 s20, s24, 0x140000
	s_addc_u32 s21, s25, 0
	s_mov_b32 m0, s36
	v_lshl_add_u64 v[240:241], s[20:21], 0, v[130:131]
	ds_read_b128 v[200:203], v161 offset:32768
	ds_read_b128 v[204:207], v161 offset:33792
	ds_read_b128 v[208:211], v161 offset:34816
	ds_read_b128 v[212:215], v161 offset:35840
	ds_read_b128 v[216:219], v161 offset:36864
	ds_read_b128 v[220:223], v161 offset:37888
	ds_read_b128 v[224:227], v161 offset:38912
	ds_read_b128 v[228:231], v161 offset:39936
	global_load_lds_dwordx4 v[240:241], off
	v_lshl_add_u64 v[240:241], s[20:21], 0, v[134:135]
	s_mov_b32 m0, s37
	s_nop 0
	global_load_lds_dwordx4 v[240:241], off
	s_waitcnt vmcnt(8)
	s_waitcnt lgkmcnt(0)
	s_barrier
	s_setprio 1
	s_waitcnt lgkmcnt(0)
	v_mfma_f32_16x16x32_bf16 v[124:127], v[148:151], v[200:203], v[124:127]
	v_mfma_f32_16x16x32_bf16 v[120:123], v[156:159], v[200:203], v[120:123]
	v_mfma_f32_16x16x32_bf16 v[108:111], v[148:151], v[208:211], v[108:111]
	v_mfma_f32_16x16x32_bf16 v[104:107], v[156:159], v[208:211], v[104:107]
	v_mfma_f32_16x16x32_bf16 v[92:95], v[148:151], v[216:219], v[92:95]
	v_mfma_f32_16x16x32_bf16 v[88:91], v[156:159], v[216:219], v[88:91]
	v_mfma_f32_16x16x32_bf16 v[76:79], v[148:151], v[224:227], v[76:79]
	v_mfma_f32_16x16x32_bf16 v[72:75], v[156:159], v[224:227], v[72:75]
	v_mfma_f32_16x16x32_bf16 v[124:127], v[152:155], v[204:207], v[124:127]
	v_mfma_f32_16x16x32_bf16 v[120:123], v[180:183], v[204:207], v[120:123]
	v_mfma_f32_16x16x32_bf16 v[108:111], v[152:155], v[212:215], v[108:111]
	v_mfma_f32_16x16x32_bf16 v[104:107], v[180:183], v[212:215], v[104:107]
	v_mfma_f32_16x16x32_bf16 v[92:95], v[152:155], v[220:223], v[92:95]
	v_mfma_f32_16x16x32_bf16 v[88:91], v[180:183], v[220:223], v[88:91]
	v_mfma_f32_16x16x32_bf16 v[76:79], v[152:155], v[228:231], v[76:79]
	v_mfma_f32_16x16x32_bf16 v[72:75], v[180:183], v[228:231], v[72:75]
	s_setprio 0
	s_setprio 1
	v_mfma_f32_16x16x32_bf16 v[116:119], v[184:187], v[200:203], v[116:119]
	v_mfma_f32_16x16x32_bf16 v[112:115], v[192:195], v[200:203], v[112:115]
	v_mfma_f32_16x16x32_bf16 v[100:103], v[184:187], v[208:211], v[100:103]
	v_mfma_f32_16x16x32_bf16 v[96:99], v[192:195], v[208:211], v[96:99]
	v_mfma_f32_16x16x32_bf16 v[84:87], v[184:187], v[216:219], v[84:87]
	v_mfma_f32_16x16x32_bf16 v[80:83], v[192:195], v[216:219], v[80:83]
	v_mfma_f32_16x16x32_bf16 v[68:71], v[184:187], v[224:227], v[68:71]
	v_mfma_f32_16x16x32_bf16 v[64:67], v[192:195], v[224:227], v[64:67]
	v_mfma_f32_16x16x32_bf16 v[116:119], v[188:191], v[204:207], v[116:119]
	v_mfma_f32_16x16x32_bf16 v[112:115], v[196:199], v[204:207], v[112:115]
	v_mfma_f32_16x16x32_bf16 v[100:103], v[188:191], v[212:215], v[100:103]
	v_mfma_f32_16x16x32_bf16 v[96:99], v[196:199], v[212:215], v[96:99]
	v_mfma_f32_16x16x32_bf16 v[84:87], v[188:191], v[220:223], v[84:87]
	v_mfma_f32_16x16x32_bf16 v[80:83], v[196:199], v[220:223], v[80:83]
	v_mfma_f32_16x16x32_bf16 v[68:71], v[188:191], v[228:231], v[68:71]
	v_mfma_f32_16x16x32_bf16 v[64:67], v[196:199], v[228:231], v[64:67]
	s_setprio 0
	s_barrier
; #define PG8_STAGE(bufoff, gbase, voff) do { _Pragma("unroll") for (int _i = 0; _i < 2; ++_i) \
;         __builtin_amdgcn_global_load_lds((const unsigned*)((const char*)(gbase) + (voff)[_i]), (PG8_LAS unsigned*)(lds + (bufoff) + ldsw + _i * 8192), 16, 0, 0); } while (0)
; #define PG8_LDA(dst, b, h) do { _Pragma("unroll") for (int m = 0; m < 4; ++m) _Pragma("unroll") for (int k = 0; k < 2; ++k) dst[m][k] = *(const PG8_LAS bf16x8*)(lds + PG8_SA(b, h) + aoff + m * 2048 + k * 1024); } while (0)
; #define PG8_MMA(ai, bj, At, Bt) do { __builtin_amdgcn_s_setprio(1); _Pragma("unroll") for (int m = 0; m < 4; ++m) _Pragma("unroll") for (int n = 0; n < 2; ++n) _Pragma("unroll") for (int k = 0; k < 2; ++k) \
;         acc[ai][bj][m][n] = __builtin_amdgcn_mfma_f32_16x16x32_bf16(Bt[n][k], At[m][k], acc[ai][bj][m][n], 0, 0, 0); __builtin_amdgcn_s_setprio(0); } while (0)
; #define PG8_WAIT_V(n) asm volatile("s_waitcnt vmcnt(" #n ")" ::: "memory")
; #define PG8_WAIT_L(n) asm volatile("s_waitcnt lgkmcnt(" #n ")" ::: "memory")
; #define PG8_BAR __builtin_amdgcn_s_barrier()
; #define PG8_SCHED __builtin_amdgcn_sched_barrier(0)
; template <class Epi, class Sched, bool ALIGN_EPI = false, bool SP2 = false>
; __device__ __forceinline__ void gemm_phase(PG8_LAS unsigned char* lds, const Gemm g, const Sched& S, const Epi& E) {
;     ...
;         for (int t = 0; t < nt; t += 2) {
;     ...
;             PG8_LDA(At, 1, 1); PG8_STAGE(PG8_SB(1, 0), b3, voffB); PG8_STAGE(PG8_SB(1, 1), b3 + hstepB, voffB); PG8_STAGE(PG8_SA(1, 0), a3, voffA);
;             PG8_WAIT_V(8); PG8_WAIT_L(0); PG8_BAR; PG8_MMA(1, 0, At, B0); PG8_MMA(1, 1, At, B1); PG8_BAR; PG8_SCHED;
	s_mov_b32 m0, s38
	v_lshl_add_u64 v[232:233], v[232:233], 0, s[6:7]
	s_add_u32 s20, s22, 0x80080
	ds_read_b128 v[200:203], v161 offset:49152
	ds_read_b128 v[204:207], v161 offset:50176
	ds_read_b128 v[208:211], v161 offset:51200
	ds_read_b128 v[212:215], v161 offset:52224
	ds_read_b128 v[216:219], v161 offset:53248
	ds_read_b128 v[220:223], v161 offset:54272
	ds_read_b128 v[224:227], v161 offset:55296
	ds_read_b128 v[228:231], v161 offset:56320
	global_load_lds_dwordx4 v[232:233], off
	v_lshl_add_u64 v[232:233], v[234:235], 0, s[6:7]
	s_mov_b32 m0, s39
	s_addc_u32 s21, s23, 0
	global_load_lds_dwordx4 v[232:233], off
	v_lshl_add_u64 v[232:233], s[20:21], 0, v[132:133]
	s_mov_b32 m0, s42
	s_nop 0
	global_load_lds_dwordx4 v[232:233], off
	v_lshl_add_u64 v[232:233], s[20:21], 0, v[136:137]
	s_mov_b32 m0, s43
	s_nop 0
	global_load_lds_dwordx4 v[232:233], off
	v_lshl_add_u64 v[232:233], v[236:237], 0, s[6:7]
	s_mov_b32 m0, s40
	s_nop 0
	global_load_lds_dwordx4 v[232:233], off
	v_lshl_add_u64 v[232:233], v[238:239], 0, s[6:7]
	s_mov_b32 m0, s41
	s_nop 0
	global_load_lds_dwordx4 v[232:233], off
	s_waitcnt vmcnt(8)
	s_waitcnt lgkmcnt(0)
	s_barrier
	s_setprio 1
	s_waitcnt lgkmcnt(0)
	v_mfma_f32_16x16x32_bf16 v[60:63], v[148:151], v[200:203], v[60:63]
	v_mfma_f32_16x16x32_bf16 v[56:59], v[156:159], v[200:203], v[56:59]
	v_mfma_f32_16x16x32_bf16 v[44:47], v[148:151], v[208:211], v[44:47]
	v_mfma_f32_16x16x32_bf16 v[40:43], v[156:159], v[208:211], v[40:43]
	v_mfma_f32_16x16x32_bf16 v[28:31], v[148:151], v[216:219], v[28:31]
	v_mfma_f32_16x16x32_bf16 v[24:27], v[156:159], v[216:219], v[24:27]
	v_mfma_f32_16x16x32_bf16 v[12:15], v[148:151], v[224:227], v[12:15]
	v_mfma_f32_16x16x32_bf16 v[8:11], v[156:159], v[224:227], v[8:11]
	v_mfma_f32_16x16x32_bf16 v[60:63], v[152:155], v[204:207], v[60:63]
	v_mfma_f32_16x16x32_bf16 v[56:59], v[180:183], v[204:207], v[56:59]
	v_mfma_f32_16x16x32_bf16 v[44:47], v[152:155], v[212:215], v[44:47]
	v_mfma_f32_16x16x32_bf16 v[40:43], v[180:183], v[212:215], v[40:43]
	v_mfma_f32_16x16x32_bf16 v[28:31], v[152:155], v[220:223], v[28:31]
	v_mfma_f32_16x16x32_bf16 v[24:27], v[180:183], v[220:223], v[24:27]
	v_mfma_f32_16x16x32_bf16 v[12:15], v[152:155], v[228:231], v[12:15]
	v_mfma_f32_16x16x32_bf16 v[8:11], v[180:183], v[228:231], v[8:11]
	s_setprio 0
	s_setprio 1
	v_mfma_f32_16x16x32_bf16 v[52:55], v[184:187], v[200:203], v[52:55]
	v_mfma_f32_16x16x32_bf16 v[48:51], v[192:195], v[200:203], v[48:51]
	v_mfma_f32_16x16x32_bf16 v[36:39], v[184:187], v[208:211], v[36:39]
	v_mfma_f32_16x16x32_bf16 v[32:35], v[192:195], v[208:211], v[32:35]
	v_mfma_f32_16x16x32_bf16 v[20:23], v[184:187], v[216:219], v[20:23]
	v_mfma_f32_16x16x32_bf16 v[16:19], v[192:195], v[216:219], v[16:19]
	v_mfma_f32_16x16x32_bf16 v[4:7], v[184:187], v[224:227], v[4:7]
	v_mfma_f32_16x16x32_bf16 v[0:3], v[192:195], v[224:227], v[0:3]
	v_mfma_f32_16x16x32_bf16 v[52:55], v[188:191], v[204:207], v[52:55]
	v_mfma_f32_16x16x32_bf16 v[48:51], v[196:199], v[204:207], v[48:51]
	v_mfma_f32_16x16x32_bf16 v[36:39], v[188:191], v[212:215], v[36:39]
	v_mfma_f32_16x16x32_bf16 v[32:35], v[196:199], v[212:215], v[32:35]
	v_mfma_f32_16x16x32_bf16 v[20:23], v[188:191], v[220:223], v[20:23]
	v_mfma_f32_16x16x32_bf16 v[16:19], v[196:199], v[220:223], v[16:19]
	v_mfma_f32_16x16x32_bf16 v[4:7], v[188:191], v[228:231], v[4:7]
	v_mfma_f32_16x16x32_bf16 v[0:3], v[196:199], v[228:231], v[0:3]
	s_setprio 0
	s_barrier
	s_add_i32 s73, s73, 2
	s_add_u32 s65, s65, 0x100
	s_addc_u32 s72, s72, 0
	s_cmp_gt_u32 s73, 29
	s_mov_b64 s[20:21], s[0:1]
	s_cbranch_scc0 .LBB0_864
	s_and_b64 vcc, exec, s[8:9]
	s_cbranch_vccz .LBB0_867
	s_barrier

;     __device__ __forceinline__ bool next(int i, Unit& u) const { if (i != 0 || c >= n) return false; u.pm = pm; u.pn = c & 3; return true; }
; #define PG8_WAIT_V(n) asm volatile("s_waitcnt vmcnt(" #n ")" ::: "memory")
; template <class Epi, class Sched, bool ALIGN_EPI = false, bool SP2 = false>
; __device__ __forceinline__ void gemm_phase(PG8_LAS unsigned char* lds, const Gemm g, const Sched& S, const Epi& E) {
;     ...
;     if constexpr (SP2) {
;         PG8_STAGE(PG8_SB(0, 0), cB, voffB); PG8_STAGE(PG8_SB(0, 1), cB + hstepB, voffB); PG8_STAGE(PG8_SA(0, 0), cA, voffA); PG8_STAGE(PG8_SA(0, 1), cA + hstepA, voffA);
;         if (wr == 1) PG8_BAR;
;         PG8_WAIT_V(2); PG8_BAR;
;         PG8_STAGE(PG8_SB(1, 0), cB + kstep, voffB); PG8_STAGE(PG8_SA(1, 0), cA + kstep, voffA); PG8_STAGE(PG8_SB(1, 1), cB + hstepB + kstep, voffB);
;         PG8_WAIT_V(6); PG8_BAR;
;     } else {
;         PG8_STAGE(PG8_SB(0, 0), cB, voffB); PG8_STAGE(PG8_SA(0, 0), cA, voffA); PG8_STAGE(PG8_SB(0, 1), cB + hstepB, voffB); PG8_STAGE(PG8_SA(0, 1), cA + hstepA, voffA);
;         if (wr == 1) PG8_BAR;
;         PG8_WAIT_V(4); PG8_BAR;
;         PG8_STAGE(PG8_SB(1, 0), cB + kstep, voffB); PG8_STAGE(PG8_SA(1, 0), cA + kstep, voffA); PG8_STAGE(PG8_SB(1, 1), cB + hstepB + kstep, voffB);
;         PG8_WAIT_V(6); PG8_BAR;
;     }
;     for (;;) {
;         const bool has_next = S.next(ui + 1, nxt);
;         const char* nA = has_next ? (const char*)g.A + (size_t)nxt.pm * tstepA : cA; const char* nB = has_next ? (const char*)g.Bt + (size_t)nxt.pn * tstepB : cB;
;         for (int t = 0; t < nt; t += 2) {
;             const bool last = (t == nt - 2);
;             const char* a1 = cA + (size_t)(t + 1) * kstep;
;             const char* a2 = last ? nA : cA + (size_t)(t + 2) * kstep; const char* b2 = last ? nB : cB + (size_t)(t + 2) * kstep;
;             const char* a3 = a2 + kstep; const char* b3 = b2 + kstep;
;             if (last && has_next) S.a_ready(nxt);
;             if constexpr (SP2) {
;             PG8_LDB(B0, 0, 0); PG8_LDB(B1, 0, 1); PG8_SCHED; PG8_LDA(At, 0, 0); PG8_STAGE(PG8_SA(1, 1), a1 + hstepA, voffA);
;             PG8_WAIT_V(8); PG8_WAIT_L(0); PG8_BAR; PG8_MMA(0, 0, At, B0); PG8_MMA(0, 1, At, B1); PG8_BAR; PG8_SCHED;
;             PG8_LDA(At, 0, 1); PG8_STAGE(PG8_SB(0, 0), b2, voffB); PG8_STAGE(PG8_SB(0, 1), b2 + hstepB, voffB); PG8_STAGE(PG8_SA(0, 0), a2, voffA);
.LBB0_954:
	s_lshl_b32 s1, s1, 5
	s_and_b32 s15, s1, 0x60
	s_lshl_b32 s6, s0, 13
	s_lshl_b32 s1, s15, 7
	s_add_i32 s17, s14, 0x18000
	s_mov_b64 s[4:5], 0x80
	s_add_i32 s19, s14, 0x1a000
	v_lshl_add_u64 v[64:65], v[18:19], 0, s[4:5]
	s_mov_b32 m0, s17
	v_lshl_add_u64 v[66:67], v[20:21], 0, s[4:5]
	s_add_u32 s4, s31, 0x14000080
	s_waitcnt vmcnt(2)
	s_barrier
	global_load_lds_dwordx4 v[64:65], off
	s_mov_b32 m0, s19
	s_addc_u32 s5, s33, 0
	s_add_i32 s21, s14, 0x8000
	s_add_i32 s23, s14, 0xa000
	global_load_lds_dwordx4 v[66:67], off
	v_lshl_add_u64 v[68:69], s[4:5], 0, v[6:7]
	s_mov_b32 m0, s21
	v_lshl_add_u64 v[70:71], s[4:5], 0, v[0:1]
	s_add_u32 s4, s2, 0x80080
	global_load_lds_dwordx4 v[68:69], off
	s_mov_b32 m0, s23
	s_addc_u32 s5, s3, 0
	s_add_i32 s26, s14, 0x1c000
	global_load_lds_dwordx4 v[70:71], off
	v_lshl_add_u64 v[72:73], s[4:5], 0, v[22:23]
	s_mov_b32 m0, s26
	s_add_i32 s27, s14, 0x1e000
	global_load_lds_dwordx4 v[72:73], off
	v_lshl_add_u64 v[74:75], s[4:5], 0, v[8:9]
	s_mov_b32 m0, s27
	v_bfe_u32 v76, v24, 4, 2
	global_load_lds_dwordx4 v[74:75], off
	s_add_u32 s8, s31, 0x14000100
	v_and_b32_e32 v25, 15, v24
	v_lshlrev_b32_e32 v26, 4, v76
	v_lshlrev_b32_e32 v24, 2, v24
	s_addc_u32 s9, s33, 0
	v_lshl_or_b32 v77, s0, 6, v25
	v_lshl_or_b32 v25, v25, 6, v26
	v_and_b32_e32 v24, 32, v24
	s_add_u32 s0, s31, 0x14000180
	v_bitop3_b32 v126, v25, s1, v24 bitop3:0xde
	s_addc_u32 s1, s33, 0
	s_add_u32 s36, s31, 0x14140080
	s_addc_u32 s37, s33, 0
	s_add_i32 s34, s14, 0xc000
	s_add_i32 s30, s14, 0xe000
	s_add_u32 s10, s2, 0x80100
	s_addc_u32 s11, s3, 0
	v_bitop3_b32 v129, v25, s6, v24 bitop3:0xde
	v_or_b32_e32 v158, 0x10000, v126
	s_add_u32 s6, s31, 0x14140100
	v_or_b32_e32 v175, 0x10400, v126
	v_or_b32_e32 v177, 0x10c00, v126
	v_or_b32_e32 v179, 0x14800, v126
	s_waitcnt vmcnt(6)
	s_barrier
	v_or_b32_e32 v159, 0x14000, v126
	s_addc_u32 s7, s33, 0
	v_or_b32_e32 v176, 0x10800, v126
	ds_read_b128 v[24:27], v175
	ds_read_b128 v[28:31], v176
	ds_read_b128 v[32:35], v158
	ds_read_b128 v[36:39], v159
	v_or_b32_e32 v178, 0x14400, v126
	ds_read_b128 v[40:43], v177
	ds_read_b128 v[44:47], v178
	v_or_b32_e32 v180, 0x14c00, v126
	ds_read_b128 v[48:51], v179
	ds_read_b128 v[52:55], v180
	s_add_u32 s4, s2, 0x80180
	s_addc_u32 s5, s3, 0
	s_add_u32 s2, s31, 0x14140180
	s_addc_u32 s3, s33, 0
	v_or_b32_e32 v161, 0x18000, v126
	v_or_b32_e32 v174, 0x1c000, v126
	s_cmpk_gt_u32 s29, 0xff
	s_mov_b32 m0, s34
	v_lshl_add_u64 v[102:103], s[36:37], 0, v[6:7]
	ds_read_b128 v[56:59], v129
	ds_read_b128 v[60:63], v129 offset:1024
	ds_read_b128 v[78:81], v129 offset:2048
	ds_read_b128 v[82:85], v129 offset:3072
	ds_read_b128 v[86:89], v129 offset:4096
	ds_read_b128 v[90:93], v129 offset:5120
	ds_read_b128 v[94:97], v129 offset:6144
	ds_read_b128 v[98:101], v129 offset:7168
	global_load_lds_dwordx4 v[102:103], off
	v_lshl_add_u64 v[102:103], s[36:37], 0, v[0:1]
	s_mov_b32 m0, s30
	s_nop 0
	global_load_lds_dwordx4 v[102:103], off
	s_waitcnt vmcnt(8)
	s_waitcnt lgkmcnt(0)
	s_barrier
	s_setprio 1
	s_waitcnt lgkmcnt(0)
	v_mfma_f32_16x16x32_bf16 v[102:105], v[32:35], v[56:59], 0
	v_mfma_f32_16x16x32_bf16 v[106:109], v[28:31], v[56:59], 0
	v_mfma_f32_16x16x32_bf16 v[110:113], v[32:35], v[78:81], 0
	v_mfma_f32_16x16x32_bf16 v[114:117], v[28:31], v[78:81], 0
	v_mfma_f32_16x16x32_bf16 v[118:121], v[32:35], v[86:89], 0
	v_mfma_f32_16x16x32_bf16 v[122:125], v[28:31], v[86:89], 0
	v_mfma_f32_16x16x32_bf16 v[32:35], v[32:35], v[94:97], 0
	v_mfma_f32_16x16x32_bf16 v[28:31], v[28:31], v[94:97], 0
	v_mfma_f32_16x16x32_bf16 v[102:105], v[24:27], v[60:63], v[102:105]
	v_mfma_f32_16x16x32_bf16 v[110:113], v[24:27], v[82:85], v[110:113]
	v_mfma_f32_16x16x32_bf16 v[118:121], v[24:27], v[90:93], v[118:121]
	v_mfma_f32_16x16x32_bf16 v[24:27], v[24:27], v[98:101], v[32:35]
	v_mfma_f32_16x16x32_bf16 v[28:31], v[40:43], v[98:101], v[28:31]
	v_mfma_f32_16x16x32_bf16 v[106:109], v[40:43], v[60:63], v[106:109]
	v_mfma_f32_16x16x32_bf16 v[114:117], v[40:43], v[82:85], v[114:117]
	v_mfma_f32_16x16x32_bf16 v[122:125], v[40:43], v[90:93], v[122:125]
	s_setprio 0
	s_setprio 1
	v_mfma_f32_16x16x32_bf16 v[32:35], v[36:39], v[56:59], 0
	v_mfma_f32_16x16x32_bf16 v[40:43], v[48:51], v[56:59], 0
	v_mfma_f32_16x16x32_bf16 v[32:35], v[44:47], v[60:63], v[32:35]
	v_mfma_f32_16x16x32_bf16 v[40:43], v[52:55], v[60:63], v[40:43]
	v_mfma_f32_16x16x32_bf16 v[56:59], v[36:39], v[78:81], 0
	v_mfma_f32_16x16x32_bf16 v[60:63], v[48:51], v[78:81], 0
	v_mfma_f32_16x16x32_bf16 v[78:81], v[36:39], v[86:89], 0
	v_mfma_f32_16x16x32_bf16 v[36:39], v[36:39], v[94:97], 0
	v_mfma_f32_16x16x32_bf16 v[56:59], v[44:47], v[82:85], v[56:59]
	v_mfma_f32_16x16x32_bf16 v[78:81], v[44:47], v[90:93], v[78:81]
	v_mfma_f32_16x16x32_bf16 v[36:39], v[44:47], v[98:101], v[36:39]
	v_mfma_f32_16x16x32_bf16 v[44:47], v[48:51], v[94:97], 0
	v_mfma_f32_16x16x32_bf16 v[60:63], v[52:55], v[82:85], v[60:63]
	v_mfma_f32_16x16x32_bf16 v[82:85], v[48:51], v[86:89], 0
	v_mfma_f32_16x16x32_bf16 v[44:47], v[52:55], v[98:101], v[44:47]
	v_mfma_f32_16x16x32_bf16 v[82:85], v[52:55], v[90:93], v[82:85]
	s_setprio 0
	s_barrier
	s_mov_b64 s[36:37], 0x100
	s_mov_b32 m0, s16
	v_lshl_add_u64 v[48:49], v[18:19], 0, s[36:37]
	global_load_lds_dwordx4 v[48:49], off
	v_lshl_add_u64 v[48:49], v[20:21], 0, s[36:37]
	s_mov_b32 m0, s22
	s_nop 0
	global_load_lds_dwordx4 v[48:49], off
	v_lshl_add_u64 v[48:49], s[10:11], 0, v[22:23]
	s_mov_b32 m0, s24
	s_nop 0
	global_load_lds_dwordx4 v[48:49], off
	v_lshl_add_u64 v[48:49], s[10:11], 0, v[8:9]
	s_mov_b32 m0, s25
	s_nop 0
	global_load_lds_dwordx4 v[48:49], off
	v_lshl_add_u64 v[48:49], s[8:9], 0, v[6:7]
	s_mov_b32 m0, s14
	s_nop 0
	global_load_lds_dwordx4 v[48:49], off
	v_lshl_add_u64 v[48:49], s[8:9], 0, v[0:1]
	s_mov_b32 m0, s28
	s_nop 0
	global_load_lds_dwordx4 v[48:49], off
	s_waitcnt vmcnt(8)
	s_waitcnt lgkmcnt(0)
	s_barrier
; #define PG8_STAGE(bufoff, gbase, voff) do { _Pragma("unroll") for (int _i = 0; _i < 2; ++_i) \
;         __builtin_amdgcn_global_load_lds((const unsigned*)((const char*)(gbase) + (voff)[_i]), (PG8_LAS unsigned*)(lds + (bufoff) + ldsw + _i * 8192), 16, 0, 0); } while (0)
; #define PG8_LDA(dst, b, h) do { _Pragma("unroll") for (int m = 0; m < 4; ++m) _Pragma("unroll") for (int k = 0; k < 2; ++k) dst[m][k] = *(const PG8_LAS bf16x8*)(lds + PG8_SA(b, h) + aoff + m * 2048 + k * 1024); } while (0)
; #define PG8_LDB(dst, b, h) do { _Pragma("unroll") for (int n = 0; n < 2; ++n) _Pragma("unroll") for (int k = 0; k < 2; ++k) dst[n][k] = *(const PG8_LAS bf16x8*)(lds + PG8_SB(b, h) + boff + n * 2048 + k * 1024); } while (0)
; #define PG8_MMA(ai, bj, At, Bt) do { __builtin_amdgcn_s_setprio(1); _Pragma("unroll") for (int m = 0; m < 4; ++m) _Pragma("unroll") for (int n = 0; n < 2; ++n) _Pragma("unroll") for (int k = 0; k < 2; ++k) \
;         acc[ai][bj][m][n] = __builtin_amdgcn_mfma_f32_16x16x32_bf16(Bt[n][k], At[m][k], acc[ai][bj][m][n], 0, 0, 0); __builtin_amdgcn_s_setprio(0); } while (0)
; #define PG8_WAIT_V(n) asm volatile("s_waitcnt vmcnt(" #n ")" ::: "memory")
; template <class Epi, class Sched, bool ALIGN_EPI = false, bool SP2 = false>
; __device__ __forceinline__ void gemm_phase(PG8_LAS unsigned char* lds, const Gemm g, const Sched& S, const Epi& E) {
;     ...
;             PG8_LDB(B0, 0, 0); PG8_LDB(B1, 0, 1); PG8_SCHED; PG8_LDA(At, 0, 0); PG8_STAGE(PG8_SA(1, 1), a1 + hstepA, voffA);
;             PG8_WAIT_V(8); PG8_WAIT_L(0); PG8_BAR; PG8_MMA(0, 0, At, B0); PG8_MMA(0, 1, At, B1); PG8_BAR; PG8_SCHED;
;             PG8_LDA(At, 0, 1); PG8_STAGE(PG8_SB(0, 0), b2, voffB); PG8_STAGE(PG8_SB(0, 1), b2 + hstepB, voffB); PG8_STAGE(PG8_SA(0, 0), a2, voffA);
;             PG8_WAIT_V(8); PG8_WAIT_L(0); PG8_BAR; PG8_MMA(1, 0, At, B0); PG8_MMA(1, 1, At, B1); PG8_BAR; PG8_SCHED;
;             PG8_LDB(B0, 1, 0); PG8_LDB(B1, 1, 1); PG8_SCHED; PG8_LDA(At, 1, 0); PG8_STAGE(PG8_SA(0, 1), a2 + hstepA, voffA);
;             PG8_WAIT_V(8); PG8_WAIT_L(0); PG8_BAR; PG8_MMA(0, 0, At, B0); PG8_MMA(0, 1, At, B1); PG8_BAR; PG8_SCHED;
;             PG8_LDA(At, 1, 1); PG8_STAGE(PG8_SB(1, 0), b3, voffB); PG8_STAGE(PG8_SB(1, 1), b3 + hstepB, voffB); PG8_STAGE(PG8_SA(1, 0), a3, voffA);
;             PG8_WAIT_V(8); PG8_WAIT_L(0); PG8_BAR; PG8_MMA(1, 0, At, B0); PG8_MMA(1, 1, At, B1); PG8_BAR; PG8_SCHED;
	s_setprio 1
	s_setprio 0
	s_setprio 1
	s_setprio 0
	s_barrier
	v_or_b32_e32 v181, 0x18400, v126
	v_or_b32_e32 v183, 0x18c00, v126
	v_or_b32_e32 v185, 0x1c800, v126
	v_or_b32_e32 v182, 0x18800, v126
	ds_read_b128 v[48:51], v181
	ds_read_b128 v[52:55], v182
	ds_read_b128 v[86:89], v161
	ds_read_b128 v[90:93], v174
	v_or_b32_e32 v184, 0x1c400, v126
	ds_read_b128 v[94:97], v183
	ds_read_b128 v[98:101], v184
	v_or_b32_e32 v186, 0x1cc00, v126
	ds_read_b128 v[130:133], v185
	ds_read_b128 v[134:137], v186
	s_mov_b32 m0, s18
	v_lshl_add_u64 v[126:127], s[6:7], 0, v[6:7]
	ds_read_b128 v[138:141], v129 offset:32768
	ds_read_b128 v[142:145], v129 offset:33792
	ds_read_b128 v[146:149], v129 offset:34816
	ds_read_b128 v[150:153], v129 offset:35840
	ds_read_b128 v[154:157], v129 offset:36864
	ds_read_b128 v[162:165], v129 offset:37888
	ds_read_b128 v[166:169], v129 offset:38912
	ds_read_b128 v[170:173], v129 offset:39936
	global_load_lds_dwordx4 v[126:127], off
	v_lshl_add_u64 v[126:127], s[6:7], 0, v[0:1]
	s_mov_b32 m0, s20
	s_nop 0
	global_load_lds_dwordx4 v[126:127], off
	s_waitcnt vmcnt(8)
	s_waitcnt lgkmcnt(0)
	s_barrier
	s_setprio 1
	s_waitcnt lgkmcnt(0)
	v_mfma_f32_16x16x32_bf16 v[24:27], v[86:89], v[166:169], v[24:27]
	v_mfma_f32_16x16x32_bf16 v[28:31], v[52:55], v[166:169], v[28:31]
	v_mfma_f32_16x16x32_bf16 v[102:105], v[86:89], v[138:141], v[102:105]
	v_mfma_f32_16x16x32_bf16 v[106:109], v[52:55], v[138:141], v[106:109]
	v_mfma_f32_16x16x32_bf16 v[110:113], v[86:89], v[146:149], v[110:113]
	v_mfma_f32_16x16x32_bf16 v[114:117], v[52:55], v[146:149], v[114:117]
	v_mfma_f32_16x16x32_bf16 v[118:121], v[86:89], v[154:157], v[118:121]
	v_mfma_f32_16x16x32_bf16 v[122:125], v[52:55], v[154:157], v[122:125]
	v_mfma_f32_16x16x32_bf16 v[24:27], v[48:51], v[170:173], v[24:27]
	v_mfma_f32_16x16x32_bf16 v[28:31], v[94:97], v[170:173], v[28:31]
	v_mfma_f32_16x16x32_bf16 v[102:105], v[48:51], v[142:145], v[102:105]
	v_mfma_f32_16x16x32_bf16 v[106:109], v[94:97], v[142:145], v[106:109]
	v_mfma_f32_16x16x32_bf16 v[110:113], v[48:51], v[150:153], v[110:113]
	v_mfma_f32_16x16x32_bf16 v[114:117], v[94:97], v[150:153], v[114:117]
	v_mfma_f32_16x16x32_bf16 v[118:121], v[48:51], v[162:165], v[118:121]
	v_mfma_f32_16x16x32_bf16 v[122:125], v[94:97], v[162:165], v[122:125]
	s_setprio 0
	s_setprio 1
	v_mfma_f32_16x16x32_bf16 v[32:35], v[90:93], v[138:141], v[32:35]
	v_mfma_f32_16x16x32_bf16 v[40:43], v[130:133], v[138:141], v[40:43]
	v_mfma_f32_16x16x32_bf16 v[48:51], v[90:93], v[146:149], v[56:59]
	v_mfma_f32_16x16x32_bf16 v[52:55], v[130:133], v[146:149], v[60:63]
	v_mfma_f32_16x16x32_bf16 v[56:59], v[90:93], v[154:157], v[78:81]
	v_mfma_f32_16x16x32_bf16 v[60:63], v[130:133], v[154:157], v[82:85]
	v_mfma_f32_16x16x32_bf16 v[36:39], v[90:93], v[166:169], v[36:39]
	v_mfma_f32_16x16x32_bf16 v[44:47], v[130:133], v[166:169], v[44:47]
	v_mfma_f32_16x16x32_bf16 v[32:35], v[98:101], v[142:145], v[32:35]
	v_mfma_f32_16x16x32_bf16 v[40:43], v[134:137], v[142:145], v[40:43]
	v_mfma_f32_16x16x32_bf16 v[48:51], v[98:101], v[150:153], v[48:51]
	v_mfma_f32_16x16x32_bf16 v[52:55], v[134:137], v[150:153], v[52:55]
	v_mfma_f32_16x16x32_bf16 v[56:59], v[98:101], v[162:165], v[56:59]
	v_mfma_f32_16x16x32_bf16 v[60:63], v[134:137], v[162:165], v[60:63]
	v_mfma_f32_16x16x32_bf16 v[36:39], v[98:101], v[170:173], v[36:39]
	v_mfma_f32_16x16x32_bf16 v[44:47], v[134:137], v[170:173], v[44:47]
	s_setprio 0
	s_barrier
	s_mov_b64 s[6:7], 0x180
	s_mov_b32 m0, s17
	v_lshl_add_u64 v[78:79], v[18:19], 0, s[6:7]
	global_load_lds_dwordx4 v[78:79], off
	v_lshl_add_u64 v[78:79], v[20:21], 0, s[6:7]
	s_mov_b32 m0, s19
	v_lshl_add_u64 v[22:23], s[4:5], 0, v[22:23]
	global_load_lds_dwordx4 v[78:79], off
	s_mov_b32 m0, s26
	v_lshl_add_u64 v[8:9], s[4:5], 0, v[8:9]
	global_load_lds_dwordx4 v[22:23], off
	s_mov_b32 m0, s27
	s_nop 0
	global_load_lds_dwordx4 v[8:9], off
	v_lshl_add_u64 v[8:9], s[0:1], 0, v[6:7]
	s_mov_b32 m0, s21
	s_nop 0
	global_load_lds_dwordx4 v[8:9], off
	v_lshl_add_u64 v[8:9], s[0:1], 0, v[0:1]
	s_mov_b32 m0, s23
	s_nop 0
	global_load_lds_dwordx4 v[8:9], off
	s_waitcnt vmcnt(8)
	s_waitcnt lgkmcnt(0)
	s_barrier
	s_setprio 1
	s_setprio 0
	s_setprio 1
	s_setprio 0
	s_barrier
	ds_read_b128 v[78:81], v175
	ds_read_b128 v[82:85], v176
	ds_read_b128 v[86:89], v158
	ds_read_b128 v[90:93], v159
	ds_read_b128 v[94:97], v177
	ds_read_b128 v[98:101], v178
	ds_read_b128 v[130:133], v179
	ds_read_b128 v[134:137], v180
	s_mov_b32 m0, s34
	v_lshl_add_u64 v[6:7], s[2:3], 0, v[6:7]
	ds_read_b128 v[138:141], v129
	ds_read_b128 v[142:145], v129 offset:1024
	ds_read_b128 v[146:149], v129 offset:2048
	ds_read_b128 v[150:153], v129 offset:3072
	ds_read_b128 v[154:157], v129 offset:4096
	ds_read_b128 v[162:165], v129 offset:5120
	ds_read_b128 v[166:169], v129 offset:6144
	ds_read_b128 v[170:173], v129 offset:7168
	global_load_lds_dwordx4 v[6:7], off
	v_lshl_add_u64 v[0:1], s[2:3], 0, v[0:1]
	s_mov_b32 m0, s30
	s_nop 0
	global_load_lds_dwordx4 v[0:1], off
	s_waitcnt vmcnt(8)
	s_waitcnt lgkmcnt(0)
	s_barrier
; #define PG8_STAGE(bufoff, gbase, voff) do { _Pragma("unroll") for (int _i = 0; _i < 2; ++_i) \
;         __builtin_amdgcn_global_load_lds((const unsigned*)((const char*)(gbase) + (voff)[_i]), (PG8_LAS unsigned*)(lds + (bufoff) + ldsw + _i * 8192), 16, 0, 0); } while (0)
; #define PG8_LDA(dst, b, h) do { _Pragma("unroll") for (int m = 0; m < 4; ++m) _Pragma("unroll") for (int k = 0; k < 2; ++k) dst[m][k] = *(const PG8_LAS bf16x8*)(lds + PG8_SA(b, h) + aoff + m * 2048 + k * 1024); } while (0)
; #define PG8_LDB(dst, b, h) do { _Pragma("unroll") for (int n = 0; n < 2; ++n) _Pragma("unroll") for (int k = 0; k < 2; ++k) dst[n][k] = *(const PG8_LAS bf16x8*)(lds + PG8_SB(b, h) + boff + n * 2048 + k * 1024); } while (0)
; #define PG8_MMA(ai, bj, At, Bt) do { __builtin_amdgcn_s_setprio(1); _Pragma("unroll") for (int m = 0; m < 4; ++m) _Pragma("unroll") for (int n = 0; n < 2; ++n) _Pragma("unroll") for (int k = 0; k < 2; ++k) \
;         acc[ai][bj][m][n] = __builtin_amdgcn_mfma_f32_16x16x32_bf16(Bt[n][k], At[m][k], acc[ai][bj][m][n], 0, 0, 0); __builtin_amdgcn_s_setprio(0); } while (0)
; #define PG8_WAIT_V(n) asm volatile("s_waitcnt vmcnt(" #n ")" ::: "memory")
; template <class Epi, class Sched, bool ALIGN_EPI = false, bool SP2 = false>
; __device__ __forceinline__ void gemm_phase(PG8_LAS unsigned char* lds, const Gemm g, const Sched& S, const Epi& E) {
;     ...
;             PG8_LDB(B0, 0, 0); PG8_LDB(B1, 0, 1); PG8_SCHED; PG8_LDA(At, 0, 0); PG8_STAGE(PG8_SA(1, 1), a1 + hstepA, voffA);
;             PG8_WAIT_V(8); PG8_WAIT_L(0); PG8_BAR; PG8_MMA(0, 0, At, B0); PG8_MMA(0, 1, At, B1); PG8_BAR; PG8_SCHED;
;             PG8_LDA(At, 0, 1); PG8_STAGE(PG8_SB(0, 0), b2, voffB); PG8_STAGE(PG8_SB(0, 1), b2 + hstepB, voffB); PG8_STAGE(PG8_SA(0, 0), a2, voffA);
;             PG8_WAIT_V(8); PG8_WAIT_L(0); PG8_BAR; PG8_MMA(1, 0, At, B0); PG8_MMA(1, 1, At, B1); PG8_BAR; PG8_SCHED;
;             PG8_LDB(B0, 1, 0); PG8_LDB(B1, 1, 1); PG8_SCHED; PG8_LDA(At, 1, 0); PG8_STAGE(PG8_SA(0, 1), a2 + hstepA, voffA);
;             PG8_WAIT_V(8); PG8_WAIT_L(0); PG8_BAR; PG8_MMA(0, 0, At, B0); PG8_MMA(0, 1, At, B1); PG8_BAR; PG8_SCHED;
;             PG8_LDA(At, 1, 1); PG8_STAGE(PG8_SB(1, 0), b3, voffB); PG8_STAGE(PG8_SB(1, 1), b3 + hstepB, voffB); PG8_STAGE(PG8_SA(1, 0), a3, voffA);
;             PG8_WAIT_V(8); PG8_WAIT_L(0); PG8_BAR; PG8_MMA(1, 0, At, B0); PG8_MMA(1, 1, At, B1); PG8_BAR; PG8_SCHED;
	s_setprio 1
	s_waitcnt lgkmcnt(0)
	v_mfma_f32_16x16x32_bf16 v[6:9], v[86:89], v[138:141], v[102:105]
	v_mfma_f32_16x16x32_bf16 v[102:105], v[82:85], v[138:141], v[106:109]
	v_mfma_f32_16x16x32_bf16 v[106:109], v[86:89], v[146:149], v[110:113]
	v_mfma_f32_16x16x32_bf16 v[110:113], v[82:85], v[146:149], v[114:117]
	v_mfma_f32_16x16x32_bf16 v[114:117], v[86:89], v[154:157], v[118:121]
	v_mfma_f32_16x16x32_bf16 v[22:25], v[86:89], v[166:169], v[24:27]
	v_mfma_f32_16x16x32_bf16 v[6:9], v[78:81], v[142:145], v[6:9]
	v_mfma_f32_16x16x32_bf16 v[106:109], v[78:81], v[150:153], v[106:109]
	v_mfma_f32_16x16x32_bf16 v[114:117], v[78:81], v[162:165], v[114:117]
	v_mfma_f32_16x16x32_bf16 v[118:121], v[82:85], v[154:157], v[122:125]
	v_mfma_f32_16x16x32_bf16 v[78:81], v[78:81], v[170:173], v[22:25]
	v_mfma_f32_16x16x32_bf16 v[22:25], v[82:85], v[166:169], v[28:31]
	v_mfma_f32_16x16x32_bf16 v[102:105], v[94:97], v[142:145], v[102:105]
	v_mfma_f32_16x16x32_bf16 v[110:113], v[94:97], v[150:153], v[110:113]
	v_mfma_f32_16x16x32_bf16 v[118:121], v[94:97], v[162:165], v[118:121]
	v_mfma_f32_16x16x32_bf16 v[82:85], v[94:97], v[170:173], v[22:25]
	s_setprio 0
	s_setprio 1
	v_mfma_f32_16x16x32_bf16 v[22:25], v[90:93], v[138:141], v[32:35]
	v_mfma_f32_16x16x32_bf16 v[32:35], v[98:101], v[142:145], v[22:25]
	v_mfma_f32_16x16x32_bf16 v[22:25], v[130:133], v[138:141], v[40:43]
	v_mfma_f32_16x16x32_bf16 v[40:43], v[134:137], v[142:145], v[22:25]
	v_mfma_f32_16x16x32_bf16 v[22:25], v[90:93], v[146:149], v[48:51]
	v_mfma_f32_16x16x32_bf16 v[48:51], v[98:101], v[150:153], v[22:25]
	v_mfma_f32_16x16x32_bf16 v[22:25], v[130:133], v[146:149], v[52:55]
	v_mfma_f32_16x16x32_bf16 v[86:89], v[134:137], v[150:153], v[22:25]
	v_mfma_f32_16x16x32_bf16 v[22:25], v[90:93], v[154:157], v[56:59]
	v_mfma_f32_16x16x32_bf16 v[94:97], v[98:101], v[162:165], v[22:25]
	v_mfma_f32_16x16x32_bf16 v[22:25], v[130:133], v[154:157], v[60:63]
	v_mfma_f32_16x16x32_bf16 v[122:125], v[134:137], v[162:165], v[22:25]
	v_mfma_f32_16x16x32_bf16 v[22:25], v[90:93], v[166:169], v[36:39]
	v_mfma_f32_16x16x32_bf16 v[90:93], v[98:101], v[170:173], v[22:25]
	v_mfma_f32_16x16x32_bf16 v[22:25], v[130:133], v[166:169], v[44:47]
	v_mfma_f32_16x16x32_bf16 v[98:101], v[134:137], v[170:173], v[22:25]
	s_setprio 0
	s_barrier
	s_mov_b32 m0, s16
	s_nop 0
	global_load_lds_dwordx4 v[18:19], off
	s_mov_b32 m0, s22
	s_nop 0
	global_load_lds_dwordx4 v[20:21], off
	s_mov_b32 m0, s24
	s_nop 0
	global_load_lds_dwordx4 v[16:17], off
	s_mov_b32 m0, s25
	s_nop 0
	global_load_lds_dwordx4 v[10:11], off
	s_mov_b32 m0, s14
	s_nop 0
	global_load_lds_dwordx4 v[12:13], off
	s_mov_b32 m0, s28
	s_nop 0
	global_load_lds_dwordx4 v[14:15], off
	s_waitcnt vmcnt(8)
	s_waitcnt lgkmcnt(0)
	s_barrier
	s_setprio 1
	s_setprio 0
	s_setprio 1
	s_setprio 0
	s_barrier
	ds_read_b128 v[36:39], v181
	ds_read_b128 v[44:47], v182
	ds_read_b128 v[52:55], v161
	ds_read_b128 v[130:133], v174
	ds_read_b128 v[56:59], v183
	ds_read_b128 v[134:137], v184
	ds_read_b128 v[138:141], v185
	ds_read_b128 v[142:145], v186
	s_mov_b32 m0, s18
	ds_read_b128 v[60:63], v129 offset:32768
	ds_read_b128 v[146:149], v129 offset:33792
	ds_read_b128 v[150:153], v129 offset:34816
	ds_read_b128 v[154:157], v129 offset:35840
	ds_read_b128 v[162:165], v129 offset:36864
	ds_read_b128 v[166:169], v129 offset:37888
	ds_read_b128 v[170:173], v129 offset:38912
	ds_read_b128 v[174:177], v129 offset:39936
	global_load_lds_dwordx4 v[2:3], off
	s_mov_b32 m0, s20
	s_nop 0
	global_load_lds_dwordx4 v[4:5], off
	s_waitcnt vmcnt(8)
	s_waitcnt lgkmcnt(0)
	s_barrier
	s_setprio 1
	s_waitcnt lgkmcnt(0)
	v_mfma_f32_16x16x32_bf16 v[0:3], v[52:55], v[60:63], v[6:9]
	v_mfma_f32_16x16x32_bf16 v[20:23], v[36:39], v[146:149], v[0:3]
	v_mfma_f32_16x16x32_bf16 v[0:3], v[44:47], v[60:63], v[102:105]
	v_mfma_f32_16x16x32_bf16 v[28:31], v[56:59], v[146:149], v[0:3]
	v_mfma_f32_16x16x32_bf16 v[0:3], v[52:55], v[150:153], v[106:109]
	v_mfma_f32_16x16x32_bf16 v[12:15], v[36:39], v[154:157], v[0:3]
	v_mfma_f32_16x16x32_bf16 v[0:3], v[44:47], v[150:153], v[110:113]
	v_mfma_f32_16x16x32_bf16 v[24:27], v[56:59], v[154:157], v[0:3]
	v_mfma_f32_16x16x32_bf16 v[0:3], v[52:55], v[162:165], v[114:117]
	v_mfma_f32_16x16x32_bf16 v[4:7], v[36:39], v[166:169], v[0:3]
	v_mfma_f32_16x16x32_bf16 v[0:3], v[44:47], v[162:165], v[118:121]
	v_mfma_f32_16x16x32_bf16 v[16:19], v[56:59], v[166:169], v[0:3]
	v_mfma_f32_16x16x32_bf16 v[0:3], v[52:55], v[170:173], v[78:81]
	v_mfma_f32_16x16x32_bf16 v[8:11], v[44:47], v[170:173], v[82:85]
	v_mfma_f32_16x16x32_bf16 v[0:3], v[36:39], v[174:177], v[0:3]
	v_mfma_f32_16x16x32_bf16 v[8:11], v[56:59], v[174:177], v[8:11]
	s_setprio 0
	s_setprio 1
	v_mfma_f32_16x16x32_bf16 v[32:35], v[130:133], v[60:63], v[32:35]
	v_mfma_f32_16x16x32_bf16 v[52:55], v[134:137], v[146:149], v[32:35]
	v_mfma_f32_16x16x32_bf16 v[32:35], v[138:141], v[60:63], v[40:43]
	v_mfma_f32_16x16x32_bf16 v[60:63], v[142:145], v[146:149], v[32:35]
	v_mfma_f32_16x16x32_bf16 v[32:35], v[130:133], v[150:153], v[48:51]
	v_mfma_f32_16x16x32_bf16 v[44:47], v[134:137], v[154:157], v[32:35]
	v_mfma_f32_16x16x32_bf16 v[32:35], v[138:141], v[150:153], v[86:89]
	v_mfma_f32_16x16x32_bf16 v[56:59], v[142:145], v[154:157], v[32:35]
	v_mfma_f32_16x16x32_bf16 v[32:35], v[130:133], v[162:165], v[94:97]
	v_mfma_f32_16x16x32_bf16 v[36:39], v[134:137], v[166:169], v[32:35]
	v_mfma_f32_16x16x32_bf16 v[32:35], v[138:141], v[162:165], v[122:125]
	v_mfma_f32_16x16x32_bf16 v[48:51], v[142:145], v[166:169], v[32:35]
	v_mfma_f32_16x16x32_bf16 v[32:35], v[130:133], v[170:173], v[90:93]
	v_mfma_f32_16x16x32_bf16 v[40:43], v[138:141], v[170:173], v[98:101]
	v_mfma_f32_16x16x32_bf16 v[32:35], v[134:137], v[174:177], v[32:35]
	v_mfma_f32_16x16x32_bf16 v[40:43], v[142:145], v[174:177], v[40:43]
	s_setprio 0
	s_barrier
	s_mov_b32 m0, s17
	s_nop 0
	global_load_lds_dwordx4 v[64:65], off
	s_mov_b32 m0, s19
	s_nop 0
	global_load_lds_dwordx4 v[66:67], off
	s_mov_b32 m0, s26
	s_nop 0
	global_load_lds_dwordx4 v[72:73], off
	s_mov_b32 m0, s27
	s_nop 0
	global_load_lds_dwordx4 v[74:75], off
	s_mov_b32 m0, s21
	s_nop 0
	global_load_lds_dwordx4 v[68:69], off
	s_mov_b32 m0, s23
	s_nop 0
	global_load_lds_dwordx4 v[70:71], off
	s_waitcnt vmcnt(8)
	s_waitcnt lgkmcnt(0)
	s_barrier
	s_setprio 1
	s_setprio 0
	s_setprio 1
	s_setprio 0
	s_barrier
	s_cbranch_scc1 .LBB0_956
	s_barrier

; #define PG8_STAGE(bufoff, gbase, voff) do { _Pragma("unroll") for (int _i = 0; _i < 2; ++_i) \
;         __builtin_amdgcn_global_load_lds((const unsigned*)((const char*)(gbase) + (voff)[_i]), (PG8_LAS unsigned*)(lds + (bufoff) + ldsw + _i * 8192), 16, 0, 0); } while (0)
; #define PG8_LDA(dst, b, h) do { _Pragma("unroll") for (int m = 0; m < 4; ++m) _Pragma("unroll") for (int k = 0; k < 2; ++k) dst[m][k] = *(const PG8_LAS bf16x8*)(lds + PG8_SA(b, h) + aoff + m * 2048 + k * 1024); } while (0)
; #define PG8_LDB(dst, b, h) do { _Pragma("unroll") for (int n = 0; n < 2; ++n) _Pragma("unroll") for (int k = 0; k < 2; ++k) dst[n][k] = *(const PG8_LAS bf16x8*)(lds + PG8_SB(b, h) + boff + n * 2048 + k * 1024); } while (0)
; #define PG8_MMA(ai, bj, At, Bt) do { __builtin_amdgcn_s_setprio(1); _Pragma("unroll") for (int m = 0; m < 4; ++m) _Pragma("unroll") for (int n = 0; n < 2; ++n) _Pragma("unroll") for (int k = 0; k < 2; ++k) \
;         acc[ai][bj][m][n] = __builtin_amdgcn_mfma_f32_16x16x32_bf16(Bt[n][k], At[m][k], acc[ai][bj][m][n], 0, 0, 0); __builtin_amdgcn_s_setprio(0); } while (0)
; #define PG8_WAIT_V(n) asm volatile("s_waitcnt vmcnt(" #n ")" ::: "memory")
; #define PG8_WAIT_L(n) asm volatile("s_waitcnt lgkmcnt(" #n ")" ::: "memory")
; #define PG8_BAR __builtin_amdgcn_s_barrier()
; #define PG8_SCHED __builtin_amdgcn_sched_barrier(0)
; template <class Epi, class Sched, bool ALIGN_EPI = false, bool SP2 = false>
; __device__ __forceinline__ void gemm_phase(PG8_LAS unsigned char* lds, const Gemm g, const Sched& S, const Epi& E) {
;     ...
;             const bool last = (t == nt - 2);
;             const char* a1 = cA + (size_t)(t + 1) * kstep;
;             const char* a2 = last ? nA : cA + (size_t)(t + 2) * kstep; const char* b2 = last ? nB : cB + (size_t)(t + 2) * kstep;
;             const char* a3 = a2 + kstep; const char* b3 = b2 + kstep;
;             if (last && has_next) S.a_ready(nxt);
;             if constexpr (SP2) {
;             PG8_LDB(B0, 0, 0); PG8_LDB(B1, 0, 1); PG8_SCHED; PG8_LDA(At, 0, 0); PG8_STAGE(PG8_SA(1, 1), a1 + hstepA, voffA);
;             PG8_WAIT_V(8); PG8_WAIT_L(0); PG8_BAR; PG8_MMA(0, 0, At, B0); PG8_MMA(0, 1, At, B1); PG8_BAR; PG8_SCHED;
;             PG8_LDA(At, 0, 1); PG8_STAGE(PG8_SB(0, 0), b2, voffB); PG8_STAGE(PG8_SB(0, 1), b2 + hstepB, voffB); PG8_STAGE(PG8_SA(0, 0), a2, voffA);
.LBB0_1105:
	v_or_b32_e32 v162, 0x10000, v169
	v_add_u32_e32 v166, 0x10400, v169
	ds_read_b128 v[162:165], v162
	ds_read_b128 v[172:175], v166
	v_add_u32_e32 v166, 0x10800, v169
	v_add_u32_e32 v167, 0x10c00, v169
	ds_read_b128 v[194:197], v166
	ds_read_b128 v[198:201], v167
	v_or_b32_e32 v166, 0x14000, v169
	v_add_u32_e32 v167, 0x14400, v169
	ds_read_b128 v[202:205], v166
	ds_read_b128 v[206:209], v167
	v_add_u32_e32 v166, 0x14800, v169
	v_add_u32_e32 v167, 0x14c00, v169
	ds_read_b128 v[210:213], v166
	ds_read_b128 v[214:217], v167
	s_add_u32 s18, s96, 0xfffc0080
	s_addc_u32 s19, s97, -1
	s_cmp_eq_u32 s42, 12
	s_cselect_b32 s21, s1, s19
	s_cselect_b32 s20, s5, s18
	s_cselect_b32 s19, s11, s27
	s_cselect_b32 s18, s17, s25
	s_mov_b32 m0, s72
	v_lshl_add_u64 v[166:167], s[96:97], 0, v[158:159]
	ds_read_b128 v[218:221], v168
	ds_read_b128 v[222:225], v168 offset:1024
	ds_read_b128 v[226:229], v168 offset:2048
	ds_read_b128 v[230:233], v168 offset:3072
	ds_read_b128 v[234:237], v168 offset:4096
	ds_read_b128 v[238:241], v168 offset:5120
	ds_read_b128 v[242:245], v168 offset:6144
	ds_read_b128 v[246:249], v168 offset:7168
	global_load_lds_dwordx4 v[166:167], off
	v_lshl_add_u64 v[166:167], s[96:97], 0, v[160:161]
	s_mov_b32 m0, s73
	s_nop 0
	global_load_lds_dwordx4 v[166:167], off
	s_waitcnt vmcnt(8)
	s_waitcnt lgkmcnt(0)
	s_barrier
	s_setprio 1
	s_waitcnt lgkmcnt(0)
	v_mfma_f32_16x16x32_bf16 v[124:127], v[162:165], v[218:221], v[124:127]
	v_mfma_f32_16x16x32_bf16 v[120:123], v[194:197], v[218:221], v[120:123]
	v_mfma_f32_16x16x32_bf16 v[108:111], v[162:165], v[226:229], v[108:111]
	v_mfma_f32_16x16x32_bf16 v[104:107], v[194:197], v[226:229], v[104:107]
	v_mfma_f32_16x16x32_bf16 v[92:95], v[162:165], v[234:237], v[92:95]
	v_mfma_f32_16x16x32_bf16 v[88:91], v[194:197], v[234:237], v[88:91]
	v_mfma_f32_16x16x32_bf16 v[76:79], v[162:165], v[242:245], v[76:79]
	v_mfma_f32_16x16x32_bf16 v[72:75], v[194:197], v[242:245], v[72:75]
	v_mfma_f32_16x16x32_bf16 v[124:127], v[172:175], v[222:225], v[124:127]
	v_mfma_f32_16x16x32_bf16 v[120:123], v[198:201], v[222:225], v[120:123]
	v_mfma_f32_16x16x32_bf16 v[108:111], v[172:175], v[230:233], v[108:111]
	v_mfma_f32_16x16x32_bf16 v[104:107], v[198:201], v[230:233], v[104:107]
	v_mfma_f32_16x16x32_bf16 v[92:95], v[172:175], v[238:241], v[92:95]
	v_mfma_f32_16x16x32_bf16 v[88:91], v[198:201], v[238:241], v[88:91]
	v_mfma_f32_16x16x32_bf16 v[76:79], v[172:175], v[246:249], v[76:79]
	v_mfma_f32_16x16x32_bf16 v[72:75], v[198:201], v[246:249], v[72:75]
	s_setprio 0
	s_setprio 1
	v_mfma_f32_16x16x32_bf16 v[116:119], v[202:205], v[218:221], v[116:119]
	v_mfma_f32_16x16x32_bf16 v[112:115], v[210:213], v[218:221], v[112:115]
	v_mfma_f32_16x16x32_bf16 v[100:103], v[202:205], v[226:229], v[100:103]
	v_mfma_f32_16x16x32_bf16 v[96:99], v[210:213], v[226:229], v[96:99]
	v_mfma_f32_16x16x32_bf16 v[84:87], v[202:205], v[234:237], v[84:87]
	v_mfma_f32_16x16x32_bf16 v[80:83], v[210:213], v[234:237], v[80:83]
	v_mfma_f32_16x16x32_bf16 v[68:71], v[202:205], v[242:245], v[68:71]
	v_mfma_f32_16x16x32_bf16 v[64:67], v[210:213], v[242:245], v[64:67]
	v_mfma_f32_16x16x32_bf16 v[116:119], v[206:209], v[222:225], v[116:119]
	v_mfma_f32_16x16x32_bf16 v[112:115], v[214:217], v[222:225], v[112:115]
	v_mfma_f32_16x16x32_bf16 v[100:103], v[206:209], v[230:233], v[100:103]
	v_mfma_f32_16x16x32_bf16 v[96:99], v[214:217], v[230:233], v[96:99]
	v_mfma_f32_16x16x32_bf16 v[84:87], v[206:209], v[238:241], v[84:87]
	v_mfma_f32_16x16x32_bf16 v[80:83], v[214:217], v[238:241], v[80:83]
	v_mfma_f32_16x16x32_bf16 v[68:71], v[206:209], v[246:249], v[68:71]
	v_mfma_f32_16x16x32_bf16 v[64:67], v[214:217], v[246:249], v[64:67]
	s_setprio 0
	s_barrier
	s_mov_b32 m0, s37
	v_lshl_add_u64 v[166:167], s[18:19], 0, v[152:153]
	s_add_u32 s56, s18, 0x40000
	ds_read_b128 v[218:221], v168 offset:16384
	ds_read_b128 v[222:225], v168 offset:17408
	ds_read_b128 v[226:229], v168 offset:18432
	ds_read_b128 v[230:233], v168 offset:19456
	ds_read_b128 v[234:237], v168 offset:20480
	ds_read_b128 v[238:241], v168 offset:21504
	ds_read_b128 v[242:245], v168 offset:22528
	ds_read_b128 v[246:249], v168 offset:23552
	global_load_lds_dwordx4 v[166:167], off
	v_lshl_add_u64 v[176:177], s[18:19], 0, v[156:157]
	s_mov_b32 m0, s38
	s_addc_u32 s57, s19, 0
	global_load_lds_dwordx4 v[176:177], off
	v_lshl_add_u64 v[250:251], s[56:57], 0, v[152:153]
	s_mov_b32 m0, s39
	v_lshl_add_u64 v[178:179], s[20:21], 0, v[154:155]
	global_load_lds_dwordx4 v[250:251], off
	v_lshl_add_u64 v[250:251], s[56:57], 0, v[156:157]
	s_mov_b32 m0, s40
	s_nop 0
	global_load_lds_dwordx4 v[250:251], off
	v_lshl_add_u64 v[250:251], s[20:21], 0, v[150:151]
	s_mov_b32 m0, s36
	s_nop 0
	global_load_lds_dwordx4 v[250:251], off
	s_mov_b32 m0, s41
	s_nop 0
	global_load_lds_dwordx4 v[178:179], off
	s_waitcnt vmcnt(8)
	s_waitcnt lgkmcnt(0)
	s_barrier
; #define PG8_STAGE(bufoff, gbase, voff) do { _Pragma("unroll") for (int _i = 0; _i < 2; ++_i) \
;         __builtin_amdgcn_global_load_lds((const unsigned*)((const char*)(gbase) + (voff)[_i]), (PG8_LAS unsigned*)(lds + (bufoff) + ldsw + _i * 8192), 16, 0, 0); } while (0)
; #define PG8_LDA(dst, b, h) do { _Pragma("unroll") for (int m = 0; m < 4; ++m) _Pragma("unroll") for (int k = 0; k < 2; ++k) dst[m][k] = *(const PG8_LAS bf16x8*)(lds + PG8_SA(b, h) + aoff + m * 2048 + k * 1024); } while (0)
; #define PG8_LDB(dst, b, h) do { _Pragma("unroll") for (int n = 0; n < 2; ++n) _Pragma("unroll") for (int k = 0; k < 2; ++k) dst[n][k] = *(const PG8_LAS bf16x8*)(lds + PG8_SB(b, h) + boff + n * 2048 + k * 1024); } while (0)
; #define PG8_MMA(ai, bj, At, Bt) do { __builtin_amdgcn_s_setprio(1); _Pragma("unroll") for (int m = 0; m < 4; ++m) _Pragma("unroll") for (int n = 0; n < 2; ++n) _Pragma("unroll") for (int k = 0; k < 2; ++k) \
;         acc[ai][bj][m][n] = __builtin_amdgcn_mfma_f32_16x16x32_bf16(Bt[n][k], At[m][k], acc[ai][bj][m][n], 0, 0, 0); __builtin_amdgcn_s_setprio(0); } while (0)
; #define PG8_WAIT_V(n) asm volatile("s_waitcnt vmcnt(" #n ")" ::: "memory")
; #define PG8_WAIT_L(n) asm volatile("s_waitcnt lgkmcnt(" #n ")" ::: "memory")
; #define PG8_BAR __builtin_amdgcn_s_barrier()
; #define PG8_SCHED __builtin_amdgcn_sched_barrier(0)
; template <class Epi, class Sched, bool ALIGN_EPI = false, bool SP2 = false>
; __device__ __forceinline__ void gemm_phase(PG8_LAS unsigned char* lds, const Gemm g, const Sched& S, const Epi& E) {
;     ...
;             PG8_WAIT_V(8); PG8_WAIT_L(0); PG8_BAR; PG8_MMA(1, 0, At, B0); PG8_MMA(1, 1, At, B1); PG8_BAR; PG8_SCHED;
;             PG8_LDB(B0, 1, 0); PG8_LDB(B1, 1, 1); PG8_SCHED; PG8_LDA(At, 1, 0); PG8_STAGE(PG8_SA(0, 1), a2 + hstepA, voffA);
;             PG8_WAIT_V(8); PG8_WAIT_L(0); PG8_BAR; PG8_MMA(0, 0, At, B0); PG8_MMA(0, 1, At, B1); PG8_BAR; PG8_SCHED;
	s_setprio 1
	s_waitcnt lgkmcnt(0)
	v_mfma_f32_16x16x32_bf16 v[60:63], v[162:165], v[218:221], v[60:63]
	v_mfma_f32_16x16x32_bf16 v[56:59], v[194:197], v[218:221], v[56:59]
	v_mfma_f32_16x16x32_bf16 v[44:47], v[162:165], v[226:229], v[44:47]
	v_mfma_f32_16x16x32_bf16 v[40:43], v[194:197], v[226:229], v[40:43]
	v_mfma_f32_16x16x32_bf16 v[28:31], v[162:165], v[234:237], v[28:31]
	v_mfma_f32_16x16x32_bf16 v[24:27], v[194:197], v[234:237], v[24:27]
	v_mfma_f32_16x16x32_bf16 v[12:15], v[162:165], v[242:245], v[12:15]
	v_mfma_f32_16x16x32_bf16 v[8:11], v[194:197], v[242:245], v[8:11]
	v_mfma_f32_16x16x32_bf16 v[60:63], v[172:175], v[222:225], v[60:63]
	v_mfma_f32_16x16x32_bf16 v[56:59], v[198:201], v[222:225], v[56:59]
	v_mfma_f32_16x16x32_bf16 v[44:47], v[172:175], v[230:233], v[44:47]
	v_mfma_f32_16x16x32_bf16 v[40:43], v[198:201], v[230:233], v[40:43]
	v_mfma_f32_16x16x32_bf16 v[28:31], v[172:175], v[238:241], v[28:31]
	v_mfma_f32_16x16x32_bf16 v[24:27], v[198:201], v[238:241], v[24:27]
	v_mfma_f32_16x16x32_bf16 v[12:15], v[172:175], v[246:249], v[12:15]
	v_mfma_f32_16x16x32_bf16 v[8:11], v[198:201], v[246:249], v[8:11]
	s_setprio 0
	s_setprio 1
	v_mfma_f32_16x16x32_bf16 v[52:55], v[202:205], v[218:221], v[52:55]
	v_mfma_f32_16x16x32_bf16 v[48:51], v[210:213], v[218:221], v[48:51]
	v_mfma_f32_16x16x32_bf16 v[36:39], v[202:205], v[226:229], v[36:39]
	v_mfma_f32_16x16x32_bf16 v[32:35], v[210:213], v[226:229], v[32:35]
	v_mfma_f32_16x16x32_bf16 v[20:23], v[202:205], v[234:237], v[20:23]
	v_mfma_f32_16x16x32_bf16 v[16:19], v[210:213], v[234:237], v[16:19]
	v_mfma_f32_16x16x32_bf16 v[4:7], v[202:205], v[242:245], v[4:7]
	v_mfma_f32_16x16x32_bf16 v[0:3], v[210:213], v[242:245], v[0:3]
	v_mfma_f32_16x16x32_bf16 v[52:55], v[206:209], v[222:225], v[52:55]
	v_mfma_f32_16x16x32_bf16 v[48:51], v[214:217], v[222:225], v[48:51]
	v_mfma_f32_16x16x32_bf16 v[36:39], v[206:209], v[230:233], v[36:39]
	v_mfma_f32_16x16x32_bf16 v[32:35], v[214:217], v[230:233], v[32:35]
	v_mfma_f32_16x16x32_bf16 v[20:23], v[206:209], v[238:241], v[20:23]
	v_mfma_f32_16x16x32_bf16 v[16:19], v[214:217], v[238:241], v[16:19]
	v_mfma_f32_16x16x32_bf16 v[4:7], v[206:209], v[246:249], v[4:7]
	v_mfma_f32_16x16x32_bf16 v[0:3], v[214:217], v[246:249], v[0:3]
	s_setprio 0
	s_barrier
	v_or_b32_e32 v162, 0x18000, v169
	v_add_u32_e32 v171, 0x18400, v169
	ds_read_b128 v[162:165], v162
	ds_read_b128 v[172:175], v171
	v_add_u32_e32 v171, 0x18800, v169
	v_add_u32_e32 v188, 0x18c00, v169
	ds_read_b128 v[194:197], v171
	ds_read_b128 v[198:201], v188
	v_or_b32_e32 v171, 0x1c000, v169
	v_add_u32_e32 v188, 0x1c400, v169
	ds_read_b128 v[202:205], v171
	ds_read_b128 v[206:209], v188
	v_add_u32_e32 v171, 0x1c800, v169
	v_add_u32_e32 v188, 0x1cc00, v169
	ds_read_b128 v[210:213], v171
	ds_read_b128 v[214:217], v188
	s_add_u32 s20, s20, 0x40000
	s_addc_u32 s21, s21, 0
	s_mov_b32 m0, s44
	v_lshl_add_u64 v[188:189], s[20:21], 0, v[150:151]
	ds_read_b128 v[218:221], v168 offset:32768
	ds_read_b128 v[222:225], v168 offset:33792
	ds_read_b128 v[226:229], v168 offset:34816
	ds_read_b128 v[230:233], v168 offset:35840
	ds_read_b128 v[234:237], v168 offset:36864
	ds_read_b128 v[238:241], v168 offset:37888
	ds_read_b128 v[242:245], v168 offset:38912
	ds_read_b128 v[246:249], v168 offset:39936
	global_load_lds_dwordx4 v[188:189], off
	v_lshl_add_u64 v[188:189], s[20:21], 0, v[154:155]
	s_mov_b32 m0, s45
	s_nop 0
	global_load_lds_dwordx4 v[188:189], off
	s_waitcnt vmcnt(8)
	s_waitcnt lgkmcnt(0)
	s_barrier
	s_setprio 1
	s_waitcnt lgkmcnt(0)
	v_mfma_f32_16x16x32_bf16 v[124:127], v[162:165], v[218:221], v[124:127]
	v_mfma_f32_16x16x32_bf16 v[120:123], v[194:197], v[218:221], v[120:123]
	v_mfma_f32_16x16x32_bf16 v[108:111], v[162:165], v[226:229], v[108:111]
	v_mfma_f32_16x16x32_bf16 v[104:107], v[194:197], v[226:229], v[104:107]
	v_mfma_f32_16x16x32_bf16 v[92:95], v[162:165], v[234:237], v[92:95]
	v_mfma_f32_16x16x32_bf16 v[88:91], v[194:197], v[234:237], v[88:91]
	v_mfma_f32_16x16x32_bf16 v[76:79], v[162:165], v[242:245], v[76:79]
	v_mfma_f32_16x16x32_bf16 v[72:75], v[194:197], v[242:245], v[72:75]
	v_mfma_f32_16x16x32_bf16 v[124:127], v[172:175], v[222:225], v[124:127]
	v_mfma_f32_16x16x32_bf16 v[120:123], v[198:201], v[222:225], v[120:123]
	v_mfma_f32_16x16x32_bf16 v[108:111], v[172:175], v[230:233], v[108:111]
	v_mfma_f32_16x16x32_bf16 v[104:107], v[198:201], v[230:233], v[104:107]
	v_mfma_f32_16x16x32_bf16 v[92:95], v[172:175], v[238:241], v[92:95]
	v_mfma_f32_16x16x32_bf16 v[88:91], v[198:201], v[238:241], v[88:91]
	v_mfma_f32_16x16x32_bf16 v[76:79], v[172:175], v[246:249], v[76:79]
	v_mfma_f32_16x16x32_bf16 v[72:75], v[198:201], v[246:249], v[72:75]
	s_setprio 0
	s_setprio 1
	v_mfma_f32_16x16x32_bf16 v[116:119], v[202:205], v[218:221], v[116:119]
	v_mfma_f32_16x16x32_bf16 v[112:115], v[210:213], v[218:221], v[112:115]
	v_mfma_f32_16x16x32_bf16 v[100:103], v[202:205], v[226:229], v[100:103]
	v_mfma_f32_16x16x32_bf16 v[96:99], v[210:213], v[226:229], v[96:99]
	v_mfma_f32_16x16x32_bf16 v[84:87], v[202:205], v[234:237], v[84:87]
	v_mfma_f32_16x16x32_bf16 v[80:83], v[210:213], v[234:237], v[80:83]
	v_mfma_f32_16x16x32_bf16 v[68:71], v[202:205], v[242:245], v[68:71]
	v_mfma_f32_16x16x32_bf16 v[64:67], v[210:213], v[242:245], v[64:67]
	v_mfma_f32_16x16x32_bf16 v[116:119], v[206:209], v[222:225], v[116:119]
	v_mfma_f32_16x16x32_bf16 v[112:115], v[214:217], v[222:225], v[112:115]
	v_mfma_f32_16x16x32_bf16 v[100:103], v[206:209], v[230:233], v[100:103]
	v_mfma_f32_16x16x32_bf16 v[96:99], v[214:217], v[230:233], v[96:99]
	v_mfma_f32_16x16x32_bf16 v[84:87], v[206:209], v[238:241], v[84:87]
	v_mfma_f32_16x16x32_bf16 v[80:83], v[214:217], v[238:241], v[80:83]
	v_mfma_f32_16x16x32_bf16 v[68:71], v[206:209], v[246:249], v[68:71]
	v_mfma_f32_16x16x32_bf16 v[64:67], v[214:217], v[246:249], v[64:67]
	s_setprio 0
	s_barrier
; #define PG8_STAGE(bufoff, gbase, voff) do { _Pragma("unroll") for (int _i = 0; _i < 2; ++_i) \
;         __builtin_amdgcn_global_load_lds((const unsigned*)((const char*)(gbase) + (voff)[_i]), (PG8_LAS unsigned*)(lds + (bufoff) + ldsw + _i * 8192), 16, 0, 0); } while (0)
; #define PG8_LDA(dst, b, h) do { _Pragma("unroll") for (int m = 0; m < 4; ++m) _Pragma("unroll") for (int k = 0; k < 2; ++k) dst[m][k] = *(const PG8_LAS bf16x8*)(lds + PG8_SA(b, h) + aoff + m * 2048 + k * 1024); } while (0)
; #define PG8_MMA(ai, bj, At, Bt) do { __builtin_amdgcn_s_setprio(1); _Pragma("unroll") for (int m = 0; m < 4; ++m) _Pragma("unroll") for (int n = 0; n < 2; ++n) _Pragma("unroll") for (int k = 0; k < 2; ++k) \
;         acc[ai][bj][m][n] = __builtin_amdgcn_mfma_f32_16x16x32_bf16(Bt[n][k], At[m][k], acc[ai][bj][m][n], 0, 0, 0); __builtin_amdgcn_s_setprio(0); } while (0)
; #define PG8_WAIT_V(n) asm volatile("s_waitcnt vmcnt(" #n ")" ::: "memory")
; #define PG8_WAIT_L(n) asm volatile("s_waitcnt lgkmcnt(" #n ")" ::: "memory")
; #define PG8_BAR __builtin_amdgcn_s_barrier()
; #define PG8_SCHED __builtin_amdgcn_sched_barrier(0)
; template <class Epi, class Sched, bool ALIGN_EPI = false, bool SP2 = false>
; __device__ __forceinline__ void gemm_phase(PG8_LAS unsigned char* lds, const Gemm g, const Sched& S, const Epi& E) {
;     ...
;         for (int t = 0; t < nt; t += 2) {
;     ...
;             PG8_LDA(At, 1, 1); PG8_STAGE(PG8_SB(1, 0), b3, voffB); PG8_STAGE(PG8_SB(1, 1), b3 + hstepB, voffB); PG8_STAGE(PG8_SA(1, 0), a3, voffA);
;             PG8_WAIT_V(8); PG8_WAIT_L(0); PG8_BAR; PG8_MMA(1, 0, At, B0); PG8_MMA(1, 1, At, B1); PG8_BAR; PG8_SCHED;
	s_mov_b32 m0, s46
	v_lshl_add_u64 v[166:167], v[166:167], 0, s[54:55]
	s_add_u32 s18, s18, 0x40080
	ds_read_b128 v[218:221], v168 offset:49152
	ds_read_b128 v[222:225], v168 offset:50176
	ds_read_b128 v[226:229], v168 offset:51200
	ds_read_b128 v[230:233], v168 offset:52224
	ds_read_b128 v[234:237], v168 offset:53248
	ds_read_b128 v[238:241], v168 offset:54272
	ds_read_b128 v[242:245], v168 offset:55296
	ds_read_b128 v[246:249], v168 offset:56320
	global_load_lds_dwordx4 v[166:167], off
	v_lshl_add_u64 v[166:167], v[176:177], 0, s[54:55]
	s_mov_b32 m0, s47
	s_addc_u32 s19, s19, 0
	global_load_lds_dwordx4 v[166:167], off
	v_lshl_add_u64 v[166:167], s[18:19], 0, v[152:153]
	s_mov_b32 m0, s62
	s_nop 0
	global_load_lds_dwordx4 v[166:167], off
	v_lshl_add_u64 v[166:167], s[18:19], 0, v[156:157]
	s_mov_b32 m0, s63
	s_nop 0
	global_load_lds_dwordx4 v[166:167], off
	v_lshl_add_u64 v[166:167], v[250:251], 0, s[54:55]
	s_mov_b32 m0, s58
	s_nop 0
	global_load_lds_dwordx4 v[166:167], off
	v_lshl_add_u64 v[166:167], v[178:179], 0, s[54:55]
	s_mov_b32 m0, s59
	s_nop 0
	global_load_lds_dwordx4 v[166:167], off
	s_waitcnt vmcnt(8)
	s_waitcnt lgkmcnt(0)
	s_barrier
	s_setprio 1
	s_waitcnt lgkmcnt(0)
	v_mfma_f32_16x16x32_bf16 v[60:63], v[162:165], v[218:221], v[60:63]
	v_mfma_f32_16x16x32_bf16 v[56:59], v[194:197], v[218:221], v[56:59]
	v_mfma_f32_16x16x32_bf16 v[44:47], v[162:165], v[226:229], v[44:47]
	v_mfma_f32_16x16x32_bf16 v[40:43], v[194:197], v[226:229], v[40:43]
	v_mfma_f32_16x16x32_bf16 v[28:31], v[162:165], v[234:237], v[28:31]
	v_mfma_f32_16x16x32_bf16 v[24:27], v[194:197], v[234:237], v[24:27]
	v_mfma_f32_16x16x32_bf16 v[12:15], v[162:165], v[242:245], v[12:15]
	v_mfma_f32_16x16x32_bf16 v[8:11], v[194:197], v[242:245], v[8:11]
	v_mfma_f32_16x16x32_bf16 v[60:63], v[172:175], v[222:225], v[60:63]
	v_mfma_f32_16x16x32_bf16 v[56:59], v[198:201], v[222:225], v[56:59]
	v_mfma_f32_16x16x32_bf16 v[44:47], v[172:175], v[230:233], v[44:47]
	v_mfma_f32_16x16x32_bf16 v[40:43], v[198:201], v[230:233], v[40:43]
	v_mfma_f32_16x16x32_bf16 v[28:31], v[172:175], v[238:241], v[28:31]
	v_mfma_f32_16x16x32_bf16 v[24:27], v[198:201], v[238:241], v[24:27]
	v_mfma_f32_16x16x32_bf16 v[12:15], v[172:175], v[246:249], v[12:15]
	v_mfma_f32_16x16x32_bf16 v[8:11], v[198:201], v[246:249], v[8:11]
	s_setprio 0
	s_setprio 1
	v_mfma_f32_16x16x32_bf16 v[52:55], v[202:205], v[218:221], v[52:55]
	v_mfma_f32_16x16x32_bf16 v[48:51], v[210:213], v[218:221], v[48:51]
	v_mfma_f32_16x16x32_bf16 v[36:39], v[202:205], v[226:229], v[36:39]
	v_mfma_f32_16x16x32_bf16 v[32:35], v[210:213], v[226:229], v[32:35]
	v_mfma_f32_16x16x32_bf16 v[20:23], v[202:205], v[234:237], v[20:23]
	v_mfma_f32_16x16x32_bf16 v[16:19], v[210:213], v[234:237], v[16:19]
	v_mfma_f32_16x16x32_bf16 v[4:7], v[202:205], v[242:245], v[4:7]
	v_mfma_f32_16x16x32_bf16 v[0:3], v[210:213], v[242:245], v[0:3]
	v_mfma_f32_16x16x32_bf16 v[52:55], v[206:209], v[222:225], v[52:55]
	v_mfma_f32_16x16x32_bf16 v[48:51], v[214:217], v[222:225], v[48:51]
	v_mfma_f32_16x16x32_bf16 v[36:39], v[206:209], v[230:233], v[36:39]
	v_mfma_f32_16x16x32_bf16 v[32:35], v[214:217], v[230:233], v[32:35]
	v_mfma_f32_16x16x32_bf16 v[20:23], v[206:209], v[238:241], v[20:23]
	v_mfma_f32_16x16x32_bf16 v[16:19], v[214:217], v[238:241], v[16:19]
	v_mfma_f32_16x16x32_bf16 v[4:7], v[206:209], v[246:249], v[4:7]
	v_mfma_f32_16x16x32_bf16 v[0:3], v[214:217], v[246:249], v[0:3]
	s_setprio 0
	s_barrier
	s_add_i32 s42, s42, 2
	s_add_u32 s96, s96, 0x100
	s_addc_u32 s97, s97, 0
	s_add_u32 s25, s25, 0x100
	s_addc_u32 s27, s27, 0
	s_cmp_gt_u32 s42, 13
	s_cbranch_scc0 .LBB0_1105
	s_and_b64 vcc, exec, s[8:9]
	s_cbranch_vccz .LBB0_1108
	s_barrier

; #define PG8_STAGE(bufoff, gbase, voff) do { _Pragma("unroll") for (int _i = 0; _i < 2; ++_i) \
;         __builtin_amdgcn_global_load_lds((const unsigned*)((const char*)(gbase) + (voff)[_i]), (PG8_LAS unsigned*)(lds + (bufoff) + ldsw + _i * 8192), 16, 0, 0); } while (0)
; #define PG8_LDA(dst, b, h) do { _Pragma("unroll") for (int m = 0; m < 4; ++m) _Pragma("unroll") for (int k = 0; k < 2; ++k) dst[m][k] = *(const PG8_LAS bf16x8*)(lds + PG8_SA(b, h) + aoff + m * 2048 + k * 1024); } while (0)
; #define PG8_LDB(dst, b, h) do { _Pragma("unroll") for (int n = 0; n < 2; ++n) _Pragma("unroll") for (int k = 0; k < 2; ++k) dst[n][k] = *(const PG8_LAS bf16x8*)(lds + PG8_SB(b, h) + boff + n * 2048 + k * 1024); } while (0)
; #define PG8_MMA(ai, bj, At, Bt) do { __builtin_amdgcn_s_setprio(1); _Pragma("unroll") for (int m = 0; m < 4; ++m) _Pragma("unroll") for (int n = 0; n < 2; ++n) _Pragma("unroll") for (int k = 0; k < 2; ++k) \
;         acc[ai][bj][m][n] = __builtin_amdgcn_mfma_f32_16x16x32_bf16(Bt[n][k], At[m][k], acc[ai][bj][m][n], 0, 0, 0); __builtin_amdgcn_s_setprio(0); } while (0)
; #define PG8_WAIT_V(n) asm volatile("s_waitcnt vmcnt(" #n ")" ::: "memory")
; #define PG8_WAIT_L(n) asm volatile("s_waitcnt lgkmcnt(" #n ")" ::: "memory")
; #define PG8_BAR __builtin_amdgcn_s_barrier()
; #define PG8_SCHED __builtin_amdgcn_sched_barrier(0)
; template <class Epi, class Sched, bool ALIGN_EPI = false, bool SP2 = false>
; __device__ __forceinline__ void gemm_phase(PG8_LAS unsigned char* lds, const Gemm g, const Sched& S, const Epi& E) {
;     ...
;             const bool last = (t == nt - 2);
;             const char* a1 = cA + (size_t)(t + 1) * kstep;
;             const char* a2 = last ? nA : cA + (size_t)(t + 2) * kstep; const char* b2 = last ? nB : cB + (size_t)(t + 2) * kstep;
;             const char* a3 = a2 + kstep; const char* b3 = b2 + kstep;
;             if (last && has_next) S.a_ready(nxt);
;             if constexpr (SP2) {
;             PG8_LDB(B0, 0, 0); PG8_LDB(B1, 0, 1); PG8_SCHED; PG8_LDA(At, 0, 0); PG8_STAGE(PG8_SA(1, 1), a1 + hstepA, voffA);
;             PG8_WAIT_V(8); PG8_WAIT_L(0); PG8_BAR; PG8_MMA(0, 0, At, B0); PG8_MMA(0, 1, At, B1); PG8_BAR; PG8_SCHED;
;             PG8_LDA(At, 0, 1); PG8_STAGE(PG8_SB(0, 0), b2, voffB); PG8_STAGE(PG8_SB(0, 1), b2 + hstepB, voffB); PG8_STAGE(PG8_SA(0, 0), a2, voffA);
.LBB0_1350:
	v_or_b32_e32 v162, 0x10000, v169
	v_add_u32_e32 v166, 0x10400, v169
	ds_read_b128 v[162:165], v162
	ds_read_b128 v[172:175], v166
	v_add_u32_e32 v166, 0x10800, v169
	v_add_u32_e32 v167, 0x10c00, v169
	ds_read_b128 v[194:197], v166
	ds_read_b128 v[198:201], v167
	v_or_b32_e32 v166, 0x14000, v169
	v_add_u32_e32 v167, 0x14400, v169
	ds_read_b128 v[202:205], v166
	ds_read_b128 v[206:209], v167
	v_add_u32_e32 v166, 0x14800, v169
	v_add_u32_e32 v167, 0x14c00, v169
	ds_read_b128 v[210:213], v166
	ds_read_b128 v[214:217], v167
	s_add_u32 s0, s4, 0x100
	s_addc_u32 s1, s5, 0
	s_cmp_eq_u32 s74, 2
	s_cselect_b32 s21, s11, s1
	s_cselect_b32 s20, s10, s0
	s_cselect_b32 s19, s17, s43
	s_cselect_b32 s18, s16, s42
	v_lshl_add_u64 v[166:167], s[4:5], 0, v[158:159]
	s_add_i32 m0, s36, 0xc000
	ds_read_b128 v[218:221], v168
	ds_read_b128 v[222:225], v168 offset:1024
	ds_read_b128 v[226:229], v168 offset:2048
	ds_read_b128 v[230:233], v168 offset:3072
	ds_read_b128 v[234:237], v168 offset:4096
	ds_read_b128 v[238:241], v168 offset:5120
	ds_read_b128 v[242:245], v168 offset:6144
	ds_read_b128 v[246:249], v168 offset:7168
	global_load_lds_dwordx4 v[166:167], off
	v_lshl_add_u64 v[166:167], s[4:5], 0, v[160:161]
	s_add_i32 m0, s36, 0xe000
	s_nop 0
	global_load_lds_dwordx4 v[166:167], off
	s_waitcnt vmcnt(8)
	s_waitcnt lgkmcnt(0)
	s_barrier
	s_setprio 1
	s_waitcnt lgkmcnt(0)
	v_mfma_f32_16x16x32_bf16 v[124:127], v[162:165], v[218:221], v[124:127]
	v_mfma_f32_16x16x32_bf16 v[120:123], v[194:197], v[218:221], v[120:123]
	v_mfma_f32_16x16x32_bf16 v[108:111], v[162:165], v[226:229], v[108:111]
	v_mfma_f32_16x16x32_bf16 v[104:107], v[194:197], v[226:229], v[104:107]
	v_mfma_f32_16x16x32_bf16 v[92:95], v[162:165], v[234:237], v[92:95]
	v_mfma_f32_16x16x32_bf16 v[88:91], v[194:197], v[234:237], v[88:91]
	v_mfma_f32_16x16x32_bf16 v[76:79], v[162:165], v[242:245], v[76:79]
	v_mfma_f32_16x16x32_bf16 v[72:75], v[194:197], v[242:245], v[72:75]
	v_mfma_f32_16x16x32_bf16 v[124:127], v[172:175], v[222:225], v[124:127]
	v_mfma_f32_16x16x32_bf16 v[120:123], v[198:201], v[222:225], v[120:123]
	v_mfma_f32_16x16x32_bf16 v[108:111], v[172:175], v[230:233], v[108:111]
	v_mfma_f32_16x16x32_bf16 v[104:107], v[198:201], v[230:233], v[104:107]
	v_mfma_f32_16x16x32_bf16 v[92:95], v[172:175], v[238:241], v[92:95]
	v_mfma_f32_16x16x32_bf16 v[88:91], v[198:201], v[238:241], v[88:91]
	v_mfma_f32_16x16x32_bf16 v[76:79], v[172:175], v[246:249], v[76:79]
	v_mfma_f32_16x16x32_bf16 v[72:75], v[198:201], v[246:249], v[72:75]
	s_setprio 0
	s_setprio 1
	v_mfma_f32_16x16x32_bf16 v[116:119], v[202:205], v[218:221], v[116:119]
	v_mfma_f32_16x16x32_bf16 v[112:115], v[210:213], v[218:221], v[112:115]
	v_mfma_f32_16x16x32_bf16 v[100:103], v[202:205], v[226:229], v[100:103]
	v_mfma_f32_16x16x32_bf16 v[96:99], v[210:213], v[226:229], v[96:99]
	v_mfma_f32_16x16x32_bf16 v[84:87], v[202:205], v[234:237], v[84:87]
	v_mfma_f32_16x16x32_bf16 v[80:83], v[210:213], v[234:237], v[80:83]
	v_mfma_f32_16x16x32_bf16 v[68:71], v[202:205], v[242:245], v[68:71]
	v_mfma_f32_16x16x32_bf16 v[64:67], v[210:213], v[242:245], v[64:67]
	v_mfma_f32_16x16x32_bf16 v[116:119], v[206:209], v[222:225], v[116:119]
	v_mfma_f32_16x16x32_bf16 v[112:115], v[214:217], v[222:225], v[112:115]
	v_mfma_f32_16x16x32_bf16 v[100:103], v[206:209], v[230:233], v[100:103]
	v_mfma_f32_16x16x32_bf16 v[96:99], v[214:217], v[230:233], v[96:99]
	v_mfma_f32_16x16x32_bf16 v[84:87], v[206:209], v[238:241], v[84:87]
	v_mfma_f32_16x16x32_bf16 v[80:83], v[214:217], v[238:241], v[80:83]
	v_mfma_f32_16x16x32_bf16 v[68:71], v[206:209], v[246:249], v[68:71]
	v_mfma_f32_16x16x32_bf16 v[64:67], v[214:217], v[246:249], v[64:67]
	s_setprio 0
	s_barrier
	s_mov_b32 m0, s37
	v_lshl_add_u64 v[166:167], s[18:19], 0, v[152:153]
	s_add_u32 s4, s18, 0x18000
	ds_read_b128 v[218:221], v168 offset:16384
	ds_read_b128 v[222:225], v168 offset:17408
	ds_read_b128 v[226:229], v168 offset:18432
	ds_read_b128 v[230:233], v168 offset:19456
	ds_read_b128 v[234:237], v168 offset:20480
	ds_read_b128 v[238:241], v168 offset:21504
	ds_read_b128 v[242:245], v168 offset:22528
	ds_read_b128 v[246:249], v168 offset:23552
	global_load_lds_dwordx4 v[166:167], off
	v_lshl_add_u64 v[176:177], s[18:19], 0, v[156:157]
	s_mov_b32 m0, s38
	s_addc_u32 s5, s19, 0
	global_load_lds_dwordx4 v[176:177], off
	v_lshl_add_u64 v[178:179], s[4:5], 0, v[152:153]
	s_mov_b32 m0, s39
	v_lshl_add_u64 v[188:189], s[20:21], 0, v[154:155]
	global_load_lds_dwordx4 v[178:179], off
	v_lshl_add_u64 v[178:179], s[4:5], 0, v[156:157]
	s_mov_b32 m0, s40
	s_nop 0
	global_load_lds_dwordx4 v[178:179], off
	v_lshl_add_u64 v[178:179], s[20:21], 0, v[150:151]
	s_mov_b32 m0, s36
	s_nop 0
	global_load_lds_dwordx4 v[178:179], off
	s_mov_b32 m0, s41
	s_nop 0
	global_load_lds_dwordx4 v[188:189], off
	s_waitcnt vmcnt(8)
	s_waitcnt lgkmcnt(0)
	s_barrier
; #define PG8_STAGE(bufoff, gbase, voff) do { _Pragma("unroll") for (int _i = 0; _i < 2; ++_i) \
;         __builtin_amdgcn_global_load_lds((const unsigned*)((const char*)(gbase) + (voff)[_i]), (PG8_LAS unsigned*)(lds + (bufoff) + ldsw + _i * 8192), 16, 0, 0); } while (0)
; #define PG8_LDA(dst, b, h) do { _Pragma("unroll") for (int m = 0; m < 4; ++m) _Pragma("unroll") for (int k = 0; k < 2; ++k) dst[m][k] = *(const PG8_LAS bf16x8*)(lds + PG8_SA(b, h) + aoff + m * 2048 + k * 1024); } while (0)
; #define PG8_LDB(dst, b, h) do { _Pragma("unroll") for (int n = 0; n < 2; ++n) _Pragma("unroll") for (int k = 0; k < 2; ++k) dst[n][k] = *(const PG8_LAS bf16x8*)(lds + PG8_SB(b, h) + boff + n * 2048 + k * 1024); } while (0)
; #define PG8_MMA(ai, bj, At, Bt) do { __builtin_amdgcn_s_setprio(1); _Pragma("unroll") for (int m = 0; m < 4; ++m) _Pragma("unroll") for (int n = 0; n < 2; ++n) _Pragma("unroll") for (int k = 0; k < 2; ++k) \
;         acc[ai][bj][m][n] = __builtin_amdgcn_mfma_f32_16x16x32_bf16(Bt[n][k], At[m][k], acc[ai][bj][m][n], 0, 0, 0); __builtin_amdgcn_s_setprio(0); } while (0)
; #define PG8_WAIT_V(n) asm volatile("s_waitcnt vmcnt(" #n ")" ::: "memory")
; #define PG8_WAIT_L(n) asm volatile("s_waitcnt lgkmcnt(" #n ")" ::: "memory")
; #define PG8_BAR __builtin_amdgcn_s_barrier()
; #define PG8_SCHED __builtin_amdgcn_sched_barrier(0)
; template <class Epi, class Sched, bool ALIGN_EPI = false, bool SP2 = false>
; __device__ __forceinline__ void gemm_phase(PG8_LAS unsigned char* lds, const Gemm g, const Sched& S, const Epi& E) {
;     ...
;             PG8_WAIT_V(8); PG8_WAIT_L(0); PG8_BAR; PG8_MMA(1, 0, At, B0); PG8_MMA(1, 1, At, B1); PG8_BAR; PG8_SCHED;
;             PG8_LDB(B0, 1, 0); PG8_LDB(B1, 1, 1); PG8_SCHED; PG8_LDA(At, 1, 0); PG8_STAGE(PG8_SA(0, 1), a2 + hstepA, voffA);
;             PG8_WAIT_V(8); PG8_WAIT_L(0); PG8_BAR; PG8_MMA(0, 0, At, B0); PG8_MMA(0, 1, At, B1); PG8_BAR; PG8_SCHED;
	s_setprio 1
	s_waitcnt lgkmcnt(0)
	v_mfma_f32_16x16x32_bf16 v[60:63], v[162:165], v[218:221], v[60:63]
	v_mfma_f32_16x16x32_bf16 v[56:59], v[194:197], v[218:221], v[56:59]
	v_mfma_f32_16x16x32_bf16 v[44:47], v[162:165], v[226:229], v[44:47]
	v_mfma_f32_16x16x32_bf16 v[40:43], v[194:197], v[226:229], v[40:43]
	v_mfma_f32_16x16x32_bf16 v[28:31], v[162:165], v[234:237], v[28:31]
	v_mfma_f32_16x16x32_bf16 v[24:27], v[194:197], v[234:237], v[24:27]
	v_mfma_f32_16x16x32_bf16 v[12:15], v[162:165], v[242:245], v[12:15]
	v_mfma_f32_16x16x32_bf16 v[8:11], v[194:197], v[242:245], v[8:11]
	v_mfma_f32_16x16x32_bf16 v[60:63], v[172:175], v[222:225], v[60:63]
	v_mfma_f32_16x16x32_bf16 v[56:59], v[198:201], v[222:225], v[56:59]
	v_mfma_f32_16x16x32_bf16 v[44:47], v[172:175], v[230:233], v[44:47]
	v_mfma_f32_16x16x32_bf16 v[40:43], v[198:201], v[230:233], v[40:43]
	v_mfma_f32_16x16x32_bf16 v[28:31], v[172:175], v[238:241], v[28:31]
	v_mfma_f32_16x16x32_bf16 v[24:27], v[198:201], v[238:241], v[24:27]
	v_mfma_f32_16x16x32_bf16 v[12:15], v[172:175], v[246:249], v[12:15]
	v_mfma_f32_16x16x32_bf16 v[8:11], v[198:201], v[246:249], v[8:11]
	s_setprio 0
	s_setprio 1
	v_mfma_f32_16x16x32_bf16 v[52:55], v[202:205], v[218:221], v[52:55]
	v_mfma_f32_16x16x32_bf16 v[48:51], v[210:213], v[218:221], v[48:51]
	v_mfma_f32_16x16x32_bf16 v[36:39], v[202:205], v[226:229], v[36:39]
	v_mfma_f32_16x16x32_bf16 v[32:35], v[210:213], v[226:229], v[32:35]
	v_mfma_f32_16x16x32_bf16 v[20:23], v[202:205], v[234:237], v[20:23]
	v_mfma_f32_16x16x32_bf16 v[16:19], v[210:213], v[234:237], v[16:19]
	v_mfma_f32_16x16x32_bf16 v[4:7], v[202:205], v[242:245], v[4:7]
	v_mfma_f32_16x16x32_bf16 v[0:3], v[210:213], v[242:245], v[0:3]
	v_mfma_f32_16x16x32_bf16 v[52:55], v[206:209], v[222:225], v[52:55]
	v_mfma_f32_16x16x32_bf16 v[48:51], v[214:217], v[222:225], v[48:51]
	v_mfma_f32_16x16x32_bf16 v[36:39], v[206:209], v[230:233], v[36:39]
	v_mfma_f32_16x16x32_bf16 v[32:35], v[214:217], v[230:233], v[32:35]
	v_mfma_f32_16x16x32_bf16 v[20:23], v[206:209], v[238:241], v[20:23]
	v_mfma_f32_16x16x32_bf16 v[16:19], v[214:217], v[238:241], v[16:19]
	v_mfma_f32_16x16x32_bf16 v[4:7], v[206:209], v[246:249], v[4:7]
	v_mfma_f32_16x16x32_bf16 v[0:3], v[214:217], v[246:249], v[0:3]
	s_setprio 0
	s_barrier
	v_or_b32_e32 v162, 0x18000, v169
	v_add_u32_e32 v171, 0x18400, v169
	ds_read_b128 v[162:165], v162
	ds_read_b128 v[172:175], v171
	v_add_u32_e32 v171, 0x18800, v169
	v_add_u32_e32 v198, 0x18c00, v169
	ds_read_b128 v[194:197], v171
	ds_read_b128 v[198:201], v198
	v_or_b32_e32 v171, 0x1c000, v169
	v_add_u32_e32 v206, 0x1c400, v169
	ds_read_b128 v[202:205], v171
	ds_read_b128 v[206:209], v206
	v_add_u32_e32 v171, 0x1c800, v169
	v_add_u32_e32 v214, 0x1cc00, v169
	ds_read_b128 v[210:213], v171
	ds_read_b128 v[214:217], v214
	s_add_u32 s4, s20, 0x90000
	s_addc_u32 s5, s21, 0
	s_mov_b32 m0, s44
	v_lshl_add_u64 v[250:251], s[4:5], 0, v[150:151]
	ds_read_b128 v[218:221], v168 offset:32768
	ds_read_b128 v[222:225], v168 offset:33792
	ds_read_b128 v[226:229], v168 offset:34816
	ds_read_b128 v[230:233], v168 offset:35840
	ds_read_b128 v[234:237], v168 offset:36864
	ds_read_b128 v[238:241], v168 offset:37888
	ds_read_b128 v[242:245], v168 offset:38912
	ds_read_b128 v[246:249], v168 offset:39936
	global_load_lds_dwordx4 v[250:251], off
	v_lshl_add_u64 v[250:251], s[4:5], 0, v[154:155]
	s_mov_b32 m0, s45
	s_nop 0
	global_load_lds_dwordx4 v[250:251], off
	s_waitcnt vmcnt(8)
	s_waitcnt lgkmcnt(0)
	s_barrier
	s_setprio 1
	s_waitcnt lgkmcnt(0)
	v_mfma_f32_16x16x32_bf16 v[124:127], v[162:165], v[218:221], v[124:127]
	v_mfma_f32_16x16x32_bf16 v[120:123], v[194:197], v[218:221], v[120:123]
	v_mfma_f32_16x16x32_bf16 v[108:111], v[162:165], v[226:229], v[108:111]
	v_mfma_f32_16x16x32_bf16 v[104:107], v[194:197], v[226:229], v[104:107]
	v_mfma_f32_16x16x32_bf16 v[92:95], v[162:165], v[234:237], v[92:95]
	v_mfma_f32_16x16x32_bf16 v[88:91], v[194:197], v[234:237], v[88:91]
	v_mfma_f32_16x16x32_bf16 v[76:79], v[162:165], v[242:245], v[76:79]
	v_mfma_f32_16x16x32_bf16 v[72:75], v[194:197], v[242:245], v[72:75]
	v_mfma_f32_16x16x32_bf16 v[124:127], v[172:175], v[222:225], v[124:127]
	v_mfma_f32_16x16x32_bf16 v[120:123], v[198:201], v[222:225], v[120:123]
	v_mfma_f32_16x16x32_bf16 v[108:111], v[172:175], v[230:233], v[108:111]
	v_mfma_f32_16x16x32_bf16 v[104:107], v[198:201], v[230:233], v[104:107]
	v_mfma_f32_16x16x32_bf16 v[92:95], v[172:175], v[238:241], v[92:95]
	v_mfma_f32_16x16x32_bf16 v[88:91], v[198:201], v[238:241], v[88:91]
	v_mfma_f32_16x16x32_bf16 v[76:79], v[172:175], v[246:249], v[76:79]
	v_mfma_f32_16x16x32_bf16 v[72:75], v[198:201], v[246:249], v[72:75]
	s_setprio 0
	s_setprio 1
	v_mfma_f32_16x16x32_bf16 v[116:119], v[202:205], v[218:221], v[116:119]
	v_mfma_f32_16x16x32_bf16 v[112:115], v[210:213], v[218:221], v[112:115]
	v_mfma_f32_16x16x32_bf16 v[100:103], v[202:205], v[226:229], v[100:103]
	v_mfma_f32_16x16x32_bf16 v[96:99], v[210:213], v[226:229], v[96:99]
	v_mfma_f32_16x16x32_bf16 v[84:87], v[202:205], v[234:237], v[84:87]
	v_mfma_f32_16x16x32_bf16 v[80:83], v[210:213], v[234:237], v[80:83]
	v_mfma_f32_16x16x32_bf16 v[68:71], v[202:205], v[242:245], v[68:71]
	v_mfma_f32_16x16x32_bf16 v[64:67], v[210:213], v[242:245], v[64:67]
	v_mfma_f32_16x16x32_bf16 v[116:119], v[206:209], v[222:225], v[116:119]
	v_mfma_f32_16x16x32_bf16 v[112:115], v[214:217], v[222:225], v[112:115]
	v_mfma_f32_16x16x32_bf16 v[100:103], v[206:209], v[230:233], v[100:103]
	v_mfma_f32_16x16x32_bf16 v[96:99], v[214:217], v[230:233], v[96:99]
	v_mfma_f32_16x16x32_bf16 v[84:87], v[206:209], v[238:241], v[84:87]
	v_mfma_f32_16x16x32_bf16 v[80:83], v[214:217], v[238:241], v[80:83]
	v_mfma_f32_16x16x32_bf16 v[68:71], v[206:209], v[246:249], v[68:71]
	v_mfma_f32_16x16x32_bf16 v[64:67], v[214:217], v[246:249], v[64:67]
	s_setprio 0
	s_barrier
; #define PG8_STAGE(bufoff, gbase, voff) do { _Pragma("unroll") for (int _i = 0; _i < 2; ++_i) \
;         __builtin_amdgcn_global_load_lds((const unsigned*)((const char*)(gbase) + (voff)[_i]), (PG8_LAS unsigned*)(lds + (bufoff) + ldsw + _i * 8192), 16, 0, 0); } while (0)
; #define PG8_LDA(dst, b, h) do { _Pragma("unroll") for (int m = 0; m < 4; ++m) _Pragma("unroll") for (int k = 0; k < 2; ++k) dst[m][k] = *(const PG8_LAS bf16x8*)(lds + PG8_SA(b, h) + aoff + m * 2048 + k * 1024); } while (0)
; #define PG8_MMA(ai, bj, At, Bt) do { __builtin_amdgcn_s_setprio(1); _Pragma("unroll") for (int m = 0; m < 4; ++m) _Pragma("unroll") for (int n = 0; n < 2; ++n) _Pragma("unroll") for (int k = 0; k < 2; ++k) \
;         acc[ai][bj][m][n] = __builtin_amdgcn_mfma_f32_16x16x32_bf16(Bt[n][k], At[m][k], acc[ai][bj][m][n], 0, 0, 0); __builtin_amdgcn_s_setprio(0); } while (0)
; #define PG8_WAIT_V(n) asm volatile("s_waitcnt vmcnt(" #n ")" ::: "memory")
; #define PG8_WAIT_L(n) asm volatile("s_waitcnt lgkmcnt(" #n ")" ::: "memory")
; #define PG8_BAR __builtin_amdgcn_s_barrier()
; #define PG8_SCHED __builtin_amdgcn_sched_barrier(0)
; template <class Epi, class Sched, bool ALIGN_EPI = false, bool SP2 = false>
; __device__ __forceinline__ void gemm_phase(PG8_LAS unsigned char* lds, const Gemm g, const Sched& S, const Epi& E) {
;     ...
;         for (int t = 0; t < nt; t += 2) {
;     ...
;             PG8_LDA(At, 1, 1); PG8_STAGE(PG8_SB(1, 0), b3, voffB); PG8_STAGE(PG8_SB(1, 1), b3 + hstepB, voffB); PG8_STAGE(PG8_SA(1, 0), a3, voffA);
;             PG8_WAIT_V(8); PG8_WAIT_L(0); PG8_BAR; PG8_MMA(1, 0, At, B0); PG8_MMA(1, 1, At, B1); PG8_BAR; PG8_SCHED;
	s_mov_b32 m0, s46
	v_lshl_add_u64 v[166:167], v[166:167], 0, s[54:55]
	s_add_u32 s4, s18, 0x18080
	ds_read_b128 v[218:221], v168 offset:49152
	ds_read_b128 v[222:225], v168 offset:50176
	ds_read_b128 v[226:229], v168 offset:51200
	ds_read_b128 v[230:233], v168 offset:52224
	ds_read_b128 v[234:237], v168 offset:53248
	ds_read_b128 v[238:241], v168 offset:54272
	ds_read_b128 v[242:245], v168 offset:55296
	ds_read_b128 v[246:249], v168 offset:56320
	global_load_lds_dwordx4 v[166:167], off
	v_lshl_add_u64 v[166:167], v[176:177], 0, s[54:55]
	s_mov_b32 m0, s47
	s_addc_u32 s5, s19, 0
	global_load_lds_dwordx4 v[166:167], off
	v_lshl_add_u64 v[166:167], s[4:5], 0, v[152:153]
	s_mov_b32 m0, s62
	s_nop 0
	global_load_lds_dwordx4 v[166:167], off
	v_lshl_add_u64 v[166:167], s[4:5], 0, v[156:157]
	s_mov_b32 m0, s63
	s_nop 0
	global_load_lds_dwordx4 v[166:167], off
	v_lshl_add_u64 v[166:167], v[178:179], 0, s[54:55]
	s_mov_b32 m0, s58
	s_nop 0
	global_load_lds_dwordx4 v[166:167], off
	v_lshl_add_u64 v[166:167], v[188:189], 0, s[54:55]
	s_mov_b32 m0, s59
	s_nop 0
	global_load_lds_dwordx4 v[166:167], off
	s_waitcnt vmcnt(8)
	s_waitcnt lgkmcnt(0)
	s_barrier
	s_setprio 1
	s_waitcnt lgkmcnt(0)
	v_mfma_f32_16x16x32_bf16 v[60:63], v[162:165], v[218:221], v[60:63]
	v_mfma_f32_16x16x32_bf16 v[56:59], v[194:197], v[218:221], v[56:59]
	v_mfma_f32_16x16x32_bf16 v[44:47], v[162:165], v[226:229], v[44:47]
	v_mfma_f32_16x16x32_bf16 v[40:43], v[194:197], v[226:229], v[40:43]
	v_mfma_f32_16x16x32_bf16 v[28:31], v[162:165], v[234:237], v[28:31]
	v_mfma_f32_16x16x32_bf16 v[24:27], v[194:197], v[234:237], v[24:27]
	v_mfma_f32_16x16x32_bf16 v[12:15], v[162:165], v[242:245], v[12:15]
	v_mfma_f32_16x16x32_bf16 v[8:11], v[194:197], v[242:245], v[8:11]
	v_mfma_f32_16x16x32_bf16 v[60:63], v[172:175], v[222:225], v[60:63]
	v_mfma_f32_16x16x32_bf16 v[56:59], v[198:201], v[222:225], v[56:59]
	v_mfma_f32_16x16x32_bf16 v[44:47], v[172:175], v[230:233], v[44:47]
	v_mfma_f32_16x16x32_bf16 v[40:43], v[198:201], v[230:233], v[40:43]
	v_mfma_f32_16x16x32_bf16 v[28:31], v[172:175], v[238:241], v[28:31]
	v_mfma_f32_16x16x32_bf16 v[24:27], v[198:201], v[238:241], v[24:27]
	v_mfma_f32_16x16x32_bf16 v[12:15], v[172:175], v[246:249], v[12:15]
	v_mfma_f32_16x16x32_bf16 v[8:11], v[198:201], v[246:249], v[8:11]
	s_setprio 0
	s_setprio 1
	v_mfma_f32_16x16x32_bf16 v[52:55], v[202:205], v[218:221], v[52:55]
	v_mfma_f32_16x16x32_bf16 v[48:51], v[210:213], v[218:221], v[48:51]
	v_mfma_f32_16x16x32_bf16 v[36:39], v[202:205], v[226:229], v[36:39]
	v_mfma_f32_16x16x32_bf16 v[32:35], v[210:213], v[226:229], v[32:35]
	v_mfma_f32_16x16x32_bf16 v[20:23], v[202:205], v[234:237], v[20:23]
	v_mfma_f32_16x16x32_bf16 v[16:19], v[210:213], v[234:237], v[16:19]
	v_mfma_f32_16x16x32_bf16 v[4:7], v[202:205], v[242:245], v[4:7]
	v_mfma_f32_16x16x32_bf16 v[0:3], v[210:213], v[242:245], v[0:3]
	v_mfma_f32_16x16x32_bf16 v[52:55], v[206:209], v[222:225], v[52:55]
	v_mfma_f32_16x16x32_bf16 v[48:51], v[214:217], v[222:225], v[48:51]
	v_mfma_f32_16x16x32_bf16 v[36:39], v[206:209], v[230:233], v[36:39]
	v_mfma_f32_16x16x32_bf16 v[32:35], v[214:217], v[230:233], v[32:35]
	v_mfma_f32_16x16x32_bf16 v[20:23], v[206:209], v[238:241], v[20:23]
	v_mfma_f32_16x16x32_bf16 v[16:19], v[214:217], v[238:241], v[16:19]
	v_mfma_f32_16x16x32_bf16 v[4:7], v[206:209], v[246:249], v[4:7]
	v_mfma_f32_16x16x32_bf16 v[0:3], v[214:217], v[246:249], v[0:3]
	s_setprio 0
	s_barrier
	s_add_i32 s74, s74, 2
	s_add_u32 s42, s42, 0x100
	s_addc_u32 s43, s43, 0
	s_cmp_gt_u32 s74, 3
	s_mov_b64 s[4:5], s[0:1]
	s_cbranch_scc0 .LBB0_1350
	s_and_b64 vcc, exec, s[8:9]
	s_cbranch_vccz .LBB0_1353
	s_barrier

;     __device__ __forceinline__ bool next(int i, Unit& u) const { if (i != 0 || c >= n) return false; u.pm = pm; u.pn = c & 3; return true; }
; #define PG8_STAGE(bufoff, gbase, voff) do { _Pragma("unroll") for (int _i = 0; _i < 2; ++_i) \
;         __builtin_amdgcn_global_load_lds((const unsigned*)((const char*)(gbase) + (voff)[_i]), (PG8_LAS unsigned*)(lds + (bufoff) + ldsw + _i * 8192), 16, 0, 0); } while (0)
; #define PG8_LDA(dst, b, h) do { _Pragma("unroll") for (int m = 0; m < 4; ++m) _Pragma("unroll") for (int k = 0; k < 2; ++k) dst[m][k] = *(const PG8_LAS bf16x8*)(lds + PG8_SA(b, h) + aoff + m * 2048 + k * 1024); } while (0)
; #define PG8_LDB(dst, b, h) do { _Pragma("unroll") for (int n = 0; n < 2; ++n) _Pragma("unroll") for (int k = 0; k < 2; ++k) dst[n][k] = *(const PG8_LAS bf16x8*)(lds + PG8_SB(b, h) + boff + n * 2048 + k * 1024); } while (0)
; #define PG8_WAIT_V(n) asm volatile("s_waitcnt vmcnt(" #n ")" ::: "memory")
; #define PG8_WAIT_L(n) asm volatile("s_waitcnt lgkmcnt(" #n ")" ::: "memory")
; #define PG8_BAR __builtin_amdgcn_s_barrier()
; #define PG8_SCHED __builtin_amdgcn_sched_barrier(0)
; template <class Epi, class Sched, bool ALIGN_EPI = false, bool SP2 = false>
; __device__ __forceinline__ void gemm_phase(PG8_LAS unsigned char* lds, const Gemm g, const Sched& S, const Epi& E) {
;     ...
;         const bool has_next = S.next(ui + 1, nxt);
;         const char* nA = has_next ? (const char*)g.A + (size_t)nxt.pm * tstepA : cA; const char* nB = has_next ? (const char*)g.Bt + (size_t)nxt.pn * tstepB : cB;
;         for (int t = 0; t < nt; t += 2) {
;             const bool last = (t == nt - 2);
;             const char* a1 = cA + (size_t)(t + 1) * kstep;
;             const char* a2 = last ? nA : cA + (size_t)(t + 2) * kstep; const char* b2 = last ? nB : cB + (size_t)(t + 2) * kstep;
;             const char* a3 = a2 + kstep; const char* b3 = b2 + kstep;
;             if (last && has_next) S.a_ready(nxt);
;             if constexpr (SP2) {
;             PG8_LDB(B0, 0, 0); PG8_LDB(B1, 0, 1); PG8_SCHED; PG8_LDA(At, 0, 0); PG8_STAGE(PG8_SA(1, 1), a1 + hstepA, voffA);
;             PG8_WAIT_V(8); PG8_WAIT_L(0); PG8_BAR; PG8_MMA(0, 0, At, B0); PG8_MMA(0, 1, At, B1); PG8_BAR; PG8_SCHED;
;             PG8_LDA(At, 0, 1); PG8_STAGE(PG8_SB(0, 0), b2, voffB); PG8_STAGE(PG8_SB(0, 1), b2 + hstepB, voffB); PG8_STAGE(PG8_SA(0, 0), a2, voffA);
.LBB0_1474:
	s_add_u32 s36, s96, s18
	s_addc_u32 s57, s97, 0
	s_add_u32 s19, s36, 0x100
	s_addc_u32 s58, s57, 0
	s_and_b64 s[20:21], s[42:43], exec
	s_cselect_b32 s63, s17, s58
	s_cselect_b32 s62, s16, s19
	s_add_u32 s18, s94, s18
	s_addc_u32 s19, s95, 0
	s_add_u32 s20, s18, 0x100
	v_add_u32_e32 v169, 0x10800, v167
	s_addc_u32 s21, s19, 0
	ds_read_b128 v[170:173], v169
	v_add_u32_e32 v169, 0x10c00, v167
	s_and_b64 s[18:19], s[42:43], exec
	ds_read_b128 v[174:177], v169
	v_or_b32_e32 v169, 0x14000, v167
	s_cselect_b32 s59, s5, s21
	s_cselect_b32 s58, s11, s20
	s_add_u32 s20, s36, 0x90080
	ds_read_b128 v[194:197], v169
	v_add_u32_e32 v169, 0x14400, v167
	s_addc_u32 s21, s57, 0
	s_add_i32 m0, s56, 0xc000
	s_add_i32 s36, s56, 0xe000
	ds_read_b128 v[198:201], v169
	v_add_u32_e32 v169, 0x14800, v167
	s_add_u32 s18, s58, 0x10000
	v_or_b32_e32 v158, 0x10000, v167
	v_add_u32_e32 v162, 0x10400, v167
	ds_read_b128 v[202:205], v169
	v_add_u32_e32 v169, 0x14c00, v167
	s_addc_u32 s19, s59, 0
	ds_read_b128 v[158:161], v158
	ds_read_b128 v[162:165], v162
	ds_read_b128 v[206:209], v169
	s_add_u32 s42, s62, 0x90000
	s_addc_u32 s43, s63, 0
	s_add_u32 vcc_lo, s58, 0x10080
	s_addc_u32 vcc_hi, s59, 0
	v_lshl_add_u64 v[178:179], s[20:21], 0, v[150:151]
	ds_read_b128 v[210:213], v166
	ds_read_b128 v[214:217], v166 offset:1024
	ds_read_b128 v[218:221], v166 offset:2048
	ds_read_b128 v[222:225], v166 offset:3072
	ds_read_b128 v[226:229], v166 offset:4096
	ds_read_b128 v[230:233], v166 offset:5120
	ds_read_b128 v[234:237], v166 offset:6144
	ds_read_b128 v[238:241], v166 offset:7168
	global_load_lds_dwordx4 v[178:179], off
	v_lshl_add_u64 v[178:179], s[20:21], 0, v[154:155]
	s_mov_b32 m0, s36
	s_nop 0
	global_load_lds_dwordx4 v[178:179], off
	s_waitcnt vmcnt(8)
	s_waitcnt lgkmcnt(0)
	s_barrier
	s_setprio 1
	s_waitcnt lgkmcnt(0)
	v_mfma_f32_16x16x32_bf16 v[124:127], v[158:161], v[210:213], v[124:127]
	v_mfma_f32_16x16x32_bf16 v[120:123], v[170:173], v[210:213], v[120:123]
	v_mfma_f32_16x16x32_bf16 v[108:111], v[158:161], v[218:221], v[108:111]
	v_mfma_f32_16x16x32_bf16 v[104:107], v[170:173], v[218:221], v[104:107]
	v_mfma_f32_16x16x32_bf16 v[92:95], v[158:161], v[226:229], v[92:95]
	v_mfma_f32_16x16x32_bf16 v[88:91], v[170:173], v[226:229], v[88:91]
	v_mfma_f32_16x16x32_bf16 v[76:79], v[158:161], v[234:237], v[76:79]
	v_mfma_f32_16x16x32_bf16 v[72:75], v[170:173], v[234:237], v[72:75]
	v_mfma_f32_16x16x32_bf16 v[124:127], v[162:165], v[214:217], v[124:127]
	v_mfma_f32_16x16x32_bf16 v[120:123], v[174:177], v[214:217], v[120:123]
	v_mfma_f32_16x16x32_bf16 v[108:111], v[162:165], v[222:225], v[108:111]
	v_mfma_f32_16x16x32_bf16 v[104:107], v[174:177], v[222:225], v[104:107]
	v_mfma_f32_16x16x32_bf16 v[92:95], v[162:165], v[230:233], v[92:95]
	v_mfma_f32_16x16x32_bf16 v[88:91], v[174:177], v[230:233], v[88:91]
	v_mfma_f32_16x16x32_bf16 v[76:79], v[162:165], v[238:241], v[76:79]
	v_mfma_f32_16x16x32_bf16 v[72:75], v[174:177], v[238:241], v[72:75]
	s_setprio 0
	s_setprio 1
	v_mfma_f32_16x16x32_bf16 v[116:119], v[194:197], v[210:213], v[116:119]
	v_mfma_f32_16x16x32_bf16 v[112:115], v[202:205], v[210:213], v[112:115]
	v_mfma_f32_16x16x32_bf16 v[100:103], v[194:197], v[218:221], v[100:103]
	v_mfma_f32_16x16x32_bf16 v[96:99], v[202:205], v[218:221], v[96:99]
	v_mfma_f32_16x16x32_bf16 v[84:87], v[194:197], v[226:229], v[84:87]
	v_mfma_f32_16x16x32_bf16 v[80:83], v[202:205], v[226:229], v[80:83]
	v_mfma_f32_16x16x32_bf16 v[68:71], v[194:197], v[234:237], v[68:71]
	v_mfma_f32_16x16x32_bf16 v[64:67], v[202:205], v[234:237], v[64:67]
	v_mfma_f32_16x16x32_bf16 v[116:119], v[198:201], v[214:217], v[116:119]
	v_mfma_f32_16x16x32_bf16 v[112:115], v[206:209], v[214:217], v[112:115]
	v_mfma_f32_16x16x32_bf16 v[100:103], v[198:201], v[222:225], v[100:103]
	v_mfma_f32_16x16x32_bf16 v[96:99], v[206:209], v[222:225], v[96:99]
	v_mfma_f32_16x16x32_bf16 v[84:87], v[198:201], v[230:233], v[84:87]
	v_mfma_f32_16x16x32_bf16 v[80:83], v[206:209], v[230:233], v[80:83]
	v_mfma_f32_16x16x32_bf16 v[68:71], v[198:201], v[238:241], v[68:71]
	v_mfma_f32_16x16x32_bf16 v[64:67], v[206:209], v[238:241], v[64:67]
	s_setprio 0
	s_barrier
	s_mov_b32 m0, s37
	v_lshl_add_u64 v[178:179], s[58:59], 0, v[152:153]
	ds_read_b128 v[210:213], v166 offset:16384
	ds_read_b128 v[214:217], v166 offset:17408
	ds_read_b128 v[218:221], v166 offset:18432
	ds_read_b128 v[222:225], v166 offset:19456
	ds_read_b128 v[226:229], v166 offset:20480
	ds_read_b128 v[230:233], v166 offset:21504
	ds_read_b128 v[234:237], v166 offset:22528
	ds_read_b128 v[238:241], v166 offset:23552
	global_load_lds_dwordx4 v[178:179], off
	v_lshl_add_u64 v[188:189], s[58:59], 0, v[156:157]
	s_mov_b32 m0, s38
	v_lshl_add_u64 v[242:243], s[18:19], 0, v[152:153]
	global_load_lds_dwordx4 v[188:189], off
	s_mov_b32 m0, s39
	v_lshl_add_u64 v[244:245], s[62:63], 0, v[154:155]
	global_load_lds_dwordx4 v[242:243], off
	v_lshl_add_u64 v[242:243], s[18:19], 0, v[156:157]
	s_mov_b32 m0, s40
	s_nop 0
	global_load_lds_dwordx4 v[242:243], off
	v_lshl_add_u64 v[242:243], s[62:63], 0, v[150:151]
	s_mov_b32 m0, s56
	s_nop 0
	global_load_lds_dwordx4 v[242:243], off
	s_mov_b32 m0, s41
	s_nop 0
	global_load_lds_dwordx4 v[244:245], off
	s_waitcnt vmcnt(8)
	s_waitcnt lgkmcnt(0)
	s_barrier
; #define PG8_STAGE(bufoff, gbase, voff) do { _Pragma("unroll") for (int _i = 0; _i < 2; ++_i) \
;         __builtin_amdgcn_global_load_lds((const unsigned*)((const char*)(gbase) + (voff)[_i]), (PG8_LAS unsigned*)(lds + (bufoff) + ldsw + _i * 8192), 16, 0, 0); } while (0)
; #define PG8_LDA(dst, b, h) do { _Pragma("unroll") for (int m = 0; m < 4; ++m) _Pragma("unroll") for (int k = 0; k < 2; ++k) dst[m][k] = *(const PG8_LAS bf16x8*)(lds + PG8_SA(b, h) + aoff + m * 2048 + k * 1024); } while (0)
; #define PG8_LDB(dst, b, h) do { _Pragma("unroll") for (int n = 0; n < 2; ++n) _Pragma("unroll") for (int k = 0; k < 2; ++k) dst[n][k] = *(const PG8_LAS bf16x8*)(lds + PG8_SB(b, h) + boff + n * 2048 + k * 1024); } while (0)
; #define PG8_MMA(ai, bj, At, Bt) do { __builtin_amdgcn_s_setprio(1); _Pragma("unroll") for (int m = 0; m < 4; ++m) _Pragma("unroll") for (int n = 0; n < 2; ++n) _Pragma("unroll") for (int k = 0; k < 2; ++k) \
;         acc[ai][bj][m][n] = __builtin_amdgcn_mfma_f32_16x16x32_bf16(Bt[n][k], At[m][k], acc[ai][bj][m][n], 0, 0, 0); __builtin_amdgcn_s_setprio(0); } while (0)
; #define PG8_WAIT_V(n) asm volatile("s_waitcnt vmcnt(" #n ")" ::: "memory")
; #define PG8_WAIT_L(n) asm volatile("s_waitcnt lgkmcnt(" #n ")" ::: "memory")
; #define PG8_BAR __builtin_amdgcn_s_barrier()
; #define PG8_SCHED __builtin_amdgcn_sched_barrier(0)
; template <class Epi, class Sched, bool ALIGN_EPI = false, bool SP2 = false>
; __device__ __forceinline__ void gemm_phase(PG8_LAS unsigned char* lds, const Gemm g, const Sched& S, const Epi& E) {
;     ...
;             PG8_WAIT_V(8); PG8_WAIT_L(0); PG8_BAR; PG8_MMA(1, 0, At, B0); PG8_MMA(1, 1, At, B1); PG8_BAR; PG8_SCHED;
;             PG8_LDB(B0, 1, 0); PG8_LDB(B1, 1, 1); PG8_SCHED; PG8_LDA(At, 1, 0); PG8_STAGE(PG8_SA(0, 1), a2 + hstepA, voffA);
;             PG8_WAIT_V(8); PG8_WAIT_L(0); PG8_BAR; PG8_MMA(0, 0, At, B0); PG8_MMA(0, 1, At, B1); PG8_BAR; PG8_SCHED;
	s_setprio 1
	s_waitcnt lgkmcnt(0)
	v_mfma_f32_16x16x32_bf16 v[60:63], v[158:161], v[210:213], v[60:63]
	v_mfma_f32_16x16x32_bf16 v[56:59], v[170:173], v[210:213], v[56:59]
	v_mfma_f32_16x16x32_bf16 v[44:47], v[158:161], v[218:221], v[44:47]
	v_mfma_f32_16x16x32_bf16 v[40:43], v[170:173], v[218:221], v[40:43]
	v_mfma_f32_16x16x32_bf16 v[28:31], v[158:161], v[226:229], v[28:31]
	v_mfma_f32_16x16x32_bf16 v[24:27], v[170:173], v[226:229], v[24:27]
	v_mfma_f32_16x16x32_bf16 v[12:15], v[158:161], v[234:237], v[12:15]
	v_mfma_f32_16x16x32_bf16 v[8:11], v[170:173], v[234:237], v[8:11]
	v_mfma_f32_16x16x32_bf16 v[60:63], v[162:165], v[214:217], v[60:63]
	v_mfma_f32_16x16x32_bf16 v[56:59], v[174:177], v[214:217], v[56:59]
	v_mfma_f32_16x16x32_bf16 v[44:47], v[162:165], v[222:225], v[44:47]
	v_mfma_f32_16x16x32_bf16 v[40:43], v[174:177], v[222:225], v[40:43]
	v_mfma_f32_16x16x32_bf16 v[28:31], v[162:165], v[230:233], v[28:31]
	v_mfma_f32_16x16x32_bf16 v[24:27], v[174:177], v[230:233], v[24:27]
	v_mfma_f32_16x16x32_bf16 v[12:15], v[162:165], v[238:241], v[12:15]
	v_mfma_f32_16x16x32_bf16 v[8:11], v[174:177], v[238:241], v[8:11]
	s_setprio 0
	s_setprio 1
	v_mfma_f32_16x16x32_bf16 v[52:55], v[194:197], v[210:213], v[52:55]
	v_mfma_f32_16x16x32_bf16 v[48:51], v[202:205], v[210:213], v[48:51]
	v_mfma_f32_16x16x32_bf16 v[36:39], v[194:197], v[218:221], v[36:39]
	v_mfma_f32_16x16x32_bf16 v[32:35], v[202:205], v[218:221], v[32:35]
	v_mfma_f32_16x16x32_bf16 v[20:23], v[194:197], v[226:229], v[20:23]
	v_mfma_f32_16x16x32_bf16 v[16:19], v[202:205], v[226:229], v[16:19]
	v_mfma_f32_16x16x32_bf16 v[4:7], v[194:197], v[234:237], v[4:7]
	v_mfma_f32_16x16x32_bf16 v[0:3], v[202:205], v[234:237], v[0:3]
	v_mfma_f32_16x16x32_bf16 v[52:55], v[198:201], v[214:217], v[52:55]
	v_mfma_f32_16x16x32_bf16 v[48:51], v[206:209], v[214:217], v[48:51]
	v_mfma_f32_16x16x32_bf16 v[36:39], v[198:201], v[222:225], v[36:39]
	v_mfma_f32_16x16x32_bf16 v[32:35], v[206:209], v[222:225], v[32:35]
	v_mfma_f32_16x16x32_bf16 v[20:23], v[198:201], v[230:233], v[20:23]
	v_mfma_f32_16x16x32_bf16 v[16:19], v[206:209], v[230:233], v[16:19]
	v_mfma_f32_16x16x32_bf16 v[4:7], v[198:201], v[238:241], v[4:7]
	v_mfma_f32_16x16x32_bf16 v[0:3], v[206:209], v[238:241], v[0:3]
	s_setprio 0
	s_barrier
	v_or_b32_e32 v158, 0x18000, v167
	v_add_u32_e32 v162, 0x18400, v167
	v_add_u32_e32 v169, 0x18800, v167
	v_add_u32_e32 v174, 0x18c00, v167
	ds_read_b128 v[158:161], v158
	ds_read_b128 v[162:165], v162
	ds_read_b128 v[170:173], v169
	ds_read_b128 v[174:177], v174
	v_or_b32_e32 v169, 0x1c000, v167
	v_add_u32_e32 v198, 0x1c400, v167
	ds_read_b128 v[194:197], v169
	ds_read_b128 v[198:201], v198
	v_add_u32_e32 v169, 0x1c800, v167
	v_add_u32_e32 v206, 0x1cc00, v167
	ds_read_b128 v[202:205], v169
	ds_read_b128 v[206:209], v206
	s_mov_b32 m0, s44
	v_lshl_add_u64 v[246:247], s[42:43], 0, v[150:151]
	ds_read_b128 v[210:213], v166 offset:32768
	ds_read_b128 v[214:217], v166 offset:33792
	ds_read_b128 v[218:221], v166 offset:34816
	ds_read_b128 v[222:225], v166 offset:35840
	ds_read_b128 v[226:229], v166 offset:36864
	ds_read_b128 v[230:233], v166 offset:37888
	ds_read_b128 v[234:237], v166 offset:38912
	ds_read_b128 v[238:241], v166 offset:39936
	global_load_lds_dwordx4 v[246:247], off
	v_lshl_add_u64 v[246:247], s[42:43], 0, v[154:155]
	s_mov_b32 m0, s45
	s_nop 0
	global_load_lds_dwordx4 v[246:247], off
	s_waitcnt vmcnt(8)
	s_waitcnt lgkmcnt(0)
	s_barrier
	s_setprio 1
	s_waitcnt lgkmcnt(0)
	v_mfma_f32_16x16x32_bf16 v[124:127], v[158:161], v[210:213], v[124:127]
	v_mfma_f32_16x16x32_bf16 v[120:123], v[170:173], v[210:213], v[120:123]
	v_mfma_f32_16x16x32_bf16 v[108:111], v[158:161], v[218:221], v[108:111]
	v_mfma_f32_16x16x32_bf16 v[104:107], v[170:173], v[218:221], v[104:107]
	v_mfma_f32_16x16x32_bf16 v[92:95], v[158:161], v[226:229], v[92:95]
	v_mfma_f32_16x16x32_bf16 v[88:91], v[170:173], v[226:229], v[88:91]
	v_mfma_f32_16x16x32_bf16 v[76:79], v[158:161], v[234:237], v[76:79]
	v_mfma_f32_16x16x32_bf16 v[72:75], v[170:173], v[234:237], v[72:75]
	v_mfma_f32_16x16x32_bf16 v[124:127], v[162:165], v[214:217], v[124:127]
	v_mfma_f32_16x16x32_bf16 v[120:123], v[174:177], v[214:217], v[120:123]
	v_mfma_f32_16x16x32_bf16 v[108:111], v[162:165], v[222:225], v[108:111]
	v_mfma_f32_16x16x32_bf16 v[104:107], v[174:177], v[222:225], v[104:107]
	v_mfma_f32_16x16x32_bf16 v[92:95], v[162:165], v[230:233], v[92:95]
	v_mfma_f32_16x16x32_bf16 v[88:91], v[174:177], v[230:233], v[88:91]
	v_mfma_f32_16x16x32_bf16 v[76:79], v[162:165], v[238:241], v[76:79]
	v_mfma_f32_16x16x32_bf16 v[72:75], v[174:177], v[238:241], v[72:75]
	s_setprio 0
	s_setprio 1
	v_mfma_f32_16x16x32_bf16 v[116:119], v[194:197], v[210:213], v[116:119]
	v_mfma_f32_16x16x32_bf16 v[112:115], v[202:205], v[210:213], v[112:115]
	v_mfma_f32_16x16x32_bf16 v[100:103], v[194:197], v[218:221], v[100:103]
	v_mfma_f32_16x16x32_bf16 v[96:99], v[202:205], v[218:221], v[96:99]
	v_mfma_f32_16x16x32_bf16 v[84:87], v[194:197], v[226:229], v[84:87]
	v_mfma_f32_16x16x32_bf16 v[80:83], v[202:205], v[226:229], v[80:83]
	v_mfma_f32_16x16x32_bf16 v[68:71], v[194:197], v[234:237], v[68:71]
	v_mfma_f32_16x16x32_bf16 v[64:67], v[202:205], v[234:237], v[64:67]
	v_mfma_f32_16x16x32_bf16 v[116:119], v[198:201], v[214:217], v[116:119]
	v_mfma_f32_16x16x32_bf16 v[112:115], v[206:209], v[214:217], v[112:115]
	v_mfma_f32_16x16x32_bf16 v[100:103], v[198:201], v[222:225], v[100:103]
	v_mfma_f32_16x16x32_bf16 v[96:99], v[206:209], v[222:225], v[96:99]
	v_mfma_f32_16x16x32_bf16 v[84:87], v[198:201], v[230:233], v[84:87]
	v_mfma_f32_16x16x32_bf16 v[80:83], v[206:209], v[230:233], v[80:83]
	v_mfma_f32_16x16x32_bf16 v[68:71], v[198:201], v[238:241], v[68:71]
	v_mfma_f32_16x16x32_bf16 v[64:67], v[206:209], v[238:241], v[64:67]
	s_setprio 0
	s_barrier
; #define PG8_STAGE(bufoff, gbase, voff) do { _Pragma("unroll") for (int _i = 0; _i < 2; ++_i) \
;         __builtin_amdgcn_global_load_lds((const unsigned*)((const char*)(gbase) + (voff)[_i]), (PG8_LAS unsigned*)(lds + (bufoff) + ldsw + _i * 8192), 16, 0, 0); } while (0)
; #define PG8_LDA(dst, b, h) do { _Pragma("unroll") for (int m = 0; m < 4; ++m) _Pragma("unroll") for (int k = 0; k < 2; ++k) dst[m][k] = *(const PG8_LAS bf16x8*)(lds + PG8_SA(b, h) + aoff + m * 2048 + k * 1024); } while (0)
; #define PG8_MMA(ai, bj, At, Bt) do { __builtin_amdgcn_s_setprio(1); _Pragma("unroll") for (int m = 0; m < 4; ++m) _Pragma("unroll") for (int n = 0; n < 2; ++n) _Pragma("unroll") for (int k = 0; k < 2; ++k) \
;         acc[ai][bj][m][n] = __builtin_amdgcn_mfma_f32_16x16x32_bf16(Bt[n][k], At[m][k], acc[ai][bj][m][n], 0, 0, 0); __builtin_amdgcn_s_setprio(0); } while (0)
; #define PG8_WAIT_V(n) asm volatile("s_waitcnt vmcnt(" #n ")" ::: "memory")
; #define PG8_WAIT_L(n) asm volatile("s_waitcnt lgkmcnt(" #n ")" ::: "memory")
; #define PG8_BAR __builtin_amdgcn_s_barrier()
; #define PG8_SCHED __builtin_amdgcn_sched_barrier(0)
; template <class Epi, class Sched, bool ALIGN_EPI = false, bool SP2 = false>
; __device__ __forceinline__ void gemm_phase(PG8_LAS unsigned char* lds, const Gemm g, const Sched& S, const Epi& E) {
;     ...
;         for (int t = 0; t < nt; t += 2) {
;     ...
;             PG8_LDA(At, 1, 1); PG8_STAGE(PG8_SB(1, 0), b3, voffB); PG8_STAGE(PG8_SB(1, 1), b3 + hstepB, voffB); PG8_STAGE(PG8_SA(1, 0), a3, voffA);
;             PG8_WAIT_V(8); PG8_WAIT_L(0); PG8_BAR; PG8_MMA(1, 0, At, B0); PG8_MMA(1, 1, At, B1); PG8_BAR; PG8_SCHED;
	s_mov_b32 m0, s46
	v_lshl_add_u64 v[178:179], v[178:179], 0, s[54:55]
	ds_read_b128 v[210:213], v166 offset:49152
	ds_read_b128 v[214:217], v166 offset:50176
	ds_read_b128 v[218:221], v166 offset:51200
	ds_read_b128 v[222:225], v166 offset:52224
	ds_read_b128 v[226:229], v166 offset:53248
	ds_read_b128 v[230:233], v166 offset:54272
	ds_read_b128 v[234:237], v166 offset:55296
	ds_read_b128 v[238:241], v166 offset:56320
	global_load_lds_dwordx4 v[178:179], off
	v_lshl_add_u64 v[178:179], v[188:189], 0, s[54:55]
	s_mov_b32 m0, s47
	s_nop 0
	global_load_lds_dwordx4 v[178:179], off
	v_lshl_add_u64 v[178:179], vcc, 0, v[152:153]
	s_mov_b32 m0, s72
	s_nop 0
	global_load_lds_dwordx4 v[178:179], off
	v_lshl_add_u64 v[178:179], vcc, 0, v[156:157]
	s_mov_b32 m0, s73
	s_nop 0
	global_load_lds_dwordx4 v[178:179], off
	v_lshl_add_u64 v[178:179], v[242:243], 0, s[54:55]
	s_mov_b32 m0, s64
	s_nop 0
	global_load_lds_dwordx4 v[178:179], off
	v_lshl_add_u64 v[178:179], v[244:245], 0, s[54:55]
	s_mov_b32 m0, s65
	s_nop 0
	global_load_lds_dwordx4 v[178:179], off
	s_waitcnt vmcnt(8)
	s_waitcnt lgkmcnt(0)
	s_barrier
	s_setprio 1
	s_waitcnt lgkmcnt(0)
	v_mfma_f32_16x16x32_bf16 v[60:63], v[158:161], v[210:213], v[60:63]
	v_mfma_f32_16x16x32_bf16 v[56:59], v[170:173], v[210:213], v[56:59]
	v_mfma_f32_16x16x32_bf16 v[44:47], v[158:161], v[218:221], v[44:47]
	v_mfma_f32_16x16x32_bf16 v[40:43], v[170:173], v[218:221], v[40:43]
	v_mfma_f32_16x16x32_bf16 v[28:31], v[158:161], v[226:229], v[28:31]
	v_mfma_f32_16x16x32_bf16 v[24:27], v[170:173], v[226:229], v[24:27]
	v_mfma_f32_16x16x32_bf16 v[12:15], v[158:161], v[234:237], v[12:15]
	v_mfma_f32_16x16x32_bf16 v[8:11], v[170:173], v[234:237], v[8:11]
	v_mfma_f32_16x16x32_bf16 v[60:63], v[162:165], v[214:217], v[60:63]
	v_mfma_f32_16x16x32_bf16 v[56:59], v[174:177], v[214:217], v[56:59]
	v_mfma_f32_16x16x32_bf16 v[44:47], v[162:165], v[222:225], v[44:47]
	v_mfma_f32_16x16x32_bf16 v[40:43], v[174:177], v[222:225], v[40:43]
	v_mfma_f32_16x16x32_bf16 v[28:31], v[162:165], v[230:233], v[28:31]
	v_mfma_f32_16x16x32_bf16 v[24:27], v[174:177], v[230:233], v[24:27]
	v_mfma_f32_16x16x32_bf16 v[12:15], v[162:165], v[238:241], v[12:15]
	v_mfma_f32_16x16x32_bf16 v[8:11], v[174:177], v[238:241], v[8:11]
	s_setprio 0
	s_setprio 1
	v_mfma_f32_16x16x32_bf16 v[52:55], v[194:197], v[210:213], v[52:55]
	v_mfma_f32_16x16x32_bf16 v[48:51], v[202:205], v[210:213], v[48:51]
	v_mfma_f32_16x16x32_bf16 v[36:39], v[194:197], v[218:221], v[36:39]
	v_mfma_f32_16x16x32_bf16 v[32:35], v[202:205], v[218:221], v[32:35]
	v_mfma_f32_16x16x32_bf16 v[20:23], v[194:197], v[226:229], v[20:23]
	v_mfma_f32_16x16x32_bf16 v[16:19], v[202:205], v[226:229], v[16:19]
	v_mfma_f32_16x16x32_bf16 v[4:7], v[194:197], v[234:237], v[4:7]
	v_mfma_f32_16x16x32_bf16 v[0:3], v[202:205], v[234:237], v[0:3]
	v_mfma_f32_16x16x32_bf16 v[52:55], v[198:201], v[214:217], v[52:55]
	v_mfma_f32_16x16x32_bf16 v[48:51], v[206:209], v[214:217], v[48:51]
	v_mfma_f32_16x16x32_bf16 v[36:39], v[198:201], v[222:225], v[36:39]
	v_mfma_f32_16x16x32_bf16 v[32:35], v[206:209], v[222:225], v[32:35]
	v_mfma_f32_16x16x32_bf16 v[20:23], v[198:201], v[230:233], v[20:23]
	v_mfma_f32_16x16x32_bf16 v[16:19], v[206:209], v[230:233], v[16:19]
	v_mfma_f32_16x16x32_bf16 v[4:7], v[198:201], v[238:241], v[4:7]
	v_mfma_f32_16x16x32_bf16 v[0:3], v[206:209], v[238:241], v[0:3]
	s_setprio 0
	s_barrier
	s_movk_i32 s18, 0x100
	s_andn2_b64 vcc, exec, s[0:1]
	s_mov_b64 s[42:43], -1
	s_mov_b64 s[0:1], 0
	s_cbranch_vccz .LBB0_1474
	s_and_b64 vcc, exec, s[8:9]
	s_cbranch_vccz .LBB0_1477
	s_barrier

; #define PG8_STAGE(bufoff, gbase, voff) do { _Pragma("unroll") for (int _i = 0; _i < 2; ++_i) \
;         __builtin_amdgcn_global_load_lds((const unsigned*)((const char*)(gbase) + (voff)[_i]), (PG8_LAS unsigned*)(lds + (bufoff) + ldsw + _i * 8192), 16, 0, 0); } while (0)
; #define PG8_LDA(dst, b, h) do { _Pragma("unroll") for (int m = 0; m < 4; ++m) _Pragma("unroll") for (int k = 0; k < 2; ++k) dst[m][k] = *(const PG8_LAS bf16x8*)(lds + PG8_SA(b, h) + aoff + m * 2048 + k * 1024); } while (0)
; #define PG8_LDB(dst, b, h) do { _Pragma("unroll") for (int n = 0; n < 2; ++n) _Pragma("unroll") for (int k = 0; k < 2; ++k) dst[n][k] = *(const PG8_LAS bf16x8*)(lds + PG8_SB(b, h) + boff + n * 2048 + k * 1024); } while (0)
; #define PG8_MMA(ai, bj, At, Bt) do { __builtin_amdgcn_s_setprio(1); _Pragma("unroll") for (int m = 0; m < 4; ++m) _Pragma("unroll") for (int n = 0; n < 2; ++n) _Pragma("unroll") for (int k = 0; k < 2; ++k) \
;         acc[ai][bj][m][n] = __builtin_amdgcn_mfma_f32_16x16x32_bf16(Bt[n][k], At[m][k], acc[ai][bj][m][n], 0, 0, 0); __builtin_amdgcn_s_setprio(0); } while (0)
; #define PG8_WAIT_V(n) asm volatile("s_waitcnt vmcnt(" #n ")" ::: "memory")
; #define PG8_WAIT_L(n) asm volatile("s_waitcnt lgkmcnt(" #n ")" ::: "memory")
; #define PG8_BAR __builtin_amdgcn_s_barrier()
; #define PG8_SCHED __builtin_amdgcn_sched_barrier(0)
; template <class Epi, class Sched, bool ALIGN_EPI = false, bool SP2 = false>
; __device__ __forceinline__ void gemm_phase(PG8_LAS unsigned char* lds, const Gemm g, const Sched& S, const Epi& E) {
;     ...
;             const bool last = (t == nt - 2);
;             const char* a1 = cA + (size_t)(t + 1) * kstep;
;             const char* a2 = last ? nA : cA + (size_t)(t + 2) * kstep; const char* b2 = last ? nB : cB + (size_t)(t + 2) * kstep;
;             const char* a3 = a2 + kstep; const char* b3 = b2 + kstep;
;             if (last && has_next) S.a_ready(nxt);
;             if constexpr (SP2) {
;             PG8_LDB(B0, 0, 0); PG8_LDB(B1, 0, 1); PG8_SCHED; PG8_LDA(At, 0, 0); PG8_STAGE(PG8_SA(1, 1), a1 + hstepA, voffA);
;             PG8_WAIT_V(8); PG8_WAIT_L(0); PG8_BAR; PG8_MMA(0, 0, At, B0); PG8_MMA(0, 1, At, B1); PG8_BAR; PG8_SCHED;
;             PG8_LDA(At, 0, 1); PG8_STAGE(PG8_SB(0, 0), b2, voffB); PG8_STAGE(PG8_SB(0, 1), b2 + hstepB, voffB); PG8_STAGE(PG8_SA(0, 0), a2, voffA);
.LBB0_1967:
	v_or_b32_e32 v158, 0x10000, v167
	v_add_u32_e32 v162, 0x10400, v167
	v_add_u32_e32 v169, 0x10800, v167
	v_add_u32_e32 v174, 0x10c00, v167
	ds_read_b128 v[158:161], v158
	ds_read_b128 v[162:165], v162
	ds_read_b128 v[170:173], v169
	ds_read_b128 v[174:177], v174
	v_or_b32_e32 v169, 0x14000, v167
	v_add_u32_e32 v178, 0x14400, v167
	ds_read_b128 v[194:197], v169
	ds_read_b128 v[198:201], v178
	v_add_u32_e32 v169, 0x14800, v167
	v_add_u32_e32 v178, 0x14c00, v167
	ds_read_b128 v[202:205], v169
	ds_read_b128 v[206:209], v178
	s_add_u32 s18, s96, 0xfffc0080
	s_addc_u32 s19, s97, -1
	s_cmp_eq_u32 s43, 12
	s_cselect_b32 s21, s9, s19
	s_cselect_b32 s20, s17, s18
	s_cselect_b32 s19, s7, s42
	s_cselect_b32 s18, s25, s27
	v_lshl_add_u64 v[178:179], s[96:97], 0, v[154:155]
	s_add_i32 m0, s35, 0xc000
	ds_read_b128 v[210:213], v166
	ds_read_b128 v[214:217], v166 offset:1024
	ds_read_b128 v[218:221], v166 offset:2048
	ds_read_b128 v[222:225], v166 offset:3072
	ds_read_b128 v[226:229], v166 offset:4096
	ds_read_b128 v[230:233], v166 offset:5120
	ds_read_b128 v[234:237], v166 offset:6144
	ds_read_b128 v[238:241], v166 offset:7168
	global_load_lds_dwordx4 v[178:179], off
	v_lshl_add_u64 v[178:179], s[96:97], 0, v[156:157]
	s_add_i32 m0, s35, 0xe000
	s_nop 0
	global_load_lds_dwordx4 v[178:179], off
	s_waitcnt vmcnt(8)
	s_waitcnt lgkmcnt(0)
	s_barrier
	s_setprio 1
	s_waitcnt lgkmcnt(0)
	v_mfma_f32_16x16x32_bf16 v[124:127], v[158:161], v[210:213], v[124:127]
	v_mfma_f32_16x16x32_bf16 v[120:123], v[170:173], v[210:213], v[120:123]
	v_mfma_f32_16x16x32_bf16 v[108:111], v[158:161], v[218:221], v[108:111]
	v_mfma_f32_16x16x32_bf16 v[104:107], v[170:173], v[218:221], v[104:107]
	v_mfma_f32_16x16x32_bf16 v[92:95], v[158:161], v[226:229], v[92:95]
	v_mfma_f32_16x16x32_bf16 v[88:91], v[170:173], v[226:229], v[88:91]
	v_mfma_f32_16x16x32_bf16 v[76:79], v[158:161], v[234:237], v[76:79]
	v_mfma_f32_16x16x32_bf16 v[72:75], v[170:173], v[234:237], v[72:75]
	v_mfma_f32_16x16x32_bf16 v[124:127], v[162:165], v[214:217], v[124:127]
	v_mfma_f32_16x16x32_bf16 v[120:123], v[174:177], v[214:217], v[120:123]
	v_mfma_f32_16x16x32_bf16 v[108:111], v[162:165], v[222:225], v[108:111]
	v_mfma_f32_16x16x32_bf16 v[104:107], v[174:177], v[222:225], v[104:107]
	v_mfma_f32_16x16x32_bf16 v[92:95], v[162:165], v[230:233], v[92:95]
	v_mfma_f32_16x16x32_bf16 v[88:91], v[174:177], v[230:233], v[88:91]
	v_mfma_f32_16x16x32_bf16 v[76:79], v[162:165], v[238:241], v[76:79]
	v_mfma_f32_16x16x32_bf16 v[72:75], v[174:177], v[238:241], v[72:75]
	s_setprio 0
	s_setprio 1
	v_mfma_f32_16x16x32_bf16 v[116:119], v[194:197], v[210:213], v[116:119]
	v_mfma_f32_16x16x32_bf16 v[112:115], v[202:205], v[210:213], v[112:115]
	v_mfma_f32_16x16x32_bf16 v[100:103], v[194:197], v[218:221], v[100:103]
	v_mfma_f32_16x16x32_bf16 v[96:99], v[202:205], v[218:221], v[96:99]
	v_mfma_f32_16x16x32_bf16 v[84:87], v[194:197], v[226:229], v[84:87]
	v_mfma_f32_16x16x32_bf16 v[80:83], v[202:205], v[226:229], v[80:83]
	v_mfma_f32_16x16x32_bf16 v[68:71], v[194:197], v[234:237], v[68:71]
	v_mfma_f32_16x16x32_bf16 v[64:67], v[202:205], v[234:237], v[64:67]
	v_mfma_f32_16x16x32_bf16 v[116:119], v[198:201], v[214:217], v[116:119]
	v_mfma_f32_16x16x32_bf16 v[112:115], v[206:209], v[214:217], v[112:115]
	v_mfma_f32_16x16x32_bf16 v[100:103], v[198:201], v[222:225], v[100:103]
	v_mfma_f32_16x16x32_bf16 v[96:99], v[206:209], v[222:225], v[96:99]
	v_mfma_f32_16x16x32_bf16 v[84:87], v[198:201], v[230:233], v[84:87]
	v_mfma_f32_16x16x32_bf16 v[80:83], v[206:209], v[230:233], v[80:83]
	v_mfma_f32_16x16x32_bf16 v[68:71], v[198:201], v[238:241], v[68:71]
	v_mfma_f32_16x16x32_bf16 v[64:67], v[206:209], v[238:241], v[64:67]
	s_setprio 0
	s_barrier
	s_mov_b32 m0, s36
	v_lshl_add_u64 v[178:179], s[18:19], 0, v[150:151]
	s_add_u32 s56, s18, 0x40000
	ds_read_b128 v[210:213], v166 offset:16384
	ds_read_b128 v[214:217], v166 offset:17408
	ds_read_b128 v[218:221], v166 offset:18432
	ds_read_b128 v[222:225], v166 offset:19456
	ds_read_b128 v[226:229], v166 offset:20480
	ds_read_b128 v[230:233], v166 offset:21504
	ds_read_b128 v[234:237], v166 offset:22528
	ds_read_b128 v[238:241], v166 offset:23552
	global_load_lds_dwordx4 v[178:179], off
	v_lshl_add_u64 v[188:189], s[18:19], 0, v[152:153]
	s_mov_b32 m0, s37
	s_addc_u32 s57, s19, 0
	global_load_lds_dwordx4 v[188:189], off
	v_lshl_add_u64 v[242:243], s[56:57], 0, v[150:151]
	s_mov_b32 m0, s59
	v_lshl_add_u64 v[244:245], s[20:21], 0, v[152:153]
	global_load_lds_dwordx4 v[242:243], off
	v_lshl_add_u64 v[242:243], s[56:57], 0, v[152:153]
	s_mov_b32 m0, s38
	s_nop 0
	global_load_lds_dwordx4 v[242:243], off
	v_lshl_add_u64 v[242:243], s[20:21], 0, v[150:151]
	s_mov_b32 m0, s35
	s_nop 0
	global_load_lds_dwordx4 v[242:243], off
	s_mov_b32 m0, s39
	s_nop 0
	global_load_lds_dwordx4 v[244:245], off
	s_waitcnt vmcnt(8)
	s_waitcnt lgkmcnt(0)
	s_barrier
; #define PG8_STAGE(bufoff, gbase, voff) do { _Pragma("unroll") for (int _i = 0; _i < 2; ++_i) \
;         __builtin_amdgcn_global_load_lds((const unsigned*)((const char*)(gbase) + (voff)[_i]), (PG8_LAS unsigned*)(lds + (bufoff) + ldsw + _i * 8192), 16, 0, 0); } while (0)
; #define PG8_LDA(dst, b, h) do { _Pragma("unroll") for (int m = 0; m < 4; ++m) _Pragma("unroll") for (int k = 0; k < 2; ++k) dst[m][k] = *(const PG8_LAS bf16x8*)(lds + PG8_SA(b, h) + aoff + m * 2048 + k * 1024); } while (0)
; #define PG8_LDB(dst, b, h) do { _Pragma("unroll") for (int n = 0; n < 2; ++n) _Pragma("unroll") for (int k = 0; k < 2; ++k) dst[n][k] = *(const PG8_LAS bf16x8*)(lds + PG8_SB(b, h) + boff + n * 2048 + k * 1024); } while (0)
; #define PG8_MMA(ai, bj, At, Bt) do { __builtin_amdgcn_s_setprio(1); _Pragma("unroll") for (int m = 0; m < 4; ++m) _Pragma("unroll") for (int n = 0; n < 2; ++n) _Pragma("unroll") for (int k = 0; k < 2; ++k) \
;         acc[ai][bj][m][n] = __builtin_amdgcn_mfma_f32_16x16x32_bf16(Bt[n][k], At[m][k], acc[ai][bj][m][n], 0, 0, 0); __builtin_amdgcn_s_setprio(0); } while (0)
; #define PG8_WAIT_V(n) asm volatile("s_waitcnt vmcnt(" #n ")" ::: "memory")
; #define PG8_WAIT_L(n) asm volatile("s_waitcnt lgkmcnt(" #n ")" ::: "memory")
; #define PG8_BAR __builtin_amdgcn_s_barrier()
; #define PG8_SCHED __builtin_amdgcn_sched_barrier(0)
; template <class Epi, class Sched, bool ALIGN_EPI = false, bool SP2 = false>
; __device__ __forceinline__ void gemm_phase(PG8_LAS unsigned char* lds, const Gemm g, const Sched& S, const Epi& E) {
;     ...
;             PG8_WAIT_V(8); PG8_WAIT_L(0); PG8_BAR; PG8_MMA(1, 0, At, B0); PG8_MMA(1, 1, At, B1); PG8_BAR; PG8_SCHED;
;             PG8_LDB(B0, 1, 0); PG8_LDB(B1, 1, 1); PG8_SCHED; PG8_LDA(At, 1, 0); PG8_STAGE(PG8_SA(0, 1), a2 + hstepA, voffA);
;             PG8_WAIT_V(8); PG8_WAIT_L(0); PG8_BAR; PG8_MMA(0, 0, At, B0); PG8_MMA(0, 1, At, B1); PG8_BAR; PG8_SCHED;
	s_setprio 1
	s_waitcnt lgkmcnt(0)
	v_mfma_f32_16x16x32_bf16 v[60:63], v[158:161], v[210:213], v[60:63]
	v_mfma_f32_16x16x32_bf16 v[56:59], v[170:173], v[210:213], v[56:59]
	v_mfma_f32_16x16x32_bf16 v[44:47], v[158:161], v[218:221], v[44:47]
	v_mfma_f32_16x16x32_bf16 v[40:43], v[170:173], v[218:221], v[40:43]
	v_mfma_f32_16x16x32_bf16 v[28:31], v[158:161], v[226:229], v[28:31]
	v_mfma_f32_16x16x32_bf16 v[24:27], v[170:173], v[226:229], v[24:27]
	v_mfma_f32_16x16x32_bf16 v[12:15], v[158:161], v[234:237], v[12:15]
	v_mfma_f32_16x16x32_bf16 v[8:11], v[170:173], v[234:237], v[8:11]
	v_mfma_f32_16x16x32_bf16 v[60:63], v[162:165], v[214:217], v[60:63]
	v_mfma_f32_16x16x32_bf16 v[56:59], v[174:177], v[214:217], v[56:59]
	v_mfma_f32_16x16x32_bf16 v[44:47], v[162:165], v[222:225], v[44:47]
	v_mfma_f32_16x16x32_bf16 v[40:43], v[174:177], v[222:225], v[40:43]
	v_mfma_f32_16x16x32_bf16 v[28:31], v[162:165], v[230:233], v[28:31]
	v_mfma_f32_16x16x32_bf16 v[24:27], v[174:177], v[230:233], v[24:27]
	v_mfma_f32_16x16x32_bf16 v[12:15], v[162:165], v[238:241], v[12:15]
	v_mfma_f32_16x16x32_bf16 v[8:11], v[174:177], v[238:241], v[8:11]
	s_setprio 0
	s_setprio 1
	v_mfma_f32_16x16x32_bf16 v[52:55], v[194:197], v[210:213], v[52:55]
	v_mfma_f32_16x16x32_bf16 v[48:51], v[202:205], v[210:213], v[48:51]
	v_mfma_f32_16x16x32_bf16 v[36:39], v[194:197], v[218:221], v[36:39]
	v_mfma_f32_16x16x32_bf16 v[32:35], v[202:205], v[218:221], v[32:35]
	v_mfma_f32_16x16x32_bf16 v[20:23], v[194:197], v[226:229], v[20:23]
	v_mfma_f32_16x16x32_bf16 v[16:19], v[202:205], v[226:229], v[16:19]
	v_mfma_f32_16x16x32_bf16 v[4:7], v[194:197], v[234:237], v[4:7]
	v_mfma_f32_16x16x32_bf16 v[0:3], v[202:205], v[234:237], v[0:3]
	v_mfma_f32_16x16x32_bf16 v[52:55], v[198:201], v[214:217], v[52:55]
	v_mfma_f32_16x16x32_bf16 v[48:51], v[206:209], v[214:217], v[48:51]
	v_mfma_f32_16x16x32_bf16 v[36:39], v[198:201], v[222:225], v[36:39]
	v_mfma_f32_16x16x32_bf16 v[32:35], v[206:209], v[222:225], v[32:35]
	v_mfma_f32_16x16x32_bf16 v[20:23], v[198:201], v[230:233], v[20:23]
	v_mfma_f32_16x16x32_bf16 v[16:19], v[206:209], v[230:233], v[16:19]
	v_mfma_f32_16x16x32_bf16 v[4:7], v[198:201], v[238:241], v[4:7]
	v_mfma_f32_16x16x32_bf16 v[0:3], v[206:209], v[238:241], v[0:3]
	s_setprio 0
	s_barrier
	v_or_b32_e32 v158, 0x18000, v167
	v_add_u32_e32 v162, 0x18400, v167
	v_add_u32_e32 v169, 0x18800, v167
	v_add_u32_e32 v174, 0x18c00, v167
	ds_read_b128 v[158:161], v158
	ds_read_b128 v[162:165], v162
	ds_read_b128 v[170:173], v169
	ds_read_b128 v[174:177], v174
	v_or_b32_e32 v169, 0x1c000, v167
	v_add_u32_e32 v198, 0x1c400, v167
	ds_read_b128 v[194:197], v169
	ds_read_b128 v[198:201], v198
	v_add_u32_e32 v169, 0x1c800, v167
	v_add_u32_e32 v206, 0x1cc00, v167
	ds_read_b128 v[202:205], v169
	ds_read_b128 v[206:209], v206
	s_add_u32 s20, s20, 0x40000
	s_addc_u32 s21, s21, 0
	s_mov_b32 m0, s40
	v_lshl_add_u64 v[246:247], s[20:21], 0, v[150:151]
	ds_read_b128 v[210:213], v166 offset:32768
	ds_read_b128 v[214:217], v166 offset:33792
	ds_read_b128 v[218:221], v166 offset:34816
	ds_read_b128 v[222:225], v166 offset:35840
	ds_read_b128 v[226:229], v166 offset:36864
	ds_read_b128 v[230:233], v166 offset:37888
	ds_read_b128 v[234:237], v166 offset:38912
	ds_read_b128 v[238:241], v166 offset:39936
	global_load_lds_dwordx4 v[246:247], off
	v_lshl_add_u64 v[246:247], s[20:21], 0, v[152:153]
	s_mov_b32 m0, s41
	s_nop 0
	global_load_lds_dwordx4 v[246:247], off
	s_waitcnt vmcnt(8)
	s_waitcnt lgkmcnt(0)
	s_barrier
	s_setprio 1
	s_waitcnt lgkmcnt(0)
	v_mfma_f32_16x16x32_bf16 v[124:127], v[158:161], v[210:213], v[124:127]
	v_mfma_f32_16x16x32_bf16 v[120:123], v[170:173], v[210:213], v[120:123]
	v_mfma_f32_16x16x32_bf16 v[108:111], v[158:161], v[218:221], v[108:111]
	v_mfma_f32_16x16x32_bf16 v[104:107], v[170:173], v[218:221], v[104:107]
	v_mfma_f32_16x16x32_bf16 v[92:95], v[158:161], v[226:229], v[92:95]
	v_mfma_f32_16x16x32_bf16 v[88:91], v[170:173], v[226:229], v[88:91]
	v_mfma_f32_16x16x32_bf16 v[76:79], v[158:161], v[234:237], v[76:79]
	v_mfma_f32_16x16x32_bf16 v[72:75], v[170:173], v[234:237], v[72:75]
	v_mfma_f32_16x16x32_bf16 v[124:127], v[162:165], v[214:217], v[124:127]
	v_mfma_f32_16x16x32_bf16 v[120:123], v[174:177], v[214:217], v[120:123]
	v_mfma_f32_16x16x32_bf16 v[108:111], v[162:165], v[222:225], v[108:111]
	v_mfma_f32_16x16x32_bf16 v[104:107], v[174:177], v[222:225], v[104:107]
	v_mfma_f32_16x16x32_bf16 v[92:95], v[162:165], v[230:233], v[92:95]
	v_mfma_f32_16x16x32_bf16 v[88:91], v[174:177], v[230:233], v[88:91]
	v_mfma_f32_16x16x32_bf16 v[76:79], v[162:165], v[238:241], v[76:79]
	v_mfma_f32_16x16x32_bf16 v[72:75], v[174:177], v[238:241], v[72:75]
	s_setprio 0
	s_setprio 1
	v_mfma_f32_16x16x32_bf16 v[116:119], v[194:197], v[210:213], v[116:119]
	v_mfma_f32_16x16x32_bf16 v[112:115], v[202:205], v[210:213], v[112:115]
	v_mfma_f32_16x16x32_bf16 v[100:103], v[194:197], v[218:221], v[100:103]
	v_mfma_f32_16x16x32_bf16 v[96:99], v[202:205], v[218:221], v[96:99]
	v_mfma_f32_16x16x32_bf16 v[84:87], v[194:197], v[226:229], v[84:87]
	v_mfma_f32_16x16x32_bf16 v[80:83], v[202:205], v[226:229], v[80:83]
	v_mfma_f32_16x16x32_bf16 v[68:71], v[194:197], v[234:237], v[68:71]
	v_mfma_f32_16x16x32_bf16 v[64:67], v[202:205], v[234:237], v[64:67]
	v_mfma_f32_16x16x32_bf16 v[116:119], v[198:201], v[214:217], v[116:119]
	v_mfma_f32_16x16x32_bf16 v[112:115], v[206:209], v[214:217], v[112:115]
	v_mfma_f32_16x16x32_bf16 v[100:103], v[198:201], v[222:225], v[100:103]
	v_mfma_f32_16x16x32_bf16 v[96:99], v[206:209], v[222:225], v[96:99]
	v_mfma_f32_16x16x32_bf16 v[84:87], v[198:201], v[230:233], v[84:87]
	v_mfma_f32_16x16x32_bf16 v[80:83], v[206:209], v[230:233], v[80:83]
	v_mfma_f32_16x16x32_bf16 v[68:71], v[198:201], v[238:241], v[68:71]
	v_mfma_f32_16x16x32_bf16 v[64:67], v[206:209], v[238:241], v[64:67]
	s_setprio 0
	s_barrier
; #define PG8_STAGE(bufoff, gbase, voff) do { _Pragma("unroll") for (int _i = 0; _i < 2; ++_i) \
;         __builtin_amdgcn_global_load_lds((const unsigned*)((const char*)(gbase) + (voff)[_i]), (PG8_LAS unsigned*)(lds + (bufoff) + ldsw + _i * 8192), 16, 0, 0); } while (0)
; #define PG8_LDA(dst, b, h) do { _Pragma("unroll") for (int m = 0; m < 4; ++m) _Pragma("unroll") for (int k = 0; k < 2; ++k) dst[m][k] = *(const PG8_LAS bf16x8*)(lds + PG8_SA(b, h) + aoff + m * 2048 + k * 1024); } while (0)
; #define PG8_MMA(ai, bj, At, Bt) do { __builtin_amdgcn_s_setprio(1); _Pragma("unroll") for (int m = 0; m < 4; ++m) _Pragma("unroll") for (int n = 0; n < 2; ++n) _Pragma("unroll") for (int k = 0; k < 2; ++k) \
;         acc[ai][bj][m][n] = __builtin_amdgcn_mfma_f32_16x16x32_bf16(Bt[n][k], At[m][k], acc[ai][bj][m][n], 0, 0, 0); __builtin_amdgcn_s_setprio(0); } while (0)
; #define PG8_WAIT_V(n) asm volatile("s_waitcnt vmcnt(" #n ")" ::: "memory")
; #define PG8_WAIT_L(n) asm volatile("s_waitcnt lgkmcnt(" #n ")" ::: "memory")
; #define PG8_BAR __builtin_amdgcn_s_barrier()
; #define PG8_SCHED __builtin_amdgcn_sched_barrier(0)
; template <class Epi, class Sched, bool ALIGN_EPI = false, bool SP2 = false>
; __device__ __forceinline__ void gemm_phase(PG8_LAS unsigned char* lds, const Gemm g, const Sched& S, const Epi& E) {
;     ...
;         for (int t = 0; t < nt; t += 2) {
;     ...
;             PG8_LDA(At, 1, 1); PG8_STAGE(PG8_SB(1, 0), b3, voffB); PG8_STAGE(PG8_SB(1, 1), b3 + hstepB, voffB); PG8_STAGE(PG8_SA(1, 0), a3, voffA);
;             PG8_WAIT_V(8); PG8_WAIT_L(0); PG8_BAR; PG8_MMA(1, 0, At, B0); PG8_MMA(1, 1, At, B1); PG8_BAR; PG8_SCHED;
	s_mov_b32 m0, s44
	v_lshl_add_u64 v[178:179], v[178:179], 0, s[54:55]
	s_add_u32 s18, s18, 0x40080
	ds_read_b128 v[210:213], v166 offset:49152
	ds_read_b128 v[214:217], v166 offset:50176
	ds_read_b128 v[218:221], v166 offset:51200
	ds_read_b128 v[222:225], v166 offset:52224
	ds_read_b128 v[226:229], v166 offset:53248
	ds_read_b128 v[230:233], v166 offset:54272
	ds_read_b128 v[234:237], v166 offset:55296
	ds_read_b128 v[238:241], v166 offset:56320
	global_load_lds_dwordx4 v[178:179], off
	v_lshl_add_u64 v[178:179], v[188:189], 0, s[54:55]
	s_mov_b32 m0, s45
	s_addc_u32 s19, s19, 0
	global_load_lds_dwordx4 v[178:179], off
	v_lshl_add_u64 v[178:179], s[18:19], 0, v[150:151]
	s_mov_b32 m0, s62
	s_nop 0
	global_load_lds_dwordx4 v[178:179], off
	v_lshl_add_u64 v[178:179], s[18:19], 0, v[152:153]
	s_mov_b32 m0, s63
	s_nop 0
	global_load_lds_dwordx4 v[178:179], off
	v_lshl_add_u64 v[178:179], v[242:243], 0, s[54:55]
	s_mov_b32 m0, s46
	s_nop 0
	global_load_lds_dwordx4 v[178:179], off
	v_lshl_add_u64 v[178:179], v[244:245], 0, s[54:55]
	s_mov_b32 m0, s47
	s_nop 0
	global_load_lds_dwordx4 v[178:179], off
	s_waitcnt vmcnt(8)
	s_waitcnt lgkmcnt(0)
	s_barrier
	s_setprio 1
	s_waitcnt lgkmcnt(0)
	v_mfma_f32_16x16x32_bf16 v[60:63], v[158:161], v[210:213], v[60:63]
	v_mfma_f32_16x16x32_bf16 v[56:59], v[170:173], v[210:213], v[56:59]
	v_mfma_f32_16x16x32_bf16 v[44:47], v[158:161], v[218:221], v[44:47]
	v_mfma_f32_16x16x32_bf16 v[40:43], v[170:173], v[218:221], v[40:43]
	v_mfma_f32_16x16x32_bf16 v[28:31], v[158:161], v[226:229], v[28:31]
	v_mfma_f32_16x16x32_bf16 v[24:27], v[170:173], v[226:229], v[24:27]
	v_mfma_f32_16x16x32_bf16 v[12:15], v[158:161], v[234:237], v[12:15]
	v_mfma_f32_16x16x32_bf16 v[8:11], v[170:173], v[234:237], v[8:11]
	v_mfma_f32_16x16x32_bf16 v[60:63], v[162:165], v[214:217], v[60:63]
	v_mfma_f32_16x16x32_bf16 v[56:59], v[174:177], v[214:217], v[56:59]
	v_mfma_f32_16x16x32_bf16 v[44:47], v[162:165], v[222:225], v[44:47]
	v_mfma_f32_16x16x32_bf16 v[40:43], v[174:177], v[222:225], v[40:43]
	v_mfma_f32_16x16x32_bf16 v[28:31], v[162:165], v[230:233], v[28:31]
	v_mfma_f32_16x16x32_bf16 v[24:27], v[174:177], v[230:233], v[24:27]
	v_mfma_f32_16x16x32_bf16 v[12:15], v[162:165], v[238:241], v[12:15]
	v_mfma_f32_16x16x32_bf16 v[8:11], v[174:177], v[238:241], v[8:11]
	s_setprio 0
	s_setprio 1
	v_mfma_f32_16x16x32_bf16 v[52:55], v[194:197], v[210:213], v[52:55]
	v_mfma_f32_16x16x32_bf16 v[48:51], v[202:205], v[210:213], v[48:51]
	v_mfma_f32_16x16x32_bf16 v[36:39], v[194:197], v[218:221], v[36:39]
	v_mfma_f32_16x16x32_bf16 v[32:35], v[202:205], v[218:221], v[32:35]
	v_mfma_f32_16x16x32_bf16 v[20:23], v[194:197], v[226:229], v[20:23]
	v_mfma_f32_16x16x32_bf16 v[16:19], v[202:205], v[226:229], v[16:19]
	v_mfma_f32_16x16x32_bf16 v[4:7], v[194:197], v[234:237], v[4:7]
	v_mfma_f32_16x16x32_bf16 v[0:3], v[202:205], v[234:237], v[0:3]
	v_mfma_f32_16x16x32_bf16 v[52:55], v[198:201], v[214:217], v[52:55]
	v_mfma_f32_16x16x32_bf16 v[48:51], v[206:209], v[214:217], v[48:51]
	v_mfma_f32_16x16x32_bf16 v[36:39], v[198:201], v[222:225], v[36:39]
	v_mfma_f32_16x16x32_bf16 v[32:35], v[206:209], v[222:225], v[32:35]
	v_mfma_f32_16x16x32_bf16 v[20:23], v[198:201], v[230:233], v[20:23]
	v_mfma_f32_16x16x32_bf16 v[16:19], v[206:209], v[230:233], v[16:19]
	v_mfma_f32_16x16x32_bf16 v[4:7], v[198:201], v[238:241], v[4:7]
	v_mfma_f32_16x16x32_bf16 v[0:3], v[206:209], v[238:241], v[0:3]
	s_setprio 0
	s_barrier
	s_add_i32 s43, s43, 2
	s_add_u32 s96, s96, 0x100
	s_addc_u32 s97, s97, 0
	s_add_u32 s27, s27, 0x100
	s_addc_u32 s42, s42, 0
	s_cmp_gt_u32 s43, 13
	s_cbranch_scc0 .LBB0_1967
	s_and_b64 vcc, exec, s[4:5]
	s_cbranch_vccz .LBB0_1970
	s_barrier

;     __device__ __forceinline__ bool next(int i, Unit& u) const { if (i != 0 || c >= n) return false; u.pm = pm; u.pn = c & 3; return true; }
; #define PG8_WAIT_V(n) asm volatile("s_waitcnt vmcnt(" #n ")" ::: "memory")
; template <class Epi, class Sched, bool ALIGN_EPI = false, bool SP2 = false>
; __device__ __forceinline__ void gemm_phase(PG8_LAS unsigned char* lds, const Gemm g, const Sched& S, const Epi& E) {
;     ...
;     if constexpr (SP2) {
;         PG8_STAGE(PG8_SB(0, 0), cB, voffB); PG8_STAGE(PG8_SB(0, 1), cB + hstepB, voffB); PG8_STAGE(PG8_SA(0, 0), cA, voffA); PG8_STAGE(PG8_SA(0, 1), cA + hstepA, voffA);
;         if (wr == 1) PG8_BAR;
;         PG8_WAIT_V(2); PG8_BAR;
;         PG8_STAGE(PG8_SB(1, 0), cB + kstep, voffB); PG8_STAGE(PG8_SA(1, 0), cA + kstep, voffA); PG8_STAGE(PG8_SB(1, 1), cB + hstepB + kstep, voffB);
;         PG8_WAIT_V(6); PG8_BAR;
;     } else {
;         PG8_STAGE(PG8_SB(0, 0), cB, voffB); PG8_STAGE(PG8_SA(0, 0), cA, voffA); PG8_STAGE(PG8_SB(0, 1), cB + hstepB, voffB); PG8_STAGE(PG8_SA(0, 1), cA + hstepA, voffA);
;         if (wr == 1) PG8_BAR;
;         PG8_WAIT_V(4); PG8_BAR;
;         PG8_STAGE(PG8_SB(1, 0), cB + kstep, voffB); PG8_STAGE(PG8_SA(1, 0), cA + kstep, voffA); PG8_STAGE(PG8_SB(1, 1), cB + hstepB + kstep, voffB);
;         PG8_WAIT_V(6); PG8_BAR;
;     }
;     for (;;) {
;         const bool has_next = S.next(ui + 1, nxt);
;         const char* nA = has_next ? (const char*)g.A + (size_t)nxt.pm * tstepA : cA; const char* nB = has_next ? (const char*)g.Bt + (size_t)nxt.pn * tstepB : cB;
;         for (int t = 0; t < nt; t += 2) {
;             const bool last = (t == nt - 2);
;             const char* a1 = cA + (size_t)(t + 1) * kstep;
;             const char* a2 = last ? nA : cA + (size_t)(t + 2) * kstep; const char* b2 = last ? nB : cB + (size_t)(t + 2) * kstep;
;             const char* a3 = a2 + kstep; const char* b3 = b2 + kstep;
;             if (last && has_next) S.a_ready(nxt);
;             if constexpr (SP2) {
;             PG8_LDB(B0, 0, 0); PG8_LDB(B1, 0, 1); PG8_SCHED; PG8_LDA(At, 0, 0); PG8_STAGE(PG8_SA(1, 1), a1 + hstepA, voffA);
;             PG8_WAIT_V(8); PG8_WAIT_L(0); PG8_BAR; PG8_MMA(0, 0, At, B0); PG8_MMA(0, 1, At, B1); PG8_BAR; PG8_SCHED;
;             PG8_LDA(At, 0, 1); PG8_STAGE(PG8_SB(0, 0), b2, voffB); PG8_STAGE(PG8_SB(0, 1), b2 + hstepB, voffB); PG8_STAGE(PG8_SA(0, 0), a2, voffA);
.LBB0_2025:
	s_lshl_b32 s2, s2, 5
	s_and_b32 s21, s2, 0x60
	s_lshl_b32 s4, s18, 13
	s_lshl_b32 s5, s21, 7
	s_add_i32 s39, s19, 0x18000
	s_add_i32 s40, s19, 0x1a000
	v_lshl_add_u64 v[64:65], v[0:1], 0, s[54:55]
	s_mov_b32 m0, s39
	s_add_u32 s2, s46, 0x4000080
	s_waitcnt vmcnt(2)
	s_barrier
	global_load_lds_dwordx4 v[64:65], off
	v_lshl_add_u64 v[66:67], v[2:3], 0, s[54:55]
	s_mov_b32 m0, s40
	s_addc_u32 s3, s47, 0
	s_add_i32 s41, s19, 0x8000
	s_add_i32 s42, s19, 0xa000
	global_load_lds_dwordx4 v[66:67], off
	v_lshl_add_u64 v[68:69], s[2:3], 0, v[16:17]
	s_mov_b32 m0, s41
	v_lshl_add_u64 v[70:71], s[2:3], 0, v[4:5]
	s_add_u32 s2, s0, 0x40080
	global_load_lds_dwordx4 v[68:69], off
	s_mov_b32 m0, s42
	s_addc_u32 s3, s1, 0
	s_add_i32 s43, s19, 0x1c000
	global_load_lds_dwordx4 v[70:71], off
	v_lshl_add_u64 v[72:73], s[2:3], 0, v[16:17]
	s_mov_b32 m0, s43
	s_add_i32 s44, s19, 0x1e000
	global_load_lds_dwordx4 v[72:73], off
	v_lshl_add_u64 v[74:75], s[2:3], 0, v[4:5]
	s_mov_b32 m0, s44
	s_add_u32 s8, s46, 0x4000100
	global_load_lds_dwordx4 v[74:75], off
	s_addc_u32 s9, s47, 0
	s_add_u32 s2, s46, 0x4000180
	s_addc_u32 s3, s47, 0
	v_bfe_u32 v76, v20, 4, 2
	s_add_u32 s56, s46, 0x4040080
	v_and_b32_e32 v77, 15, v20
	v_lshlrev_b32_e32 v21, 4, v76
	v_lshlrev_b32_e32 v20, 2, v20
	s_addc_u32 s57, s47, 0
	s_add_i32 s59, s19, 0xc000
	s_add_i32 s58, s19, 0xe000
	v_lshl_or_b32 v21, v77, 6, v21
	v_and_b32_e32 v20, 32, v20
	s_add_u32 s10, s0, 0x40100
	v_bitop3_b32 v122, v21, s5, v20 bitop3:0xde
	s_addc_u32 s11, s1, 0
	v_or_b32_e32 v178, 0x10000, v122
	s_add_u32 s6, s46, 0x4040100
	v_or_b32_e32 v202, 0x10400, v122
	v_or_b32_e32 v204, 0x10c00, v122
	v_or_b32_e32 v206, 0x14800, v122
	v_bitop3_b32 v131, v21, s4, v20 bitop3:0xde
	s_waitcnt vmcnt(6)
	s_barrier
	v_or_b32_e32 v179, 0x14000, v122
	s_addc_u32 s7, s47, 0
	v_or_b32_e32 v203, 0x10800, v122
	ds_read_b128 v[20:23], v202
	ds_read_b128 v[24:27], v203
	ds_read_b128 v[28:31], v178
	ds_read_b128 v[32:35], v179
	v_or_b32_e32 v205, 0x14400, v122
	ds_read_b128 v[36:39], v204
	ds_read_b128 v[40:43], v205
	v_or_b32_e32 v207, 0x14c00, v122
	ds_read_b128 v[44:47], v206
	ds_read_b128 v[48:51], v207
	s_add_u32 s4, s0, 0x40180
	s_addc_u32 s5, s1, 0
	s_add_u32 s0, s46, 0x4040180
	s_addc_u32 s1, s47, 0
	v_or_b32_e32 v188, 0x18000, v122
	v_or_b32_e32 v189, 0x1c000, v122
	s_cmpk_gt_u32 s45, 0xff
	s_mov_b32 m0, s59
	v_lshl_add_u64 v[98:99], s[56:57], 0, v[16:17]
	ds_read_b128 v[52:55], v131
	ds_read_b128 v[56:59], v131 offset:1024
	ds_read_b128 v[60:63], v131 offset:2048
	ds_read_b128 v[78:81], v131 offset:3072
	ds_read_b128 v[82:85], v131 offset:4096
	ds_read_b128 v[86:89], v131 offset:5120
	ds_read_b128 v[90:93], v131 offset:6144
	ds_read_b128 v[94:97], v131 offset:7168
	global_load_lds_dwordx4 v[98:99], off
	v_lshl_add_u64 v[98:99], s[56:57], 0, v[4:5]
	s_mov_b32 m0, s58
	s_nop 0
	global_load_lds_dwordx4 v[98:99], off
	s_waitcnt vmcnt(8)
	s_waitcnt lgkmcnt(0)
	s_barrier
	s_setprio 1
	s_waitcnt lgkmcnt(0)
	v_mfma_f32_16x16x32_bf16 v[98:101], v[28:31], v[52:55], 0
	v_mfma_f32_16x16x32_bf16 v[102:105], v[24:27], v[52:55], 0
	v_mfma_f32_16x16x32_bf16 v[106:109], v[28:31], v[60:63], 0
	v_mfma_f32_16x16x32_bf16 v[110:113], v[24:27], v[60:63], 0
	v_mfma_f32_16x16x32_bf16 v[114:117], v[28:31], v[82:85], 0
	v_mfma_f32_16x16x32_bf16 v[118:121], v[24:27], v[82:85], 0
	v_mfma_f32_16x16x32_bf16 v[28:31], v[28:31], v[90:93], 0
	v_mfma_f32_16x16x32_bf16 v[24:27], v[24:27], v[90:93], 0
	v_mfma_f32_16x16x32_bf16 v[98:101], v[20:23], v[56:59], v[98:101]
	v_mfma_f32_16x16x32_bf16 v[106:109], v[20:23], v[78:81], v[106:109]
	v_mfma_f32_16x16x32_bf16 v[114:117], v[20:23], v[86:89], v[114:117]
	v_mfma_f32_16x16x32_bf16 v[20:23], v[20:23], v[94:97], v[28:31]
	v_mfma_f32_16x16x32_bf16 v[24:27], v[36:39], v[94:97], v[24:27]
	v_mfma_f32_16x16x32_bf16 v[102:105], v[36:39], v[56:59], v[102:105]
	v_mfma_f32_16x16x32_bf16 v[110:113], v[36:39], v[78:81], v[110:113]
	v_mfma_f32_16x16x32_bf16 v[118:121], v[36:39], v[86:89], v[118:121]
	s_setprio 0
	s_setprio 1
	v_mfma_f32_16x16x32_bf16 v[28:31], v[32:35], v[52:55], 0
	v_mfma_f32_16x16x32_bf16 v[36:39], v[44:47], v[52:55], 0
	v_mfma_f32_16x16x32_bf16 v[28:31], v[40:43], v[56:59], v[28:31]
	v_mfma_f32_16x16x32_bf16 v[36:39], v[48:51], v[56:59], v[36:39]
	v_mfma_f32_16x16x32_bf16 v[52:55], v[32:35], v[60:63], 0
	v_mfma_f32_16x16x32_bf16 v[56:59], v[44:47], v[60:63], 0
	v_mfma_f32_16x16x32_bf16 v[60:63], v[32:35], v[82:85], 0
	v_mfma_f32_16x16x32_bf16 v[32:35], v[32:35], v[90:93], 0
	v_mfma_f32_16x16x32_bf16 v[52:55], v[40:43], v[78:81], v[52:55]
	v_mfma_f32_16x16x32_bf16 v[60:63], v[40:43], v[86:89], v[60:63]
	v_mfma_f32_16x16x32_bf16 v[32:35], v[40:43], v[94:97], v[32:35]
	v_mfma_f32_16x16x32_bf16 v[40:43], v[44:47], v[90:93], 0
	v_mfma_f32_16x16x32_bf16 v[56:59], v[48:51], v[78:81], v[56:59]
	v_mfma_f32_16x16x32_bf16 v[78:81], v[44:47], v[82:85], 0
	v_mfma_f32_16x16x32_bf16 v[40:43], v[48:51], v[94:97], v[40:43]
	v_mfma_f32_16x16x32_bf16 v[78:81], v[48:51], v[86:89], v[78:81]
	s_setprio 0
	s_barrier
	s_mov_b64 s[46:47], 0x100
	s_mov_b32 m0, s20
	v_lshl_add_u64 v[44:45], v[0:1], 0, s[46:47]
	global_load_lds_dwordx4 v[44:45], off
	v_lshl_add_u64 v[44:45], v[2:3], 0, s[46:47]
	s_mov_b32 m0, s25
	s_nop 0
	global_load_lds_dwordx4 v[44:45], off
	v_lshl_add_u64 v[44:45], s[10:11], 0, v[16:17]
	s_mov_b32 m0, s27
	s_nop 0
	global_load_lds_dwordx4 v[44:45], off
	v_lshl_add_u64 v[44:45], s[10:11], 0, v[4:5]
	s_mov_b32 m0, s36
	s_nop 0
	global_load_lds_dwordx4 v[44:45], off
	v_lshl_add_u64 v[44:45], s[8:9], 0, v[16:17]
	s_mov_b32 m0, s19
	s_nop 0
	global_load_lds_dwordx4 v[44:45], off
	v_lshl_add_u64 v[44:45], s[8:9], 0, v[4:5]
	s_mov_b32 m0, s38
	s_nop 0
	global_load_lds_dwordx4 v[44:45], off
	s_waitcnt vmcnt(8)
	s_waitcnt lgkmcnt(0)
	s_barrier
; #define PG8_STAGE(bufoff, gbase, voff) do { _Pragma("unroll") for (int _i = 0; _i < 2; ++_i) \
;         __builtin_amdgcn_global_load_lds((const unsigned*)((const char*)(gbase) + (voff)[_i]), (PG8_LAS unsigned*)(lds + (bufoff) + ldsw + _i * 8192), 16, 0, 0); } while (0)
; #define PG8_LDA(dst, b, h) do { _Pragma("unroll") for (int m = 0; m < 4; ++m) _Pragma("unroll") for (int k = 0; k < 2; ++k) dst[m][k] = *(const PG8_LAS bf16x8*)(lds + PG8_SA(b, h) + aoff + m * 2048 + k * 1024); } while (0)
; #define PG8_LDB(dst, b, h) do { _Pragma("unroll") for (int n = 0; n < 2; ++n) _Pragma("unroll") for (int k = 0; k < 2; ++k) dst[n][k] = *(const PG8_LAS bf16x8*)(lds + PG8_SB(b, h) + boff + n * 2048 + k * 1024); } while (0)
; #define PG8_MMA(ai, bj, At, Bt) do { __builtin_amdgcn_s_setprio(1); _Pragma("unroll") for (int m = 0; m < 4; ++m) _Pragma("unroll") for (int n = 0; n < 2; ++n) _Pragma("unroll") for (int k = 0; k < 2; ++k) \
;         acc[ai][bj][m][n] = __builtin_amdgcn_mfma_f32_16x16x32_bf16(Bt[n][k], At[m][k], acc[ai][bj][m][n], 0, 0, 0); __builtin_amdgcn_s_setprio(0); } while (0)
; #define PG8_WAIT_V(n) asm volatile("s_waitcnt vmcnt(" #n ")" ::: "memory")
; template <class Epi, class Sched, bool ALIGN_EPI = false, bool SP2 = false>
; __device__ __forceinline__ void gemm_phase(PG8_LAS unsigned char* lds, const Gemm g, const Sched& S, const Epi& E) {
;     ...
;             PG8_LDB(B0, 0, 0); PG8_LDB(B1, 0, 1); PG8_SCHED; PG8_LDA(At, 0, 0); PG8_STAGE(PG8_SA(1, 1), a1 + hstepA, voffA);
;             PG8_WAIT_V(8); PG8_WAIT_L(0); PG8_BAR; PG8_MMA(0, 0, At, B0); PG8_MMA(0, 1, At, B1); PG8_BAR; PG8_SCHED;
;             PG8_LDA(At, 0, 1); PG8_STAGE(PG8_SB(0, 0), b2, voffB); PG8_STAGE(PG8_SB(0, 1), b2 + hstepB, voffB); PG8_STAGE(PG8_SA(0, 0), a2, voffA);
;             PG8_WAIT_V(8); PG8_WAIT_L(0); PG8_BAR; PG8_MMA(1, 0, At, B0); PG8_MMA(1, 1, At, B1); PG8_BAR; PG8_SCHED;
;             PG8_LDB(B0, 1, 0); PG8_LDB(B1, 1, 1); PG8_SCHED; PG8_LDA(At, 1, 0); PG8_STAGE(PG8_SA(0, 1), a2 + hstepA, voffA);
;             PG8_WAIT_V(8); PG8_WAIT_L(0); PG8_BAR; PG8_MMA(0, 0, At, B0); PG8_MMA(0, 1, At, B1); PG8_BAR; PG8_SCHED;
;             PG8_LDA(At, 1, 1); PG8_STAGE(PG8_SB(1, 0), b3, voffB); PG8_STAGE(PG8_SB(1, 1), b3 + hstepB, voffB); PG8_STAGE(PG8_SA(1, 0), a3, voffA);
;             PG8_WAIT_V(8); PG8_WAIT_L(0); PG8_BAR; PG8_MMA(1, 0, At, B0); PG8_MMA(1, 1, At, B1); PG8_BAR; PG8_SCHED;
	s_setprio 1
	s_setprio 0
	s_setprio 1
	s_setprio 0
	s_barrier
	v_or_b32_e32 v208, 0x18400, v122
	v_or_b32_e32 v210, 0x18c00, v122
	v_or_b32_e32 v212, 0x1c800, v122
	v_or_b32_e32 v209, 0x18800, v122
	ds_read_b128 v[44:47], v208
	ds_read_b128 v[48:51], v209
	ds_read_b128 v[82:85], v188
	ds_read_b128 v[86:89], v189
	v_or_b32_e32 v211, 0x1c400, v122
	ds_read_b128 v[90:93], v210
	ds_read_b128 v[94:97], v211
	v_or_b32_e32 v213, 0x1cc00, v122
	ds_read_b128 v[122:125], v212
	ds_read_b128 v[150:153], v213
	s_mov_b32 m0, s35
	v_lshl_add_u64 v[126:127], s[6:7], 0, v[16:17]
	ds_read_b128 v[154:157], v131 offset:32768
	ds_read_b128 v[158:161], v131 offset:33792
	ds_read_b128 v[162:165], v131 offset:34816
	ds_read_b128 v[166:169], v131 offset:35840
	ds_read_b128 v[170:173], v131 offset:36864
	ds_read_b128 v[174:177], v131 offset:37888
	ds_read_b128 v[194:197], v131 offset:38912
	ds_read_b128 v[198:201], v131 offset:39936
	global_load_lds_dwordx4 v[126:127], off
	v_lshl_add_u64 v[126:127], s[6:7], 0, v[4:5]
	s_mov_b32 m0, s37
	s_nop 0
	global_load_lds_dwordx4 v[126:127], off
	s_waitcnt vmcnt(8)
	s_waitcnt lgkmcnt(0)
	s_barrier
	s_setprio 1
	s_waitcnt lgkmcnt(0)
	v_mfma_f32_16x16x32_bf16 v[20:23], v[82:85], v[194:197], v[20:23]
	v_mfma_f32_16x16x32_bf16 v[24:27], v[48:51], v[194:197], v[24:27]
	v_mfma_f32_16x16x32_bf16 v[98:101], v[82:85], v[154:157], v[98:101]
	v_mfma_f32_16x16x32_bf16 v[102:105], v[48:51], v[154:157], v[102:105]
	v_mfma_f32_16x16x32_bf16 v[106:109], v[82:85], v[162:165], v[106:109]
	v_mfma_f32_16x16x32_bf16 v[110:113], v[48:51], v[162:165], v[110:113]
	v_mfma_f32_16x16x32_bf16 v[114:117], v[82:85], v[170:173], v[114:117]
	v_mfma_f32_16x16x32_bf16 v[118:121], v[48:51], v[170:173], v[118:121]
	v_mfma_f32_16x16x32_bf16 v[20:23], v[44:47], v[198:201], v[20:23]
	v_mfma_f32_16x16x32_bf16 v[24:27], v[90:93], v[198:201], v[24:27]
	v_mfma_f32_16x16x32_bf16 v[98:101], v[44:47], v[158:161], v[98:101]
	v_mfma_f32_16x16x32_bf16 v[102:105], v[90:93], v[158:161], v[102:105]
	v_mfma_f32_16x16x32_bf16 v[106:109], v[44:47], v[166:169], v[106:109]
	v_mfma_f32_16x16x32_bf16 v[110:113], v[90:93], v[166:169], v[110:113]
	v_mfma_f32_16x16x32_bf16 v[114:117], v[44:47], v[174:177], v[114:117]
	v_mfma_f32_16x16x32_bf16 v[118:121], v[90:93], v[174:177], v[118:121]
	s_setprio 0
	s_setprio 1
	v_mfma_f32_16x16x32_bf16 v[28:31], v[86:89], v[154:157], v[28:31]
	v_mfma_f32_16x16x32_bf16 v[36:39], v[122:125], v[154:157], v[36:39]
	v_mfma_f32_16x16x32_bf16 v[44:47], v[86:89], v[162:165], v[52:55]
	v_mfma_f32_16x16x32_bf16 v[48:51], v[122:125], v[162:165], v[56:59]
	v_mfma_f32_16x16x32_bf16 v[52:55], v[86:89], v[170:173], v[60:63]
	v_mfma_f32_16x16x32_bf16 v[56:59], v[122:125], v[170:173], v[78:81]
	v_mfma_f32_16x16x32_bf16 v[32:35], v[86:89], v[194:197], v[32:35]
	v_mfma_f32_16x16x32_bf16 v[40:43], v[122:125], v[194:197], v[40:43]
	v_mfma_f32_16x16x32_bf16 v[28:31], v[94:97], v[158:161], v[28:31]
	v_mfma_f32_16x16x32_bf16 v[36:39], v[150:153], v[158:161], v[36:39]
	v_mfma_f32_16x16x32_bf16 v[44:47], v[94:97], v[166:169], v[44:47]
	v_mfma_f32_16x16x32_bf16 v[48:51], v[150:153], v[166:169], v[48:51]
	v_mfma_f32_16x16x32_bf16 v[52:55], v[94:97], v[174:177], v[52:55]
	v_mfma_f32_16x16x32_bf16 v[56:59], v[150:153], v[174:177], v[56:59]
	v_mfma_f32_16x16x32_bf16 v[32:35], v[94:97], v[198:201], v[32:35]
	v_mfma_f32_16x16x32_bf16 v[40:43], v[150:153], v[198:201], v[40:43]
	s_setprio 0
	s_barrier
	s_mov_b64 s[6:7], 0x180
	s_mov_b32 m0, s39
	v_lshl_add_u64 v[60:61], v[0:1], 0, s[6:7]
	global_load_lds_dwordx4 v[60:61], off
	v_lshl_add_u64 v[60:61], v[2:3], 0, s[6:7]
	s_mov_b32 m0, s40
	s_nop 0
	global_load_lds_dwordx4 v[60:61], off
	v_lshl_add_u64 v[60:61], s[4:5], 0, v[16:17]
	s_mov_b32 m0, s43
	s_nop 0
	global_load_lds_dwordx4 v[60:61], off
	v_lshl_add_u64 v[60:61], s[4:5], 0, v[4:5]
	s_mov_b32 m0, s44
	s_nop 0
	global_load_lds_dwordx4 v[60:61], off
	v_lshl_add_u64 v[60:61], s[2:3], 0, v[16:17]
	s_mov_b32 m0, s41
	s_nop 0
	global_load_lds_dwordx4 v[60:61], off
	v_lshl_add_u64 v[60:61], s[2:3], 0, v[4:5]
	s_mov_b32 m0, s42
	s_nop 0
	global_load_lds_dwordx4 v[60:61], off
	s_waitcnt vmcnt(8)
	s_waitcnt lgkmcnt(0)
	s_barrier
	s_setprio 1
	s_setprio 0
	s_setprio 1
	s_setprio 0
	s_barrier
	ds_read_b128 v[60:63], v202
	ds_read_b128 v[78:81], v203
	ds_read_b128 v[82:85], v178
	ds_read_b128 v[86:89], v179
	ds_read_b128 v[90:93], v204
	ds_read_b128 v[94:97], v205
	ds_read_b128 v[122:125], v206
	ds_read_b128 v[150:153], v207
	s_mov_b32 m0, s59
	v_lshl_add_u64 v[16:17], s[0:1], 0, v[16:17]
	ds_read_b128 v[154:157], v131
	ds_read_b128 v[158:161], v131 offset:1024
	ds_read_b128 v[162:165], v131 offset:2048
	ds_read_b128 v[166:169], v131 offset:3072
	ds_read_b128 v[170:173], v131 offset:4096
	ds_read_b128 v[174:177], v131 offset:5120
	ds_read_b128 v[194:197], v131 offset:6144
	ds_read_b128 v[198:201], v131 offset:7168
	global_load_lds_dwordx4 v[16:17], off
	v_lshl_add_u64 v[4:5], s[0:1], 0, v[4:5]
	s_mov_b32 m0, s58
	s_nop 0
	global_load_lds_dwordx4 v[4:5], off
	s_waitcnt vmcnt(8)
	s_waitcnt lgkmcnt(0)
	s_barrier
; #define PG8_STAGE(bufoff, gbase, voff) do { _Pragma("unroll") for (int _i = 0; _i < 2; ++_i) \
;         __builtin_amdgcn_global_load_lds((const unsigned*)((const char*)(gbase) + (voff)[_i]), (PG8_LAS unsigned*)(lds + (bufoff) + ldsw + _i * 8192), 16, 0, 0); } while (0)
; #define PG8_LDA(dst, b, h) do { _Pragma("unroll") for (int m = 0; m < 4; ++m) _Pragma("unroll") for (int k = 0; k < 2; ++k) dst[m][k] = *(const PG8_LAS bf16x8*)(lds + PG8_SA(b, h) + aoff + m * 2048 + k * 1024); } while (0)
; #define PG8_LDB(dst, b, h) do { _Pragma("unroll") for (int n = 0; n < 2; ++n) _Pragma("unroll") for (int k = 0; k < 2; ++k) dst[n][k] = *(const PG8_LAS bf16x8*)(lds + PG8_SB(b, h) + boff + n * 2048 + k * 1024); } while (0)
; #define PG8_MMA(ai, bj, At, Bt) do { __builtin_amdgcn_s_setprio(1); _Pragma("unroll") for (int m = 0; m < 4; ++m) _Pragma("unroll") for (int n = 0; n < 2; ++n) _Pragma("unroll") for (int k = 0; k < 2; ++k) \
;         acc[ai][bj][m][n] = __builtin_amdgcn_mfma_f32_16x16x32_bf16(Bt[n][k], At[m][k], acc[ai][bj][m][n], 0, 0, 0); __builtin_amdgcn_s_setprio(0); } while (0)
; #define PG8_WAIT_V(n) asm volatile("s_waitcnt vmcnt(" #n ")" ::: "memory")
; template <class Epi, class Sched, bool ALIGN_EPI = false, bool SP2 = false>
; __device__ __forceinline__ void gemm_phase(PG8_LAS unsigned char* lds, const Gemm g, const Sched& S, const Epi& E) {
;     ...
;             PG8_LDB(B0, 0, 0); PG8_LDB(B1, 0, 1); PG8_SCHED; PG8_LDA(At, 0, 0); PG8_STAGE(PG8_SA(1, 1), a1 + hstepA, voffA);
;             PG8_WAIT_V(8); PG8_WAIT_L(0); PG8_BAR; PG8_MMA(0, 0, At, B0); PG8_MMA(0, 1, At, B1); PG8_BAR; PG8_SCHED;
;             PG8_LDA(At, 0, 1); PG8_STAGE(PG8_SB(0, 0), b2, voffB); PG8_STAGE(PG8_SB(0, 1), b2 + hstepB, voffB); PG8_STAGE(PG8_SA(0, 0), a2, voffA);
;             PG8_WAIT_V(8); PG8_WAIT_L(0); PG8_BAR; PG8_MMA(1, 0, At, B0); PG8_MMA(1, 1, At, B1); PG8_BAR; PG8_SCHED;
;             PG8_LDB(B0, 1, 0); PG8_LDB(B1, 1, 1); PG8_SCHED; PG8_LDA(At, 1, 0); PG8_STAGE(PG8_SA(0, 1), a2 + hstepA, voffA);
;             PG8_WAIT_V(8); PG8_WAIT_L(0); PG8_BAR; PG8_MMA(0, 0, At, B0); PG8_MMA(0, 1, At, B1); PG8_BAR; PG8_SCHED;
;             PG8_LDA(At, 1, 1); PG8_STAGE(PG8_SB(1, 0), b3, voffB); PG8_STAGE(PG8_SB(1, 1), b3 + hstepB, voffB); PG8_STAGE(PG8_SA(1, 0), a3, voffA);
;             PG8_WAIT_V(8); PG8_WAIT_L(0); PG8_BAR; PG8_MMA(1, 0, At, B0); PG8_MMA(1, 1, At, B1); PG8_BAR; PG8_SCHED;
	s_setprio 1
	s_waitcnt lgkmcnt(0)
	v_mfma_f32_16x16x32_bf16 v[98:101], v[82:85], v[154:157], v[98:101]
	v_mfma_f32_16x16x32_bf16 v[106:109], v[82:85], v[162:165], v[106:109]
	v_mfma_f32_16x16x32_bf16 v[114:117], v[82:85], v[170:173], v[114:117]
	v_mfma_f32_16x16x32_bf16 v[20:23], v[82:85], v[194:197], v[20:23]
	v_mfma_f32_16x16x32_bf16 v[98:101], v[60:63], v[158:161], v[98:101]
	v_mfma_f32_16x16x32_bf16 v[102:105], v[78:81], v[154:157], v[102:105]
	v_mfma_f32_16x16x32_bf16 v[106:109], v[60:63], v[166:169], v[106:109]
	v_mfma_f32_16x16x32_bf16 v[110:113], v[78:81], v[162:165], v[110:113]
	v_mfma_f32_16x16x32_bf16 v[114:117], v[60:63], v[174:177], v[114:117]
	v_mfma_f32_16x16x32_bf16 v[118:121], v[78:81], v[170:173], v[118:121]
	v_mfma_f32_16x16x32_bf16 v[60:63], v[60:63], v[198:201], v[20:23]
	v_mfma_f32_16x16x32_bf16 v[20:23], v[78:81], v[194:197], v[24:27]
	v_mfma_f32_16x16x32_bf16 v[102:105], v[90:93], v[158:161], v[102:105]
	v_mfma_f32_16x16x32_bf16 v[110:113], v[90:93], v[166:169], v[110:113]
	v_mfma_f32_16x16x32_bf16 v[118:121], v[90:93], v[174:177], v[118:121]
	v_mfma_f32_16x16x32_bf16 v[78:81], v[90:93], v[198:201], v[20:23]
	s_setprio 0
	s_setprio 1
	v_mfma_f32_16x16x32_bf16 v[20:23], v[86:89], v[154:157], v[28:31]
	v_mfma_f32_16x16x32_bf16 v[82:85], v[94:97], v[158:161], v[20:23]
	v_mfma_f32_16x16x32_bf16 v[20:23], v[122:125], v[154:157], v[36:39]
	v_mfma_f32_16x16x32_bf16 v[36:39], v[150:153], v[158:161], v[20:23]
	v_mfma_f32_16x16x32_bf16 v[20:23], v[86:89], v[162:165], v[44:47]
	v_mfma_f32_16x16x32_bf16 v[44:47], v[94:97], v[166:169], v[20:23]
	v_mfma_f32_16x16x32_bf16 v[20:23], v[122:125], v[162:165], v[48:51]
	v_mfma_f32_16x16x32_bf16 v[48:51], v[150:153], v[166:169], v[20:23]
	v_mfma_f32_16x16x32_bf16 v[20:23], v[86:89], v[170:173], v[52:55]
	v_mfma_f32_16x16x32_bf16 v[90:93], v[94:97], v[174:177], v[20:23]
	v_mfma_f32_16x16x32_bf16 v[20:23], v[122:125], v[170:173], v[56:59]
	v_mfma_f32_16x16x32_bf16 v[154:157], v[150:153], v[174:177], v[20:23]
	v_mfma_f32_16x16x32_bf16 v[20:23], v[86:89], v[194:197], v[32:35]
	v_mfma_f32_16x16x32_bf16 v[32:35], v[94:97], v[198:201], v[20:23]
	v_mfma_f32_16x16x32_bf16 v[20:23], v[122:125], v[194:197], v[40:43]
	v_mfma_f32_16x16x32_bf16 v[40:43], v[150:153], v[198:201], v[20:23]
	s_setprio 0
	s_barrier
	s_mov_b32 m0, s20
	s_nop 0
	global_load_lds_dwordx4 v[0:1], off
	s_mov_b32 m0, s25
	s_nop 0
	global_load_lds_dwordx4 v[2:3], off
	s_mov_b32 m0, s27
	s_nop 0
	global_load_lds_dwordx4 v[6:7], off
	s_mov_b32 m0, s36
	s_nop 0
	global_load_lds_dwordx4 v[10:11], off
	s_mov_b32 m0, s19
	s_nop 0
	global_load_lds_dwordx4 v[14:15], off
	s_mov_b32 m0, s38
	s_nop 0
	global_load_lds_dwordx4 v[18:19], off
	s_waitcnt vmcnt(8)
	s_waitcnt lgkmcnt(0)
	s_barrier
	s_setprio 1
	s_setprio 0
	s_setprio 1
	s_setprio 0
	s_barrier
	ds_read_b128 v[0:3], v208
	ds_read_b128 v[52:55], v209
	ds_read_b128 v[56:59], v188
	ds_read_b128 v[86:89], v189
	ds_read_b128 v[94:97], v210
	ds_read_b128 v[122:125], v211
	ds_read_b128 v[150:153], v212
	ds_read_b128 v[158:161], v213
	s_mov_b32 m0, s35
	ds_read_b128 v[162:165], v131 offset:32768
	ds_read_b128 v[166:169], v131 offset:33792
	ds_read_b128 v[170:173], v131 offset:34816
	ds_read_b128 v[174:177], v131 offset:35840
	ds_read_b128 v[194:197], v131 offset:36864
	ds_read_b128 v[198:201], v131 offset:37888
	ds_read_b128 v[202:205], v131 offset:38912
	ds_read_b128 v[206:209], v131 offset:39936
	global_load_lds_dwordx4 v[8:9], off
	s_mov_b32 m0, s37
	s_nop 0
	global_load_lds_dwordx4 v[12:13], off
	s_waitcnt vmcnt(8)
	s_waitcnt lgkmcnt(0)
	s_barrier
	s_setprio 1
	s_waitcnt lgkmcnt(0)
	v_mfma_f32_16x16x32_bf16 v[4:7], v[56:59], v[162:165], v[98:101]
	v_mfma_f32_16x16x32_bf16 v[20:23], v[0:3], v[166:169], v[4:7]
	v_mfma_f32_16x16x32_bf16 v[4:7], v[52:55], v[162:165], v[102:105]
	v_mfma_f32_16x16x32_bf16 v[28:31], v[94:97], v[166:169], v[4:7]
	v_mfma_f32_16x16x32_bf16 v[4:7], v[56:59], v[170:173], v[106:109]
	v_mfma_f32_16x16x32_bf16 v[12:15], v[0:3], v[174:177], v[4:7]
	v_mfma_f32_16x16x32_bf16 v[4:7], v[52:55], v[170:173], v[110:113]
	v_mfma_f32_16x16x32_bf16 v[8:11], v[52:55], v[194:197], v[118:121]
	v_mfma_f32_16x16x32_bf16 v[24:27], v[94:97], v[174:177], v[4:7]
	v_mfma_f32_16x16x32_bf16 v[4:7], v[56:59], v[194:197], v[114:117]
	v_mfma_f32_16x16x32_bf16 v[16:19], v[94:97], v[198:201], v[8:11]
	v_mfma_f32_16x16x32_bf16 v[8:11], v[56:59], v[202:205], v[60:63]
	v_mfma_f32_16x16x32_bf16 v[4:7], v[0:3], v[198:201], v[4:7]
	v_mfma_f32_16x16x32_bf16 v[0:3], v[0:3], v[206:209], v[8:11]
	v_mfma_f32_16x16x32_bf16 v[8:11], v[52:55], v[202:205], v[78:81]
	v_mfma_f32_16x16x32_bf16 v[8:11], v[94:97], v[206:209], v[8:11]
	s_setprio 0
	s_setprio 1
	v_mfma_f32_16x16x32_bf16 v[36:39], v[150:153], v[162:165], v[36:39]
	v_mfma_f32_16x16x32_bf16 v[60:63], v[158:161], v[166:169], v[36:39]
	v_mfma_f32_16x16x32_bf16 v[36:39], v[86:89], v[170:173], v[44:47]
	v_mfma_f32_16x16x32_bf16 v[44:47], v[122:125], v[174:177], v[36:39]
	v_mfma_f32_16x16x32_bf16 v[36:39], v[150:153], v[170:173], v[48:51]
	v_mfma_f32_16x16x32_bf16 v[52:55], v[86:89], v[162:165], v[82:85]
	v_mfma_f32_16x16x32_bf16 v[56:59], v[158:161], v[174:177], v[36:39]
	v_mfma_f32_16x16x32_bf16 v[36:39], v[86:89], v[194:197], v[90:93]
	v_mfma_f32_16x16x32_bf16 v[48:51], v[150:153], v[194:197], v[154:157]
	v_mfma_f32_16x16x32_bf16 v[32:35], v[86:89], v[202:205], v[32:35]
	v_mfma_f32_16x16x32_bf16 v[40:43], v[150:153], v[202:205], v[40:43]
	v_mfma_f32_16x16x32_bf16 v[52:55], v[122:125], v[166:169], v[52:55]
	v_mfma_f32_16x16x32_bf16 v[36:39], v[122:125], v[198:201], v[36:39]
	v_mfma_f32_16x16x32_bf16 v[48:51], v[158:161], v[198:201], v[48:51]
	v_mfma_f32_16x16x32_bf16 v[32:35], v[122:125], v[206:209], v[32:35]
	v_mfma_f32_16x16x32_bf16 v[40:43], v[158:161], v[206:209], v[40:43]
	s_setprio 0
	s_barrier
	s_mov_b32 m0, s39
	s_nop 0
	global_load_lds_dwordx4 v[64:65], off
	s_mov_b32 m0, s40
	s_nop 0
	global_load_lds_dwordx4 v[66:67], off
	s_mov_b32 m0, s43
	s_nop 0
	global_load_lds_dwordx4 v[72:73], off
	s_mov_b32 m0, s44
	s_nop 0
	global_load_lds_dwordx4 v[74:75], off
	s_mov_b32 m0, s41
	s_nop 0
	global_load_lds_dwordx4 v[68:69], off
	s_mov_b32 m0, s42
	s_nop 0
	global_load_lds_dwordx4 v[70:71], off
	s_waitcnt vmcnt(8)
	s_waitcnt lgkmcnt(0)
	s_barrier
	s_setprio 1
	s_setprio 0
	s_setprio 1
	s_setprio 0
	s_barrier
	s_cbranch_scc1 .LBB0_2027
	s_barrier

; #define PG8_STAGE(bufoff, gbase, voff) do { _Pragma("unroll") for (int _i = 0; _i < 2; ++_i) \
;         __builtin_amdgcn_global_load_lds((const unsigned*)((const char*)(gbase) + (voff)[_i]), (PG8_LAS unsigned*)(lds + (bufoff) + ldsw + _i * 8192), 16, 0, 0); } while (0)
; #define PG8_LDA(dst, b, h) do { _Pragma("unroll") for (int m = 0; m < 4; ++m) _Pragma("unroll") for (int k = 0; k < 2; ++k) dst[m][k] = *(const PG8_LAS bf16x8*)(lds + PG8_SA(b, h) + aoff + m * 2048 + k * 1024); } while (0)
; #define PG8_LDB(dst, b, h) do { _Pragma("unroll") for (int n = 0; n < 2; ++n) _Pragma("unroll") for (int k = 0; k < 2; ++k) dst[n][k] = *(const PG8_LAS bf16x8*)(lds + PG8_SB(b, h) + boff + n * 2048 + k * 1024); } while (0)
; #define PG8_MMA(ai, bj, At, Bt) do { __builtin_amdgcn_s_setprio(1); _Pragma("unroll") for (int m = 0; m < 4; ++m) _Pragma("unroll") for (int n = 0; n < 2; ++n) _Pragma("unroll") for (int k = 0; k < 2; ++k) \
;         acc[ai][bj][m][n] = __builtin_amdgcn_mfma_f32_16x16x32_bf16(Bt[n][k], At[m][k], acc[ai][bj][m][n], 0, 0, 0); __builtin_amdgcn_s_setprio(0); } while (0)
; #define PG8_WAIT_V(n) asm volatile("s_waitcnt vmcnt(" #n ")" ::: "memory")
; #define PG8_WAIT_L(n) asm volatile("s_waitcnt lgkmcnt(" #n ")" ::: "memory")
; #define PG8_BAR __builtin_amdgcn_s_barrier()
; #define PG8_SCHED __builtin_amdgcn_sched_barrier(0)
; template <class Epi, class Sched, bool ALIGN_EPI = false, bool SP2 = false>
; __device__ __forceinline__ void gemm_phase(PG8_LAS unsigned char* lds, const Gemm g, const Sched& S, const Epi& E) {
;     ...
;             PG8_LDB(B0, 0, 0); PG8_LDB(B1, 0, 1); PG8_SCHED; PG8_LDA(At, 0, 0); PG8_STAGE(PG8_SA(1, 1), a1 + hstepA, voffA);
;             PG8_WAIT_V(8); PG8_WAIT_L(0); PG8_BAR; PG8_MMA(0, 0, At, B0); PG8_MMA(0, 1, At, B1); PG8_BAR; PG8_SCHED;
;             PG8_LDA(At, 0, 1); PG8_STAGE(PG8_SB(0, 0), b2, voffB); PG8_STAGE(PG8_SB(0, 1), b2 + hstepB, voffB); PG8_STAGE(PG8_SA(0, 0), a2, voffA);
.LBB0_2177:
	v_or_b32_e32 v162, 0x10000, v171
	v_add_u32_e32 v166, 0x10400, v171
	v_add_u32_e32 v173, 0x10800, v171
	ds_read_b128 v[162:165], v162
	ds_read_b128 v[166:169], v166
	v_add_u32_e32 v178, 0x10c00, v171
	ds_read_b128 v[174:177], v173
	ds_read_b128 v[194:197], v178
	v_or_b32_e32 v173, 0x14000, v171
	v_add_u32_e32 v178, 0x14400, v171
	ds_read_b128 v[198:201], v173
	ds_read_b128 v[202:205], v178
	v_add_u32_e32 v173, 0x14800, v171
	v_add_u32_e32 v178, 0x14c00, v171
	ds_read_b128 v[206:209], v173
	ds_read_b128 v[210:213], v178
	s_add_u32 s18, vcc_lo, 0xfffc0080
	s_addc_u32 s19, vcc_hi, -1
	s_cmp_eq_u32 s75, 12
	s_cselect_b32 s21, s1, s19
	s_cselect_b32 s20, s5, s18
	s_cselect_b32 s19, s25, s43
	s_cselect_b32 s18, s27, s42
	v_lshl_add_u64 v[178:179], vcc, 0, v[158:159]
	s_add_i32 m0, s38, 0xc000
	ds_read_b128 v[214:217], v170
	ds_read_b128 v[218:221], v170 offset:1024
	ds_read_b128 v[222:225], v170 offset:2048
	ds_read_b128 v[226:229], v170 offset:3072
	ds_read_b128 v[230:233], v170 offset:4096
	ds_read_b128 v[234:237], v170 offset:5120
	ds_read_b128 v[238:241], v170 offset:6144
	ds_read_b128 v[242:245], v170 offset:7168
	global_load_lds_dwordx4 v[178:179], off
	v_lshl_add_u64 v[178:179], vcc, 0, v[160:161]
	s_add_i32 m0, s38, 0xe000
	s_nop 0
	global_load_lds_dwordx4 v[178:179], off
	s_waitcnt vmcnt(8)
	s_waitcnt lgkmcnt(0)
	s_barrier
	s_setprio 1
	s_waitcnt lgkmcnt(0)
	v_mfma_f32_16x16x32_bf16 v[120:123], v[162:165], v[214:217], v[120:123]
	v_mfma_f32_16x16x32_bf16 v[124:127], v[174:177], v[214:217], v[124:127]
	v_mfma_f32_16x16x32_bf16 v[104:107], v[162:165], v[222:225], v[104:107]
	v_mfma_f32_16x16x32_bf16 v[108:111], v[174:177], v[222:225], v[108:111]
	v_mfma_f32_16x16x32_bf16 v[88:91], v[162:165], v[230:233], v[88:91]
	v_mfma_f32_16x16x32_bf16 v[92:95], v[174:177], v[230:233], v[92:95]
	v_mfma_f32_16x16x32_bf16 v[72:75], v[162:165], v[238:241], v[72:75]
	v_mfma_f32_16x16x32_bf16 v[76:79], v[174:177], v[238:241], v[76:79]
	v_mfma_f32_16x16x32_bf16 v[120:123], v[166:169], v[218:221], v[120:123]
	v_mfma_f32_16x16x32_bf16 v[124:127], v[194:197], v[218:221], v[124:127]
	v_mfma_f32_16x16x32_bf16 v[104:107], v[166:169], v[226:229], v[104:107]
	v_mfma_f32_16x16x32_bf16 v[108:111], v[194:197], v[226:229], v[108:111]
	v_mfma_f32_16x16x32_bf16 v[88:91], v[166:169], v[234:237], v[88:91]
	v_mfma_f32_16x16x32_bf16 v[92:95], v[194:197], v[234:237], v[92:95]
	v_mfma_f32_16x16x32_bf16 v[72:75], v[166:169], v[242:245], v[72:75]
	v_mfma_f32_16x16x32_bf16 v[76:79], v[194:197], v[242:245], v[76:79]
	s_setprio 0
	s_setprio 1
	v_mfma_f32_16x16x32_bf16 v[112:115], v[198:201], v[214:217], v[112:115]
	v_mfma_f32_16x16x32_bf16 v[116:119], v[206:209], v[214:217], v[116:119]
	v_mfma_f32_16x16x32_bf16 v[96:99], v[198:201], v[222:225], v[96:99]
	v_mfma_f32_16x16x32_bf16 v[100:103], v[206:209], v[222:225], v[100:103]
	v_mfma_f32_16x16x32_bf16 v[80:83], v[198:201], v[230:233], v[80:83]
	v_mfma_f32_16x16x32_bf16 v[84:87], v[206:209], v[230:233], v[84:87]
	v_mfma_f32_16x16x32_bf16 v[64:67], v[198:201], v[238:241], v[64:67]
	v_mfma_f32_16x16x32_bf16 v[68:71], v[206:209], v[238:241], v[68:71]
	v_mfma_f32_16x16x32_bf16 v[112:115], v[202:205], v[218:221], v[112:115]
	v_mfma_f32_16x16x32_bf16 v[116:119], v[210:213], v[218:221], v[116:119]
	v_mfma_f32_16x16x32_bf16 v[96:99], v[202:205], v[226:229], v[96:99]
	v_mfma_f32_16x16x32_bf16 v[100:103], v[210:213], v[226:229], v[100:103]
	v_mfma_f32_16x16x32_bf16 v[80:83], v[202:205], v[234:237], v[80:83]
	v_mfma_f32_16x16x32_bf16 v[84:87], v[210:213], v[234:237], v[84:87]
	v_mfma_f32_16x16x32_bf16 v[64:67], v[202:205], v[242:245], v[64:67]
	v_mfma_f32_16x16x32_bf16 v[68:71], v[210:213], v[242:245], v[68:71]
	s_setprio 0
	s_barrier
	s_mov_b32 m0, s39
	v_lshl_add_u64 v[178:179], s[18:19], 0, v[152:153]
	s_add_u32 s56, s18, 0x40000
	ds_read_b128 v[214:217], v170 offset:16384
	ds_read_b128 v[218:221], v170 offset:17408
	ds_read_b128 v[222:225], v170 offset:18432
	ds_read_b128 v[226:229], v170 offset:19456
	ds_read_b128 v[230:233], v170 offset:20480
	ds_read_b128 v[234:237], v170 offset:21504
	ds_read_b128 v[238:241], v170 offset:22528
	ds_read_b128 v[242:245], v170 offset:23552
	global_load_lds_dwordx4 v[178:179], off
	v_lshl_add_u64 v[188:189], s[18:19], 0, v[156:157]
	s_mov_b32 m0, s40
	s_addc_u32 s57, s19, 0
	global_load_lds_dwordx4 v[188:189], off
	v_lshl_add_u64 v[246:247], s[56:57], 0, v[152:153]
	s_mov_b32 m0, s41
	v_lshl_add_u64 v[248:249], s[20:21], 0, v[154:155]
	global_load_lds_dwordx4 v[246:247], off
	v_lshl_add_u64 v[246:247], s[56:57], 0, v[156:157]
	s_mov_b32 m0, s44
	s_nop 0
	global_load_lds_dwordx4 v[246:247], off
	v_lshl_add_u64 v[246:247], s[20:21], 0, v[150:151]
	s_mov_b32 m0, s38
	s_nop 0
	global_load_lds_dwordx4 v[246:247], off
	s_mov_b32 m0, s45
	s_nop 0
	global_load_lds_dwordx4 v[248:249], off
	s_waitcnt vmcnt(8)
	s_waitcnt lgkmcnt(0)
	s_barrier
; #define PG8_STAGE(bufoff, gbase, voff) do { _Pragma("unroll") for (int _i = 0; _i < 2; ++_i) \
;         __builtin_amdgcn_global_load_lds((const unsigned*)((const char*)(gbase) + (voff)[_i]), (PG8_LAS unsigned*)(lds + (bufoff) + ldsw + _i * 8192), 16, 0, 0); } while (0)
; #define PG8_LDA(dst, b, h) do { _Pragma("unroll") for (int m = 0; m < 4; ++m) _Pragma("unroll") for (int k = 0; k < 2; ++k) dst[m][k] = *(const PG8_LAS bf16x8*)(lds + PG8_SA(b, h) + aoff + m * 2048 + k * 1024); } while (0)
; #define PG8_LDB(dst, b, h) do { _Pragma("unroll") for (int n = 0; n < 2; ++n) _Pragma("unroll") for (int k = 0; k < 2; ++k) dst[n][k] = *(const PG8_LAS bf16x8*)(lds + PG8_SB(b, h) + boff + n * 2048 + k * 1024); } while (0)
; #define PG8_MMA(ai, bj, At, Bt) do { __builtin_amdgcn_s_setprio(1); _Pragma("unroll") for (int m = 0; m < 4; ++m) _Pragma("unroll") for (int n = 0; n < 2; ++n) _Pragma("unroll") for (int k = 0; k < 2; ++k) \
;         acc[ai][bj][m][n] = __builtin_amdgcn_mfma_f32_16x16x32_bf16(Bt[n][k], At[m][k], acc[ai][bj][m][n], 0, 0, 0); __builtin_amdgcn_s_setprio(0); } while (0)
; #define PG8_WAIT_V(n) asm volatile("s_waitcnt vmcnt(" #n ")" ::: "memory")
; #define PG8_WAIT_L(n) asm volatile("s_waitcnt lgkmcnt(" #n ")" ::: "memory")
; #define PG8_BAR __builtin_amdgcn_s_barrier()
; #define PG8_SCHED __builtin_amdgcn_sched_barrier(0)
; template <class Epi, class Sched, bool ALIGN_EPI = false, bool SP2 = false>
; __device__ __forceinline__ void gemm_phase(PG8_LAS unsigned char* lds, const Gemm g, const Sched& S, const Epi& E) {
;     ...
;             PG8_WAIT_V(8); PG8_WAIT_L(0); PG8_BAR; PG8_MMA(1, 0, At, B0); PG8_MMA(1, 1, At, B1); PG8_BAR; PG8_SCHED;
;             PG8_LDB(B0, 1, 0); PG8_LDB(B1, 1, 1); PG8_SCHED; PG8_LDA(At, 1, 0); PG8_STAGE(PG8_SA(0, 1), a2 + hstepA, voffA);
;             PG8_WAIT_V(8); PG8_WAIT_L(0); PG8_BAR; PG8_MMA(0, 0, At, B0); PG8_MMA(0, 1, At, B1); PG8_BAR; PG8_SCHED;
	s_setprio 1
	s_waitcnt lgkmcnt(0)
	v_mfma_f32_16x16x32_bf16 v[56:59], v[162:165], v[214:217], v[56:59]
	v_mfma_f32_16x16x32_bf16 v[60:63], v[174:177], v[214:217], v[60:63]
	v_mfma_f32_16x16x32_bf16 v[40:43], v[162:165], v[222:225], v[40:43]
	v_mfma_f32_16x16x32_bf16 v[44:47], v[174:177], v[222:225], v[44:47]
	v_mfma_f32_16x16x32_bf16 v[24:27], v[162:165], v[230:233], v[24:27]
	v_mfma_f32_16x16x32_bf16 v[28:31], v[174:177], v[230:233], v[28:31]
	v_mfma_f32_16x16x32_bf16 v[8:11], v[162:165], v[238:241], v[8:11]
	v_mfma_f32_16x16x32_bf16 v[12:15], v[174:177], v[238:241], v[12:15]
	v_mfma_f32_16x16x32_bf16 v[56:59], v[166:169], v[218:221], v[56:59]
	v_mfma_f32_16x16x32_bf16 v[60:63], v[194:197], v[218:221], v[60:63]
	v_mfma_f32_16x16x32_bf16 v[40:43], v[166:169], v[226:229], v[40:43]
	v_mfma_f32_16x16x32_bf16 v[44:47], v[194:197], v[226:229], v[44:47]
	v_mfma_f32_16x16x32_bf16 v[24:27], v[166:169], v[234:237], v[24:27]
	v_mfma_f32_16x16x32_bf16 v[28:31], v[194:197], v[234:237], v[28:31]
	v_mfma_f32_16x16x32_bf16 v[8:11], v[166:169], v[242:245], v[8:11]
	v_mfma_f32_16x16x32_bf16 v[12:15], v[194:197], v[242:245], v[12:15]
	s_setprio 0
	s_setprio 1
	v_mfma_f32_16x16x32_bf16 v[48:51], v[198:201], v[214:217], v[48:51]
	v_mfma_f32_16x16x32_bf16 v[52:55], v[206:209], v[214:217], v[52:55]
	v_mfma_f32_16x16x32_bf16 v[32:35], v[198:201], v[222:225], v[32:35]
	v_mfma_f32_16x16x32_bf16 v[36:39], v[206:209], v[222:225], v[36:39]
	v_mfma_f32_16x16x32_bf16 v[16:19], v[198:201], v[230:233], v[16:19]
	v_mfma_f32_16x16x32_bf16 v[20:23], v[206:209], v[230:233], v[20:23]
	v_mfma_f32_16x16x32_bf16 v[0:3], v[198:201], v[238:241], v[0:3]
	v_mfma_f32_16x16x32_bf16 v[4:7], v[206:209], v[238:241], v[4:7]
	v_mfma_f32_16x16x32_bf16 v[48:51], v[202:205], v[218:221], v[48:51]
	v_mfma_f32_16x16x32_bf16 v[52:55], v[210:213], v[218:221], v[52:55]
	v_mfma_f32_16x16x32_bf16 v[32:35], v[202:205], v[226:229], v[32:35]
	v_mfma_f32_16x16x32_bf16 v[36:39], v[210:213], v[226:229], v[36:39]
	v_mfma_f32_16x16x32_bf16 v[16:19], v[202:205], v[234:237], v[16:19]
	v_mfma_f32_16x16x32_bf16 v[20:23], v[210:213], v[234:237], v[20:23]
	v_mfma_f32_16x16x32_bf16 v[0:3], v[202:205], v[242:245], v[0:3]
	v_mfma_f32_16x16x32_bf16 v[4:7], v[210:213], v[242:245], v[4:7]
	s_setprio 0
	s_barrier
	v_or_b32_e32 v162, 0x18000, v171
	v_add_u32_e32 v166, 0x18400, v171
	v_add_u32_e32 v173, 0x18800, v171
	v_add_u32_e32 v194, 0x18c00, v171
	ds_read_b128 v[162:165], v162
	ds_read_b128 v[166:169], v166
	ds_read_b128 v[174:177], v173
	ds_read_b128 v[194:197], v194
	v_or_b32_e32 v173, 0x1c000, v171
	v_add_u32_e32 v202, 0x1c400, v171
	ds_read_b128 v[198:201], v173
	ds_read_b128 v[202:205], v202
	v_add_u32_e32 v173, 0x1c800, v171
	v_add_u32_e32 v210, 0x1cc00, v171
	ds_read_b128 v[206:209], v173
	ds_read_b128 v[210:213], v210
	s_add_u32 s20, s20, 0x40000
	s_addc_u32 s21, s21, 0
	s_mov_b32 m0, s46
	v_lshl_add_u64 v[250:251], s[20:21], 0, v[150:151]
	ds_read_b128 v[214:217], v170 offset:32768
	ds_read_b128 v[218:221], v170 offset:33792
	ds_read_b128 v[222:225], v170 offset:34816
	ds_read_b128 v[226:229], v170 offset:35840
	ds_read_b128 v[230:233], v170 offset:36864
	ds_read_b128 v[234:237], v170 offset:37888
	ds_read_b128 v[238:241], v170 offset:38912
	ds_read_b128 v[242:245], v170 offset:39936
	global_load_lds_dwordx4 v[250:251], off
	v_lshl_add_u64 v[250:251], s[20:21], 0, v[154:155]
	s_mov_b32 m0, s47
	s_nop 0
	global_load_lds_dwordx4 v[250:251], off
	s_waitcnt vmcnt(8)
	s_waitcnt lgkmcnt(0)
	s_barrier
	s_setprio 1
	s_waitcnt lgkmcnt(0)
	v_mfma_f32_16x16x32_bf16 v[120:123], v[162:165], v[214:217], v[120:123]
	v_mfma_f32_16x16x32_bf16 v[124:127], v[174:177], v[214:217], v[124:127]
	v_mfma_f32_16x16x32_bf16 v[104:107], v[162:165], v[222:225], v[104:107]
	v_mfma_f32_16x16x32_bf16 v[108:111], v[174:177], v[222:225], v[108:111]
	v_mfma_f32_16x16x32_bf16 v[88:91], v[162:165], v[230:233], v[88:91]
	v_mfma_f32_16x16x32_bf16 v[92:95], v[174:177], v[230:233], v[92:95]
	v_mfma_f32_16x16x32_bf16 v[72:75], v[162:165], v[238:241], v[72:75]
	v_mfma_f32_16x16x32_bf16 v[76:79], v[174:177], v[238:241], v[76:79]
	v_mfma_f32_16x16x32_bf16 v[120:123], v[166:169], v[218:221], v[120:123]
	v_mfma_f32_16x16x32_bf16 v[124:127], v[194:197], v[218:221], v[124:127]
	v_mfma_f32_16x16x32_bf16 v[104:107], v[166:169], v[226:229], v[104:107]
	v_mfma_f32_16x16x32_bf16 v[108:111], v[194:197], v[226:229], v[108:111]
	v_mfma_f32_16x16x32_bf16 v[88:91], v[166:169], v[234:237], v[88:91]
	v_mfma_f32_16x16x32_bf16 v[92:95], v[194:197], v[234:237], v[92:95]
	v_mfma_f32_16x16x32_bf16 v[72:75], v[166:169], v[242:245], v[72:75]
	v_mfma_f32_16x16x32_bf16 v[76:79], v[194:197], v[242:245], v[76:79]
	s_setprio 0
	s_setprio 1
	v_mfma_f32_16x16x32_bf16 v[112:115], v[198:201], v[214:217], v[112:115]
	v_mfma_f32_16x16x32_bf16 v[116:119], v[206:209], v[214:217], v[116:119]
	v_mfma_f32_16x16x32_bf16 v[96:99], v[198:201], v[222:225], v[96:99]
	v_mfma_f32_16x16x32_bf16 v[100:103], v[206:209], v[222:225], v[100:103]
	v_mfma_f32_16x16x32_bf16 v[80:83], v[198:201], v[230:233], v[80:83]
	v_mfma_f32_16x16x32_bf16 v[84:87], v[206:209], v[230:233], v[84:87]
	v_mfma_f32_16x16x32_bf16 v[64:67], v[198:201], v[238:241], v[64:67]
	v_mfma_f32_16x16x32_bf16 v[68:71], v[206:209], v[238:241], v[68:71]
	v_mfma_f32_16x16x32_bf16 v[112:115], v[202:205], v[218:221], v[112:115]
	v_mfma_f32_16x16x32_bf16 v[116:119], v[210:213], v[218:221], v[116:119]
	v_mfma_f32_16x16x32_bf16 v[96:99], v[202:205], v[226:229], v[96:99]
	v_mfma_f32_16x16x32_bf16 v[100:103], v[210:213], v[226:229], v[100:103]
	v_mfma_f32_16x16x32_bf16 v[80:83], v[202:205], v[234:237], v[80:83]
	v_mfma_f32_16x16x32_bf16 v[84:87], v[210:213], v[234:237], v[84:87]
	v_mfma_f32_16x16x32_bf16 v[64:67], v[202:205], v[242:245], v[64:67]
	v_mfma_f32_16x16x32_bf16 v[68:71], v[210:213], v[242:245], v[68:71]
	s_setprio 0
	s_barrier
; #define PG8_STAGE(bufoff, gbase, voff) do { _Pragma("unroll") for (int _i = 0; _i < 2; ++_i) \
;         __builtin_amdgcn_global_load_lds((const unsigned*)((const char*)(gbase) + (voff)[_i]), (PG8_LAS unsigned*)(lds + (bufoff) + ldsw + _i * 8192), 16, 0, 0); } while (0)
; #define PG8_LDA(dst, b, h) do { _Pragma("unroll") for (int m = 0; m < 4; ++m) _Pragma("unroll") for (int k = 0; k < 2; ++k) dst[m][k] = *(const PG8_LAS bf16x8*)(lds + PG8_SA(b, h) + aoff + m * 2048 + k * 1024); } while (0)
; #define PG8_MMA(ai, bj, At, Bt) do { __builtin_amdgcn_s_setprio(1); _Pragma("unroll") for (int m = 0; m < 4; ++m) _Pragma("unroll") for (int n = 0; n < 2; ++n) _Pragma("unroll") for (int k = 0; k < 2; ++k) \
;         acc[ai][bj][m][n] = __builtin_amdgcn_mfma_f32_16x16x32_bf16(Bt[n][k], At[m][k], acc[ai][bj][m][n], 0, 0, 0); __builtin_amdgcn_s_setprio(0); } while (0)
; #define PG8_WAIT_V(n) asm volatile("s_waitcnt vmcnt(" #n ")" ::: "memory")
; #define PG8_WAIT_L(n) asm volatile("s_waitcnt lgkmcnt(" #n ")" ::: "memory")
; #define PG8_BAR __builtin_amdgcn_s_barrier()
; #define PG8_SCHED __builtin_amdgcn_sched_barrier(0)
; template <class Epi, class Sched, bool ALIGN_EPI = false, bool SP2 = false>
; __device__ __forceinline__ void gemm_phase(PG8_LAS unsigned char* lds, const Gemm g, const Sched& S, const Epi& E) {
;     ...
;             PG8_LDA(At, 1, 1); PG8_STAGE(PG8_SB(1, 0), b3, voffB); PG8_STAGE(PG8_SB(1, 1), b3 + hstepB, voffB); PG8_STAGE(PG8_SA(1, 0), a3, voffA);
;             PG8_WAIT_V(8); PG8_WAIT_L(0); PG8_BAR; PG8_MMA(1, 0, At, B0); PG8_MMA(1, 1, At, B1); PG8_BAR; PG8_SCHED;
	s_mov_b32 m0, s58
	v_lshl_add_u64 v[178:179], v[178:179], 0, s[54:55]
	s_add_u32 s18, s18, 0x40080
	ds_read_b128 v[214:217], v170 offset:49152
	ds_read_b128 v[218:221], v170 offset:50176
	ds_read_b128 v[222:225], v170 offset:51200
	ds_read_b128 v[226:229], v170 offset:52224
	ds_read_b128 v[230:233], v170 offset:53248
	ds_read_b128 v[234:237], v170 offset:54272
	ds_read_b128 v[238:241], v170 offset:55296
	ds_read_b128 v[242:245], v170 offset:56320
	global_load_lds_dwordx4 v[178:179], off
	v_lshl_add_u64 v[178:179], v[188:189], 0, s[54:55]
	s_mov_b32 m0, s59
	s_addc_u32 s19, s19, 0
	global_load_lds_dwordx4 v[178:179], off
	v_lshl_add_u64 v[178:179], s[18:19], 0, v[152:153]
	s_mov_b32 m0, s65
	s_nop 0
	global_load_lds_dwordx4 v[178:179], off
	v_lshl_add_u64 v[178:179], s[18:19], 0, v[156:157]
	s_mov_b32 m0, s72
	s_nop 0
	global_load_lds_dwordx4 v[178:179], off
	v_lshl_add_u64 v[178:179], v[246:247], 0, s[54:55]
	s_mov_b32 m0, s63
	s_nop 0
	global_load_lds_dwordx4 v[178:179], off
	v_lshl_add_u64 v[178:179], v[248:249], 0, s[54:55]
	s_mov_b32 m0, s64
	s_nop 0
	global_load_lds_dwordx4 v[178:179], off
	s_waitcnt vmcnt(8)
	s_waitcnt lgkmcnt(0)
	s_barrier
	s_setprio 1
	s_waitcnt lgkmcnt(0)
	v_mfma_f32_16x16x32_bf16 v[56:59], v[162:165], v[214:217], v[56:59]
	v_mfma_f32_16x16x32_bf16 v[60:63], v[174:177], v[214:217], v[60:63]
	v_mfma_f32_16x16x32_bf16 v[40:43], v[162:165], v[222:225], v[40:43]
	v_mfma_f32_16x16x32_bf16 v[44:47], v[174:177], v[222:225], v[44:47]
	v_mfma_f32_16x16x32_bf16 v[24:27], v[162:165], v[230:233], v[24:27]
	v_mfma_f32_16x16x32_bf16 v[28:31], v[174:177], v[230:233], v[28:31]
	v_mfma_f32_16x16x32_bf16 v[8:11], v[162:165], v[238:241], v[8:11]
	v_mfma_f32_16x16x32_bf16 v[12:15], v[174:177], v[238:241], v[12:15]
	v_mfma_f32_16x16x32_bf16 v[56:59], v[166:169], v[218:221], v[56:59]
	v_mfma_f32_16x16x32_bf16 v[60:63], v[194:197], v[218:221], v[60:63]
	v_mfma_f32_16x16x32_bf16 v[40:43], v[166:169], v[226:229], v[40:43]
	v_mfma_f32_16x16x32_bf16 v[44:47], v[194:197], v[226:229], v[44:47]
	v_mfma_f32_16x16x32_bf16 v[24:27], v[166:169], v[234:237], v[24:27]
	v_mfma_f32_16x16x32_bf16 v[28:31], v[194:197], v[234:237], v[28:31]
	v_mfma_f32_16x16x32_bf16 v[8:11], v[166:169], v[242:245], v[8:11]
	v_mfma_f32_16x16x32_bf16 v[12:15], v[194:197], v[242:245], v[12:15]
	s_setprio 0
	s_setprio 1
	v_mfma_f32_16x16x32_bf16 v[48:51], v[198:201], v[214:217], v[48:51]
	v_mfma_f32_16x16x32_bf16 v[52:55], v[206:209], v[214:217], v[52:55]
	v_mfma_f32_16x16x32_bf16 v[32:35], v[198:201], v[222:225], v[32:35]
	v_mfma_f32_16x16x32_bf16 v[36:39], v[206:209], v[222:225], v[36:39]
	v_mfma_f32_16x16x32_bf16 v[16:19], v[198:201], v[230:233], v[16:19]
	v_mfma_f32_16x16x32_bf16 v[20:23], v[206:209], v[230:233], v[20:23]
	v_mfma_f32_16x16x32_bf16 v[0:3], v[198:201], v[238:241], v[0:3]
	v_mfma_f32_16x16x32_bf16 v[4:7], v[206:209], v[238:241], v[4:7]
	v_mfma_f32_16x16x32_bf16 v[48:51], v[202:205], v[218:221], v[48:51]
	v_mfma_f32_16x16x32_bf16 v[52:55], v[210:213], v[218:221], v[52:55]
	v_mfma_f32_16x16x32_bf16 v[32:35], v[202:205], v[226:229], v[32:35]
	v_mfma_f32_16x16x32_bf16 v[36:39], v[210:213], v[226:229], v[36:39]
	v_mfma_f32_16x16x32_bf16 v[16:19], v[202:205], v[234:237], v[16:19]
	v_mfma_f32_16x16x32_bf16 v[20:23], v[210:213], v[234:237], v[20:23]
	v_mfma_f32_16x16x32_bf16 v[0:3], v[202:205], v[242:245], v[0:3]
	v_mfma_f32_16x16x32_bf16 v[4:7], v[210:213], v[242:245], v[4:7]
	s_setprio 0
	s_barrier
	s_add_i32 s75, s75, 2
	s_add_u32 vcc_lo, vcc_lo, 0x100
	s_addc_u32 vcc_hi, vcc_hi, 0
	s_add_u32 s42, s42, 0x100
	s_addc_u32 s43, s43, 0
	s_cmp_gt_u32 s75, 13
	s_cbranch_scc0 .LBB0_2177
	s_and_b64 vcc, exec, s[10:11]
	s_cbranch_vccz .LBB0_2180
	s_barrier

; #define PG8_STAGE(bufoff, gbase, voff) do { _Pragma("unroll") for (int _i = 0; _i < 2; ++_i) \
;         __builtin_amdgcn_global_load_lds((const unsigned*)((const char*)(gbase) + (voff)[_i]), (PG8_LAS unsigned*)(lds + (bufoff) + ldsw + _i * 8192), 16, 0, 0); } while (0)
; #define PG8_LDA(dst, b, h) do { _Pragma("unroll") for (int m = 0; m < 4; ++m) _Pragma("unroll") for (int k = 0; k < 2; ++k) dst[m][k] = *(const PG8_LAS bf16x8*)(lds + PG8_SA(b, h) + aoff + m * 2048 + k * 1024); } while (0)
; #define PG8_LDB(dst, b, h) do { _Pragma("unroll") for (int n = 0; n < 2; ++n) _Pragma("unroll") for (int k = 0; k < 2; ++k) dst[n][k] = *(const PG8_LAS bf16x8*)(lds + PG8_SB(b, h) + boff + n * 2048 + k * 1024); } while (0)
; #define PG8_MMA(ai, bj, At, Bt) do { __builtin_amdgcn_s_setprio(1); _Pragma("unroll") for (int m = 0; m < 4; ++m) _Pragma("unroll") for (int n = 0; n < 2; ++n) _Pragma("unroll") for (int k = 0; k < 2; ++k) \
;         acc[ai][bj][m][n] = __builtin_amdgcn_mfma_f32_16x16x32_bf16(Bt[n][k], At[m][k], acc[ai][bj][m][n], 0, 0, 0); __builtin_amdgcn_s_setprio(0); } while (0)
; #define PG8_WAIT_V(n) asm volatile("s_waitcnt vmcnt(" #n ")" ::: "memory")
; #define PG8_WAIT_L(n) asm volatile("s_waitcnt lgkmcnt(" #n ")" ::: "memory")
; #define PG8_BAR __builtin_amdgcn_s_barrier()
; #define PG8_SCHED __builtin_amdgcn_sched_barrier(0)
; template <class Epi, class Sched, bool ALIGN_EPI = false, bool SP2 = false>
; __device__ __forceinline__ void gemm_phase(PG8_LAS unsigned char* lds, const Gemm g, const Sched& S, const Epi& E) {
;     ...
;             PG8_LDB(B0, 0, 0); PG8_LDB(B1, 0, 1); PG8_SCHED; PG8_LDA(At, 0, 0); PG8_STAGE(PG8_SA(1, 1), a1 + hstepA, voffA);
;             PG8_WAIT_V(8); PG8_WAIT_L(0); PG8_BAR; PG8_MMA(0, 0, At, B0); PG8_MMA(0, 1, At, B1); PG8_BAR; PG8_SCHED;
;             PG8_LDA(At, 0, 1); PG8_STAGE(PG8_SB(0, 0), b2, voffB); PG8_STAGE(PG8_SB(0, 1), b2 + hstepB, voffB); PG8_STAGE(PG8_SA(0, 0), a2, voffA);
.LBB0_2351:
	v_or_b32_e32 v158, 0x10000, v167
	v_add_u32_e32 v162, 0x10400, v167
	v_add_u32_e32 v169, 0x10800, v167
	v_add_u32_e32 v174, 0x10c00, v167
	ds_read_b128 v[158:161], v158
	ds_read_b128 v[162:165], v162
	ds_read_b128 v[170:173], v169
	ds_read_b128 v[174:177], v174
	v_or_b32_e32 v169, 0x14000, v167
	v_add_u32_e32 v178, 0x14400, v167
	ds_read_b128 v[194:197], v169
	ds_read_b128 v[198:201], v178
	v_add_u32_e32 v169, 0x14800, v167
	v_add_u32_e32 v178, 0x14c00, v167
	ds_read_b128 v[202:205], v169
	ds_read_b128 v[206:209], v178
	s_add_u32 s18, vcc_lo, 0xfff00080
	s_addc_u32 s19, vcc_hi, -1
	s_cmp_eq_u32 s43, 60
	s_cselect_b32 s21, s11, s19
	s_cselect_b32 s20, s17, s18
	s_cselect_b32 s19, s9, s42
	s_cselect_b32 s18, s25, s27
	v_lshl_add_u64 v[178:179], vcc, 0, v[154:155]
	s_add_i32 m0, s36, 0xc000
	ds_read_b128 v[210:213], v166
	ds_read_b128 v[214:217], v166 offset:1024
	ds_read_b128 v[218:221], v166 offset:2048
	ds_read_b128 v[222:225], v166 offset:3072
	ds_read_b128 v[226:229], v166 offset:4096
	ds_read_b128 v[230:233], v166 offset:5120
	ds_read_b128 v[234:237], v166 offset:6144
	ds_read_b128 v[238:241], v166 offset:7168
	global_load_lds_dwordx4 v[178:179], off
	v_lshl_add_u64 v[178:179], vcc, 0, v[156:157]
	s_add_i32 m0, s36, 0xe000
	s_nop 0
	global_load_lds_dwordx4 v[178:179], off
	s_waitcnt vmcnt(8)
	s_waitcnt lgkmcnt(0)
	s_barrier
	s_setprio 1
	s_waitcnt lgkmcnt(0)
	v_mfma_f32_16x16x32_bf16 v[124:127], v[158:161], v[210:213], v[124:127]
	v_mfma_f32_16x16x32_bf16 v[120:123], v[170:173], v[210:213], v[120:123]
	v_mfma_f32_16x16x32_bf16 v[108:111], v[158:161], v[218:221], v[108:111]
	v_mfma_f32_16x16x32_bf16 v[104:107], v[170:173], v[218:221], v[104:107]
	v_mfma_f32_16x16x32_bf16 v[92:95], v[158:161], v[226:229], v[92:95]
	v_mfma_f32_16x16x32_bf16 v[88:91], v[170:173], v[226:229], v[88:91]
	v_mfma_f32_16x16x32_bf16 v[76:79], v[158:161], v[234:237], v[76:79]
	v_mfma_f32_16x16x32_bf16 v[72:75], v[170:173], v[234:237], v[72:75]
	v_mfma_f32_16x16x32_bf16 v[124:127], v[162:165], v[214:217], v[124:127]
	v_mfma_f32_16x16x32_bf16 v[120:123], v[174:177], v[214:217], v[120:123]
	v_mfma_f32_16x16x32_bf16 v[108:111], v[162:165], v[222:225], v[108:111]
	v_mfma_f32_16x16x32_bf16 v[104:107], v[174:177], v[222:225], v[104:107]
	v_mfma_f32_16x16x32_bf16 v[92:95], v[162:165], v[230:233], v[92:95]
	v_mfma_f32_16x16x32_bf16 v[88:91], v[174:177], v[230:233], v[88:91]
	v_mfma_f32_16x16x32_bf16 v[76:79], v[162:165], v[238:241], v[76:79]
	v_mfma_f32_16x16x32_bf16 v[72:75], v[174:177], v[238:241], v[72:75]
	s_setprio 0
	s_setprio 1
	v_mfma_f32_16x16x32_bf16 v[116:119], v[194:197], v[210:213], v[116:119]
	v_mfma_f32_16x16x32_bf16 v[112:115], v[202:205], v[210:213], v[112:115]
	v_mfma_f32_16x16x32_bf16 v[100:103], v[194:197], v[218:221], v[100:103]
	v_mfma_f32_16x16x32_bf16 v[96:99], v[202:205], v[218:221], v[96:99]
	v_mfma_f32_16x16x32_bf16 v[84:87], v[194:197], v[226:229], v[84:87]
	v_mfma_f32_16x16x32_bf16 v[80:83], v[202:205], v[226:229], v[80:83]
	v_mfma_f32_16x16x32_bf16 v[68:71], v[194:197], v[234:237], v[68:71]
	v_mfma_f32_16x16x32_bf16 v[64:67], v[202:205], v[234:237], v[64:67]
	v_mfma_f32_16x16x32_bf16 v[116:119], v[198:201], v[214:217], v[116:119]
	v_mfma_f32_16x16x32_bf16 v[112:115], v[206:209], v[214:217], v[112:115]
	v_mfma_f32_16x16x32_bf16 v[100:103], v[198:201], v[222:225], v[100:103]
	v_mfma_f32_16x16x32_bf16 v[96:99], v[206:209], v[222:225], v[96:99]
	v_mfma_f32_16x16x32_bf16 v[84:87], v[198:201], v[230:233], v[84:87]
	v_mfma_f32_16x16x32_bf16 v[80:83], v[206:209], v[230:233], v[80:83]
	v_mfma_f32_16x16x32_bf16 v[68:71], v[198:201], v[238:241], v[68:71]
	v_mfma_f32_16x16x32_bf16 v[64:67], v[206:209], v[238:241], v[64:67]
	s_setprio 0
	s_barrier
	s_mov_b32 m0, s37
	v_lshl_add_u64 v[178:179], s[18:19], 0, v[150:151]
	s_add_u32 s56, s18, 0x100000
	ds_read_b128 v[210:213], v166 offset:16384
	ds_read_b128 v[214:217], v166 offset:17408
	ds_read_b128 v[218:221], v166 offset:18432
	ds_read_b128 v[222:225], v166 offset:19456
	ds_read_b128 v[226:229], v166 offset:20480
	ds_read_b128 v[230:233], v166 offset:21504
	ds_read_b128 v[234:237], v166 offset:22528
	ds_read_b128 v[238:241], v166 offset:23552
	global_load_lds_dwordx4 v[178:179], off
	v_lshl_add_u64 v[188:189], s[18:19], 0, v[152:153]
	s_mov_b32 m0, s95
	s_addc_u32 s57, s19, 0
	global_load_lds_dwordx4 v[188:189], off
	v_lshl_add_u64 v[242:243], s[56:57], 0, v[150:151]
	s_mov_b32 m0, s38
	v_lshl_add_u64 v[244:245], s[20:21], 0, v[152:153]
	global_load_lds_dwordx4 v[242:243], off
	v_lshl_add_u64 v[242:243], s[56:57], 0, v[152:153]
	s_mov_b32 m0, s39
	s_nop 0
	global_load_lds_dwordx4 v[242:243], off
	v_lshl_add_u64 v[242:243], s[20:21], 0, v[150:151]
	s_mov_b32 m0, s36
	s_nop 0
	global_load_lds_dwordx4 v[242:243], off
	s_mov_b32 m0, s40
	s_nop 0
	global_load_lds_dwordx4 v[244:245], off
	s_waitcnt vmcnt(8)
	s_waitcnt lgkmcnt(0)
	s_barrier
; #define PG8_STAGE(bufoff, gbase, voff) do { _Pragma("unroll") for (int _i = 0; _i < 2; ++_i) \
;         __builtin_amdgcn_global_load_lds((const unsigned*)((const char*)(gbase) + (voff)[_i]), (PG8_LAS unsigned*)(lds + (bufoff) + ldsw + _i * 8192), 16, 0, 0); } while (0)
; #define PG8_LDA(dst, b, h) do { _Pragma("unroll") for (int m = 0; m < 4; ++m) _Pragma("unroll") for (int k = 0; k < 2; ++k) dst[m][k] = *(const PG8_LAS bf16x8*)(lds + PG8_SA(b, h) + aoff + m * 2048 + k * 1024); } while (0)
; #define PG8_LDB(dst, b, h) do { _Pragma("unroll") for (int n = 0; n < 2; ++n) _Pragma("unroll") for (int k = 0; k < 2; ++k) dst[n][k] = *(const PG8_LAS bf16x8*)(lds + PG8_SB(b, h) + boff + n * 2048 + k * 1024); } while (0)
; #define PG8_MMA(ai, bj, At, Bt) do { __builtin_amdgcn_s_setprio(1); _Pragma("unroll") for (int m = 0; m < 4; ++m) _Pragma("unroll") for (int n = 0; n < 2; ++n) _Pragma("unroll") for (int k = 0; k < 2; ++k) \
;         acc[ai][bj][m][n] = __builtin_amdgcn_mfma_f32_16x16x32_bf16(Bt[n][k], At[m][k], acc[ai][bj][m][n], 0, 0, 0); __builtin_amdgcn_s_setprio(0); } while (0)
; #define PG8_WAIT_V(n) asm volatile("s_waitcnt vmcnt(" #n ")" ::: "memory")
; #define PG8_WAIT_L(n) asm volatile("s_waitcnt lgkmcnt(" #n ")" ::: "memory")
; #define PG8_BAR __builtin_amdgcn_s_barrier()
; #define PG8_SCHED __builtin_amdgcn_sched_barrier(0)
; template <class Epi, class Sched, bool ALIGN_EPI = false, bool SP2 = false>
; __device__ __forceinline__ void gemm_phase(PG8_LAS unsigned char* lds, const Gemm g, const Sched& S, const Epi& E) {
;     ...
;             PG8_WAIT_V(8); PG8_WAIT_L(0); PG8_BAR; PG8_MMA(1, 0, At, B0); PG8_MMA(1, 1, At, B1); PG8_BAR; PG8_SCHED;
;             PG8_LDB(B0, 1, 0); PG8_LDB(B1, 1, 1); PG8_SCHED; PG8_LDA(At, 1, 0); PG8_STAGE(PG8_SA(0, 1), a2 + hstepA, voffA);
;             PG8_WAIT_V(8); PG8_WAIT_L(0); PG8_BAR; PG8_MMA(0, 0, At, B0); PG8_MMA(0, 1, At, B1); PG8_BAR; PG8_SCHED;
	s_setprio 1
	s_waitcnt lgkmcnt(0)
	v_mfma_f32_16x16x32_bf16 v[60:63], v[158:161], v[210:213], v[60:63]
	v_mfma_f32_16x16x32_bf16 v[56:59], v[170:173], v[210:213], v[56:59]
	v_mfma_f32_16x16x32_bf16 v[44:47], v[158:161], v[218:221], v[44:47]
	v_mfma_f32_16x16x32_bf16 v[40:43], v[170:173], v[218:221], v[40:43]
	v_mfma_f32_16x16x32_bf16 v[28:31], v[158:161], v[226:229], v[28:31]
	v_mfma_f32_16x16x32_bf16 v[24:27], v[170:173], v[226:229], v[24:27]
	v_mfma_f32_16x16x32_bf16 v[12:15], v[158:161], v[234:237], v[12:15]
	v_mfma_f32_16x16x32_bf16 v[8:11], v[170:173], v[234:237], v[8:11]
	v_mfma_f32_16x16x32_bf16 v[60:63], v[162:165], v[214:217], v[60:63]
	v_mfma_f32_16x16x32_bf16 v[56:59], v[174:177], v[214:217], v[56:59]
	v_mfma_f32_16x16x32_bf16 v[44:47], v[162:165], v[222:225], v[44:47]
	v_mfma_f32_16x16x32_bf16 v[40:43], v[174:177], v[222:225], v[40:43]
	v_mfma_f32_16x16x32_bf16 v[28:31], v[162:165], v[230:233], v[28:31]
	v_mfma_f32_16x16x32_bf16 v[24:27], v[174:177], v[230:233], v[24:27]
	v_mfma_f32_16x16x32_bf16 v[12:15], v[162:165], v[238:241], v[12:15]
	v_mfma_f32_16x16x32_bf16 v[8:11], v[174:177], v[238:241], v[8:11]
	s_setprio 0
	s_setprio 1
	v_mfma_f32_16x16x32_bf16 v[52:55], v[194:197], v[210:213], v[52:55]
	v_mfma_f32_16x16x32_bf16 v[48:51], v[202:205], v[210:213], v[48:51]
	v_mfma_f32_16x16x32_bf16 v[36:39], v[194:197], v[218:221], v[36:39]
	v_mfma_f32_16x16x32_bf16 v[32:35], v[202:205], v[218:221], v[32:35]
	v_mfma_f32_16x16x32_bf16 v[20:23], v[194:197], v[226:229], v[20:23]
	v_mfma_f32_16x16x32_bf16 v[16:19], v[202:205], v[226:229], v[16:19]
	v_mfma_f32_16x16x32_bf16 v[4:7], v[194:197], v[234:237], v[4:7]
	v_mfma_f32_16x16x32_bf16 v[0:3], v[202:205], v[234:237], v[0:3]
	v_mfma_f32_16x16x32_bf16 v[52:55], v[198:201], v[214:217], v[52:55]
	v_mfma_f32_16x16x32_bf16 v[48:51], v[206:209], v[214:217], v[48:51]
	v_mfma_f32_16x16x32_bf16 v[36:39], v[198:201], v[222:225], v[36:39]
	v_mfma_f32_16x16x32_bf16 v[32:35], v[206:209], v[222:225], v[32:35]
	v_mfma_f32_16x16x32_bf16 v[20:23], v[198:201], v[230:233], v[20:23]
	v_mfma_f32_16x16x32_bf16 v[16:19], v[206:209], v[230:233], v[16:19]
	v_mfma_f32_16x16x32_bf16 v[4:7], v[198:201], v[238:241], v[4:7]
	v_mfma_f32_16x16x32_bf16 v[0:3], v[206:209], v[238:241], v[0:3]
	s_setprio 0
	s_barrier
	v_or_b32_e32 v158, 0x18000, v167
	v_add_u32_e32 v162, 0x18400, v167
	v_add_u32_e32 v169, 0x18800, v167
	v_add_u32_e32 v174, 0x18c00, v167
	ds_read_b128 v[158:161], v158
	ds_read_b128 v[162:165], v162
	ds_read_b128 v[170:173], v169
	ds_read_b128 v[174:177], v174
	v_or_b32_e32 v169, 0x1c000, v167
	v_add_u32_e32 v198, 0x1c400, v167
	ds_read_b128 v[194:197], v169
	ds_read_b128 v[198:201], v198
	v_add_u32_e32 v169, 0x1c800, v167
	v_add_u32_e32 v206, 0x1cc00, v167
	ds_read_b128 v[202:205], v169
	ds_read_b128 v[206:209], v206
	s_add_u32 s20, s20, 0x100000
	s_addc_u32 s21, s21, 0
	s_mov_b32 m0, s41
	v_lshl_add_u64 v[246:247], s[20:21], 0, v[150:151]
	ds_read_b128 v[210:213], v166 offset:32768
	ds_read_b128 v[214:217], v166 offset:33792
	ds_read_b128 v[218:221], v166 offset:34816
	ds_read_b128 v[222:225], v166 offset:35840
	ds_read_b128 v[226:229], v166 offset:36864
	ds_read_b128 v[230:233], v166 offset:37888
	ds_read_b128 v[234:237], v166 offset:38912
	ds_read_b128 v[238:241], v166 offset:39936
	global_load_lds_dwordx4 v[246:247], off
	v_lshl_add_u64 v[246:247], s[20:21], 0, v[152:153]
	s_mov_b32 m0, s44
	s_nop 0
	global_load_lds_dwordx4 v[246:247], off
	s_waitcnt vmcnt(8)
	s_waitcnt lgkmcnt(0)
	s_barrier
	s_setprio 1
	s_waitcnt lgkmcnt(0)
	v_mfma_f32_16x16x32_bf16 v[124:127], v[158:161], v[210:213], v[124:127]
	v_mfma_f32_16x16x32_bf16 v[120:123], v[170:173], v[210:213], v[120:123]
	v_mfma_f32_16x16x32_bf16 v[108:111], v[158:161], v[218:221], v[108:111]
	v_mfma_f32_16x16x32_bf16 v[104:107], v[170:173], v[218:221], v[104:107]
	v_mfma_f32_16x16x32_bf16 v[92:95], v[158:161], v[226:229], v[92:95]
	v_mfma_f32_16x16x32_bf16 v[88:91], v[170:173], v[226:229], v[88:91]
	v_mfma_f32_16x16x32_bf16 v[76:79], v[158:161], v[234:237], v[76:79]
	v_mfma_f32_16x16x32_bf16 v[72:75], v[170:173], v[234:237], v[72:75]
	v_mfma_f32_16x16x32_bf16 v[124:127], v[162:165], v[214:217], v[124:127]
	v_mfma_f32_16x16x32_bf16 v[120:123], v[174:177], v[214:217], v[120:123]
	v_mfma_f32_16x16x32_bf16 v[108:111], v[162:165], v[222:225], v[108:111]
	v_mfma_f32_16x16x32_bf16 v[104:107], v[174:177], v[222:225], v[104:107]
	v_mfma_f32_16x16x32_bf16 v[92:95], v[162:165], v[230:233], v[92:95]
	v_mfma_f32_16x16x32_bf16 v[88:91], v[174:177], v[230:233], v[88:91]
	v_mfma_f32_16x16x32_bf16 v[76:79], v[162:165], v[238:241], v[76:79]
	v_mfma_f32_16x16x32_bf16 v[72:75], v[174:177], v[238:241], v[72:75]
	s_setprio 0
	s_setprio 1
	v_mfma_f32_16x16x32_bf16 v[116:119], v[194:197], v[210:213], v[116:119]
	v_mfma_f32_16x16x32_bf16 v[112:115], v[202:205], v[210:213], v[112:115]
	v_mfma_f32_16x16x32_bf16 v[100:103], v[194:197], v[218:221], v[100:103]
	v_mfma_f32_16x16x32_bf16 v[96:99], v[202:205], v[218:221], v[96:99]
	v_mfma_f32_16x16x32_bf16 v[84:87], v[194:197], v[226:229], v[84:87]
	v_mfma_f32_16x16x32_bf16 v[80:83], v[202:205], v[226:229], v[80:83]
	v_mfma_f32_16x16x32_bf16 v[68:71], v[194:197], v[234:237], v[68:71]
	v_mfma_f32_16x16x32_bf16 v[64:67], v[202:205], v[234:237], v[64:67]
	v_mfma_f32_16x16x32_bf16 v[116:119], v[198:201], v[214:217], v[116:119]
	v_mfma_f32_16x16x32_bf16 v[112:115], v[206:209], v[214:217], v[112:115]
	v_mfma_f32_16x16x32_bf16 v[100:103], v[198:201], v[222:225], v[100:103]
	v_mfma_f32_16x16x32_bf16 v[96:99], v[206:209], v[222:225], v[96:99]
	v_mfma_f32_16x16x32_bf16 v[84:87], v[198:201], v[230:233], v[84:87]
	v_mfma_f32_16x16x32_bf16 v[80:83], v[206:209], v[230:233], v[80:83]
	v_mfma_f32_16x16x32_bf16 v[68:71], v[198:201], v[238:241], v[68:71]
	v_mfma_f32_16x16x32_bf16 v[64:67], v[206:209], v[238:241], v[64:67]
	s_setprio 0
	s_barrier
; #define PG8_STAGE(bufoff, gbase, voff) do { _Pragma("unroll") for (int _i = 0; _i < 2; ++_i) \
;         __builtin_amdgcn_global_load_lds((const unsigned*)((const char*)(gbase) + (voff)[_i]), (PG8_LAS unsigned*)(lds + (bufoff) + ldsw + _i * 8192), 16, 0, 0); } while (0)
; #define PG8_LDA(dst, b, h) do { _Pragma("unroll") for (int m = 0; m < 4; ++m) _Pragma("unroll") for (int k = 0; k < 2; ++k) dst[m][k] = *(const PG8_LAS bf16x8*)(lds + PG8_SA(b, h) + aoff + m * 2048 + k * 1024); } while (0)
; #define PG8_MMA(ai, bj, At, Bt) do { __builtin_amdgcn_s_setprio(1); _Pragma("unroll") for (int m = 0; m < 4; ++m) _Pragma("unroll") for (int n = 0; n < 2; ++n) _Pragma("unroll") for (int k = 0; k < 2; ++k) \
;         acc[ai][bj][m][n] = __builtin_amdgcn_mfma_f32_16x16x32_bf16(Bt[n][k], At[m][k], acc[ai][bj][m][n], 0, 0, 0); __builtin_amdgcn_s_setprio(0); } while (0)
; #define PG8_WAIT_V(n) asm volatile("s_waitcnt vmcnt(" #n ")" ::: "memory")
; #define PG8_WAIT_L(n) asm volatile("s_waitcnt lgkmcnt(" #n ")" ::: "memory")
; #define PG8_BAR __builtin_amdgcn_s_barrier()
; #define PG8_SCHED __builtin_amdgcn_sched_barrier(0)
; template <class Epi, class Sched, bool ALIGN_EPI = false, bool SP2 = false>
; __device__ __forceinline__ void gemm_phase(PG8_LAS unsigned char* lds, const Gemm g, const Sched& S, const Epi& E) {
;     ...
;             PG8_LDA(At, 1, 1); PG8_STAGE(PG8_SB(1, 0), b3, voffB); PG8_STAGE(PG8_SB(1, 1), b3 + hstepB, voffB); PG8_STAGE(PG8_SA(1, 0), a3, voffA);
;             PG8_WAIT_V(8); PG8_WAIT_L(0); PG8_BAR; PG8_MMA(1, 0, At, B0); PG8_MMA(1, 1, At, B1); PG8_BAR; PG8_SCHED;
	s_mov_b32 m0, s45
	v_lshl_add_u64 v[178:179], v[178:179], 0, s[54:55]
	s_add_u32 s18, s18, 0x100080
	ds_read_b128 v[210:213], v166 offset:49152
	ds_read_b128 v[214:217], v166 offset:50176
	ds_read_b128 v[218:221], v166 offset:51200
	ds_read_b128 v[222:225], v166 offset:52224
	ds_read_b128 v[226:229], v166 offset:53248
	ds_read_b128 v[230:233], v166 offset:54272
	ds_read_b128 v[234:237], v166 offset:55296
	ds_read_b128 v[238:241], v166 offset:56320
	global_load_lds_dwordx4 v[178:179], off
	v_lshl_add_u64 v[178:179], v[188:189], 0, s[54:55]
	s_mov_b32 m0, s46
	s_addc_u32 s19, s19, 0
	global_load_lds_dwordx4 v[178:179], off
	v_lshl_add_u64 v[178:179], s[18:19], 0, v[150:151]
	s_mov_b32 m0, s65
	s_nop 0
	global_load_lds_dwordx4 v[178:179], off
	v_lshl_add_u64 v[178:179], s[18:19], 0, v[152:153]
	s_mov_b32 m0, s72
	s_nop 0
	global_load_lds_dwordx4 v[178:179], off
	v_lshl_add_u64 v[178:179], v[242:243], 0, s[54:55]
	s_mov_b32 m0, s47
	s_nop 0
	global_load_lds_dwordx4 v[178:179], off
	v_lshl_add_u64 v[178:179], v[244:245], 0, s[54:55]
	s_mov_b32 m0, s64
	s_nop 0
	global_load_lds_dwordx4 v[178:179], off
	s_waitcnt vmcnt(8)
	s_waitcnt lgkmcnt(0)
	s_barrier
	s_setprio 1
	s_waitcnt lgkmcnt(0)
	v_mfma_f32_16x16x32_bf16 v[60:63], v[158:161], v[210:213], v[60:63]
	v_mfma_f32_16x16x32_bf16 v[56:59], v[170:173], v[210:213], v[56:59]
	v_mfma_f32_16x16x32_bf16 v[44:47], v[158:161], v[218:221], v[44:47]
	v_mfma_f32_16x16x32_bf16 v[40:43], v[170:173], v[218:221], v[40:43]
	v_mfma_f32_16x16x32_bf16 v[28:31], v[158:161], v[226:229], v[28:31]
	v_mfma_f32_16x16x32_bf16 v[24:27], v[170:173], v[226:229], v[24:27]
	v_mfma_f32_16x16x32_bf16 v[12:15], v[158:161], v[234:237], v[12:15]
	v_mfma_f32_16x16x32_bf16 v[8:11], v[170:173], v[234:237], v[8:11]
	v_mfma_f32_16x16x32_bf16 v[60:63], v[162:165], v[214:217], v[60:63]
	v_mfma_f32_16x16x32_bf16 v[56:59], v[174:177], v[214:217], v[56:59]
	v_mfma_f32_16x16x32_bf16 v[44:47], v[162:165], v[222:225], v[44:47]
	v_mfma_f32_16x16x32_bf16 v[40:43], v[174:177], v[222:225], v[40:43]
	v_mfma_f32_16x16x32_bf16 v[28:31], v[162:165], v[230:233], v[28:31]
	v_mfma_f32_16x16x32_bf16 v[24:27], v[174:177], v[230:233], v[24:27]
	v_mfma_f32_16x16x32_bf16 v[12:15], v[162:165], v[238:241], v[12:15]
	v_mfma_f32_16x16x32_bf16 v[8:11], v[174:177], v[238:241], v[8:11]
	s_setprio 0
	s_setprio 1
	v_mfma_f32_16x16x32_bf16 v[52:55], v[194:197], v[210:213], v[52:55]
	v_mfma_f32_16x16x32_bf16 v[48:51], v[202:205], v[210:213], v[48:51]
	v_mfma_f32_16x16x32_bf16 v[36:39], v[194:197], v[218:221], v[36:39]
	v_mfma_f32_16x16x32_bf16 v[32:35], v[202:205], v[218:221], v[32:35]
	v_mfma_f32_16x16x32_bf16 v[20:23], v[194:197], v[226:229], v[20:23]
	v_mfma_f32_16x16x32_bf16 v[16:19], v[202:205], v[226:229], v[16:19]
	v_mfma_f32_16x16x32_bf16 v[4:7], v[194:197], v[234:237], v[4:7]
	v_mfma_f32_16x16x32_bf16 v[0:3], v[202:205], v[234:237], v[0:3]
	v_mfma_f32_16x16x32_bf16 v[52:55], v[198:201], v[214:217], v[52:55]
	v_mfma_f32_16x16x32_bf16 v[48:51], v[206:209], v[214:217], v[48:51]
	v_mfma_f32_16x16x32_bf16 v[36:39], v[198:201], v[222:225], v[36:39]
	v_mfma_f32_16x16x32_bf16 v[32:35], v[206:209], v[222:225], v[32:35]
	v_mfma_f32_16x16x32_bf16 v[20:23], v[198:201], v[230:233], v[20:23]
	v_mfma_f32_16x16x32_bf16 v[16:19], v[206:209], v[230:233], v[16:19]
	v_mfma_f32_16x16x32_bf16 v[4:7], v[198:201], v[238:241], v[4:7]
	v_mfma_f32_16x16x32_bf16 v[0:3], v[206:209], v[238:241], v[0:3]
	s_setprio 0
	s_barrier
	s_add_i32 s43, s43, 2
	s_add_u32 vcc_lo, vcc_lo, 0x100
	s_addc_u32 vcc_hi, vcc_hi, 0
	s_add_u32 s27, s27, 0x100
	s_addc_u32 s42, s42, 0
	s_cmp_gt_u32 s43, 61
	s_cbranch_scc0 .LBB0_2351
	s_and_b64 vcc, exec, s[4:5]
	s_cbranch_vccz .LBB0_2354
	s_barrier

; #define PG8_STAGE(bufoff, gbase, voff) do { _Pragma("unroll") for (int _i = 0; _i < 2; ++_i) \
;         __builtin_amdgcn_global_load_lds((const unsigned*)((const char*)(gbase) + (voff)[_i]), (PG8_LAS unsigned*)(lds + (bufoff) + ldsw + _i * 8192), 16, 0, 0); } while (0)
; #define PG8_LDA(dst, b, h) do { _Pragma("unroll") for (int m = 0; m < 4; ++m) _Pragma("unroll") for (int k = 0; k < 2; ++k) dst[m][k] = *(const PG8_LAS bf16x8*)(lds + PG8_SA(b, h) + aoff + m * 2048 + k * 1024); } while (0)
; #define PG8_LDB(dst, b, h) do { _Pragma("unroll") for (int n = 0; n < 2; ++n) _Pragma("unroll") for (int k = 0; k < 2; ++k) dst[n][k] = *(const PG8_LAS bf16x8*)(lds + PG8_SB(b, h) + boff + n * 2048 + k * 1024); } while (0)
; #define PG8_MMA(ai, bj, At, Bt) do { __builtin_amdgcn_s_setprio(1); _Pragma("unroll") for (int m = 0; m < 4; ++m) _Pragma("unroll") for (int n = 0; n < 2; ++n) _Pragma("unroll") for (int k = 0; k < 2; ++k) \
;         acc[ai][bj][m][n] = __builtin_amdgcn_mfma_f32_16x16x32_bf16(Bt[n][k], At[m][k], acc[ai][bj][m][n], 0, 0, 0); __builtin_amdgcn_s_setprio(0); } while (0)
; #define PG8_WAIT_V(n) asm volatile("s_waitcnt vmcnt(" #n ")" ::: "memory")
; #define PG8_WAIT_L(n) asm volatile("s_waitcnt lgkmcnt(" #n ")" ::: "memory")
; #define PG8_BAR __builtin_amdgcn_s_barrier()
; #define PG8_SCHED __builtin_amdgcn_sched_barrier(0)
; template <class Epi, class Sched, bool ALIGN_EPI = false, bool SP2 = false>
; __device__ __forceinline__ void gemm_phase(PG8_LAS unsigned char* lds, const Gemm g, const Sched& S, const Epi& E) {
;     ...
;         PG8_STAGE(PG8_SB(1, 0), cB + kstep, voffB); PG8_STAGE(PG8_SA(1, 0), cA + kstep, voffA); PG8_STAGE(PG8_SB(1, 1), cB + hstepB + kstep, voffB);
;         PG8_WAIT_V(6); PG8_BAR;
;     ...
;             PG8_LDB(B0, 0, 0); PG8_LDB(B1, 0, 1); PG8_SCHED; PG8_LDA(At, 0, 0); PG8_STAGE(PG8_SA(1, 1), a1 + hstepA, voffA);
;             PG8_WAIT_V(8); PG8_WAIT_L(0); PG8_BAR; PG8_MMA(0, 0, At, B0); PG8_MMA(0, 1, At, B1); PG8_BAR; PG8_SCHED;
;             PG8_LDA(At, 0, 1); PG8_STAGE(PG8_SB(0, 0), b2, voffB); PG8_STAGE(PG8_SB(0, 1), b2 + hstepB, voffB); PG8_STAGE(PG8_SA(0, 0), a2, voffA);
.LBB0_2409:
	s_lshl_b32 s2, s2, 5
	s_and_b32 s27, s2, 0x60
	s_lshl_b32 s4, s20, 13
	s_lshl_b32 s5, s27, 7
	s_add_i32 s41, s21, 0x18000
	s_add_i32 s42, s21, 0x1a000
	v_lshl_add_u64 v[64:65], v[0:1], 0, s[54:55]
	s_mov_b32 m0, s41
	s_add_u32 s2, s58, 0x10000080
	s_waitcnt vmcnt(2)
	s_barrier
	global_load_lds_dwordx4 v[64:65], off
	v_lshl_add_u64 v[66:67], v[2:3], 0, s[54:55]
	s_mov_b32 m0, s42
	s_addc_u32 s3, s59, 0
	s_add_i32 s43, s21, 0x8000
	s_add_i32 s44, s21, 0xa000
	global_load_lds_dwordx4 v[66:67], off
	v_lshl_add_u64 v[68:69], s[2:3], 0, v[16:17]
	s_mov_b32 m0, s43
	v_lshl_add_u64 v[70:71], s[2:3], 0, v[4:5]
	s_add_u32 s2, s0, 0x100080
	global_load_lds_dwordx4 v[68:69], off
	s_mov_b32 m0, s44
	s_addc_u32 s3, s1, 0
	s_add_i32 s45, s21, 0x1c000
	global_load_lds_dwordx4 v[70:71], off
	v_lshl_add_u64 v[72:73], s[2:3], 0, v[16:17]
	s_mov_b32 m0, s45
	s_add_i32 s46, s21, 0x1e000
	global_load_lds_dwordx4 v[72:73], off
	v_lshl_add_u64 v[74:75], s[2:3], 0, v[4:5]
	s_mov_b32 m0, s46
	s_add_u32 s10, s58, 0x10000100
	global_load_lds_dwordx4 v[74:75], off
	s_addc_u32 s11, s59, 0
	s_add_u32 s2, s58, 0x10000180
	s_addc_u32 s3, s59, 0
	v_bfe_u32 v76, v20, 4, 2
	s_add_u32 s56, s58, 0x10100080
	v_and_b32_e32 v77, 15, v20
	v_lshlrev_b32_e32 v21, 4, v76
	v_lshlrev_b32_e32 v20, 2, v20
	s_addc_u32 s57, s59, 0
	s_add_i32 s63, s21, 0xc000
	s_add_i32 s62, s21, 0xe000
	v_lshl_or_b32 v21, v77, 6, v21
	v_and_b32_e32 v20, 32, v20
	s_add_u32 s16, s0, 0x100100
	v_bitop3_b32 v122, v21, s5, v20 bitop3:0xde
	s_addc_u32 s17, s1, 0
	v_or_b32_e32 v178, 0x10000, v122
	s_add_u32 s8, s58, 0x10100100
	v_or_b32_e32 v202, 0x10400, v122
	v_or_b32_e32 v204, 0x10c00, v122
	v_or_b32_e32 v206, 0x14800, v122
	v_bitop3_b32 v131, v21, s4, v20 bitop3:0xde
	s_waitcnt vmcnt(6)
	s_barrier
	v_or_b32_e32 v179, 0x14000, v122
	s_addc_u32 s9, s59, 0
	v_or_b32_e32 v203, 0x10800, v122
	ds_read_b128 v[20:23], v202
	ds_read_b128 v[24:27], v203
	ds_read_b128 v[28:31], v178
	ds_read_b128 v[32:35], v179
	v_or_b32_e32 v205, 0x14400, v122
	ds_read_b128 v[36:39], v204
	ds_read_b128 v[40:43], v205
	v_or_b32_e32 v207, 0x14c00, v122
	ds_read_b128 v[44:47], v206
	ds_read_b128 v[48:51], v207
	s_add_u32 s4, s0, 0x100180
	s_addc_u32 s5, s1, 0
	s_add_u32 s0, s58, 0x10100180
	s_addc_u32 s1, s59, 0
	v_or_b32_e32 v188, 0x18000, v122
	v_or_b32_e32 v189, 0x1c000, v122
	s_cmpk_gt_u32 s47, 0xff
	s_mov_b32 m0, s63
	v_lshl_add_u64 v[98:99], s[56:57], 0, v[16:17]
	ds_read_b128 v[52:55], v131
	ds_read_b128 v[56:59], v131 offset:1024
	ds_read_b128 v[60:63], v131 offset:2048
	ds_read_b128 v[78:81], v131 offset:3072
	ds_read_b128 v[82:85], v131 offset:4096
	ds_read_b128 v[86:89], v131 offset:5120
	ds_read_b128 v[90:93], v131 offset:6144
	ds_read_b128 v[94:97], v131 offset:7168
	global_load_lds_dwordx4 v[98:99], off
	v_lshl_add_u64 v[98:99], s[56:57], 0, v[4:5]
	s_mov_b32 m0, s62
	s_nop 0
	global_load_lds_dwordx4 v[98:99], off
	s_waitcnt vmcnt(8)
	s_waitcnt lgkmcnt(0)
	s_barrier
	s_setprio 1
	s_waitcnt lgkmcnt(0)
	v_mfma_f32_16x16x32_bf16 v[98:101], v[28:31], v[52:55], 0
	v_mfma_f32_16x16x32_bf16 v[102:105], v[24:27], v[52:55], 0
	v_mfma_f32_16x16x32_bf16 v[106:109], v[28:31], v[60:63], 0
	v_mfma_f32_16x16x32_bf16 v[110:113], v[24:27], v[60:63], 0
	v_mfma_f32_16x16x32_bf16 v[114:117], v[28:31], v[82:85], 0
	v_mfma_f32_16x16x32_bf16 v[118:121], v[24:27], v[82:85], 0
	v_mfma_f32_16x16x32_bf16 v[28:31], v[28:31], v[90:93], 0
	v_mfma_f32_16x16x32_bf16 v[24:27], v[24:27], v[90:93], 0
	v_mfma_f32_16x16x32_bf16 v[98:101], v[20:23], v[56:59], v[98:101]
	v_mfma_f32_16x16x32_bf16 v[106:109], v[20:23], v[78:81], v[106:109]
	v_mfma_f32_16x16x32_bf16 v[114:117], v[20:23], v[86:89], v[114:117]
	v_mfma_f32_16x16x32_bf16 v[20:23], v[20:23], v[94:97], v[28:31]
	v_mfma_f32_16x16x32_bf16 v[24:27], v[36:39], v[94:97], v[24:27]
	v_mfma_f32_16x16x32_bf16 v[102:105], v[36:39], v[56:59], v[102:105]
	v_mfma_f32_16x16x32_bf16 v[110:113], v[36:39], v[78:81], v[110:113]
	v_mfma_f32_16x16x32_bf16 v[118:121], v[36:39], v[86:89], v[118:121]
	s_setprio 0
	s_setprio 1
	v_mfma_f32_16x16x32_bf16 v[28:31], v[32:35], v[52:55], 0
	v_mfma_f32_16x16x32_bf16 v[36:39], v[44:47], v[52:55], 0
	v_mfma_f32_16x16x32_bf16 v[28:31], v[40:43], v[56:59], v[28:31]
	v_mfma_f32_16x16x32_bf16 v[36:39], v[48:51], v[56:59], v[36:39]
	v_mfma_f32_16x16x32_bf16 v[52:55], v[32:35], v[60:63], 0
	v_mfma_f32_16x16x32_bf16 v[56:59], v[44:47], v[60:63], 0
	v_mfma_f32_16x16x32_bf16 v[60:63], v[32:35], v[82:85], 0
	v_mfma_f32_16x16x32_bf16 v[32:35], v[32:35], v[90:93], 0
	v_mfma_f32_16x16x32_bf16 v[52:55], v[40:43], v[78:81], v[52:55]
	v_mfma_f32_16x16x32_bf16 v[60:63], v[40:43], v[86:89], v[60:63]
	v_mfma_f32_16x16x32_bf16 v[32:35], v[40:43], v[94:97], v[32:35]
	v_mfma_f32_16x16x32_bf16 v[40:43], v[44:47], v[90:93], 0
	v_mfma_f32_16x16x32_bf16 v[56:59], v[48:51], v[78:81], v[56:59]
	v_mfma_f32_16x16x32_bf16 v[78:81], v[44:47], v[82:85], 0
	v_mfma_f32_16x16x32_bf16 v[40:43], v[48:51], v[94:97], v[40:43]
	v_mfma_f32_16x16x32_bf16 v[78:81], v[48:51], v[86:89], v[78:81]
	s_setprio 0
	s_barrier
	s_mov_b64 s[48:49], 0x100
	s_mov_b32 m0, s25
	v_lshl_add_u64 v[44:45], v[0:1], 0, s[48:49]
	global_load_lds_dwordx4 v[44:45], off
	v_lshl_add_u64 v[44:45], v[2:3], 0, s[48:49]
	s_mov_b32 m0, s35
	s_nop 0
	global_load_lds_dwordx4 v[44:45], off
	v_lshl_add_u64 v[44:45], s[16:17], 0, v[16:17]
	s_mov_b32 m0, s36
	s_nop 0
	global_load_lds_dwordx4 v[44:45], off
	v_lshl_add_u64 v[44:45], s[16:17], 0, v[4:5]
	s_mov_b32 m0, s38
	s_nop 0
	global_load_lds_dwordx4 v[44:45], off
	v_lshl_add_u64 v[44:45], s[10:11], 0, v[16:17]
	s_mov_b32 m0, s21
	s_nop 0
	global_load_lds_dwordx4 v[44:45], off
	v_lshl_add_u64 v[44:45], s[10:11], 0, v[4:5]
	s_mov_b32 m0, s40
	s_nop 0
	global_load_lds_dwordx4 v[44:45], off
	s_waitcnt vmcnt(8)
	s_waitcnt lgkmcnt(0)
	s_barrier
; #define PG8_STAGE(bufoff, gbase, voff) do { _Pragma("unroll") for (int _i = 0; _i < 2; ++_i) \
;         __builtin_amdgcn_global_load_lds((const unsigned*)((const char*)(gbase) + (voff)[_i]), (PG8_LAS unsigned*)(lds + (bufoff) + ldsw + _i * 8192), 16, 0, 0); } while (0)
; #define PG8_LDA(dst, b, h) do { _Pragma("unroll") for (int m = 0; m < 4; ++m) _Pragma("unroll") for (int k = 0; k < 2; ++k) dst[m][k] = *(const PG8_LAS bf16x8*)(lds + PG8_SA(b, h) + aoff + m * 2048 + k * 1024); } while (0)
; #define PG8_LDB(dst, b, h) do { _Pragma("unroll") for (int n = 0; n < 2; ++n) _Pragma("unroll") for (int k = 0; k < 2; ++k) dst[n][k] = *(const PG8_LAS bf16x8*)(lds + PG8_SB(b, h) + boff + n * 2048 + k * 1024); } while (0)
; #define PG8_MMA(ai, bj, At, Bt) do { __builtin_amdgcn_s_setprio(1); _Pragma("unroll") for (int m = 0; m < 4; ++m) _Pragma("unroll") for (int n = 0; n < 2; ++n) _Pragma("unroll") for (int k = 0; k < 2; ++k) \
;         acc[ai][bj][m][n] = __builtin_amdgcn_mfma_f32_16x16x32_bf16(Bt[n][k], At[m][k], acc[ai][bj][m][n], 0, 0, 0); __builtin_amdgcn_s_setprio(0); } while (0)
; #define PG8_WAIT_V(n) asm volatile("s_waitcnt vmcnt(" #n ")" ::: "memory")
; #define PG8_WAIT_L(n) asm volatile("s_waitcnt lgkmcnt(" #n ")" ::: "memory")
; #define PG8_BAR __builtin_amdgcn_s_barrier()
; #define PG8_SCHED __builtin_amdgcn_sched_barrier(0)
; template <class Epi, class Sched, bool ALIGN_EPI = false, bool SP2 = false>
; __device__ __forceinline__ void gemm_phase(PG8_LAS unsigned char* lds, const Gemm g, const Sched& S, const Epi& E) {
;     ...
;             PG8_LDB(B0, 0, 0); PG8_LDB(B1, 0, 1); PG8_SCHED; PG8_LDA(At, 0, 0); PG8_STAGE(PG8_SA(1, 1), a1 + hstepA, voffA);
;     ...
;             PG8_WAIT_V(8); PG8_WAIT_L(0); PG8_BAR; PG8_MMA(1, 0, At, B0); PG8_MMA(1, 1, At, B1); PG8_BAR; PG8_SCHED;
;             PG8_LDB(B0, 1, 0); PG8_LDB(B1, 1, 1); PG8_SCHED; PG8_LDA(At, 1, 0); PG8_STAGE(PG8_SA(0, 1), a2 + hstepA, voffA);
;             PG8_WAIT_V(8); PG8_WAIT_L(0); PG8_BAR; PG8_MMA(0, 0, At, B0); PG8_MMA(0, 1, At, B1); PG8_BAR; PG8_SCHED;
;             PG8_LDA(At, 1, 1); PG8_STAGE(PG8_SB(1, 0), b3, voffB); PG8_STAGE(PG8_SB(1, 1), b3 + hstepB, voffB); PG8_STAGE(PG8_SA(1, 0), a3, voffA);
;             PG8_WAIT_V(8); PG8_WAIT_L(0); PG8_BAR; PG8_MMA(1, 0, At, B0); PG8_MMA(1, 1, At, B1); PG8_BAR; PG8_SCHED;
	s_setprio 1
	s_setprio 0
	s_setprio 1
	s_setprio 0
	s_barrier
	v_or_b32_e32 v208, 0x18400, v122
	v_or_b32_e32 v210, 0x18c00, v122
	v_or_b32_e32 v212, 0x1c800, v122
	v_or_b32_e32 v209, 0x18800, v122
	ds_read_b128 v[44:47], v208
	ds_read_b128 v[48:51], v209
	ds_read_b128 v[82:85], v188
	ds_read_b128 v[86:89], v189
	v_or_b32_e32 v211, 0x1c400, v122
	ds_read_b128 v[90:93], v210
	ds_read_b128 v[94:97], v211
	v_or_b32_e32 v213, 0x1cc00, v122
	ds_read_b128 v[122:125], v212
	ds_read_b128 v[150:153], v213
	s_mov_b32 m0, s37
	v_lshl_add_u64 v[126:127], s[8:9], 0, v[16:17]
	ds_read_b128 v[154:157], v131 offset:32768
	ds_read_b128 v[158:161], v131 offset:33792
	ds_read_b128 v[162:165], v131 offset:34816
	ds_read_b128 v[166:169], v131 offset:35840
	ds_read_b128 v[170:173], v131 offset:36864
	ds_read_b128 v[174:177], v131 offset:37888
	ds_read_b128 v[194:197], v131 offset:38912
	ds_read_b128 v[198:201], v131 offset:39936
	global_load_lds_dwordx4 v[126:127], off
	v_lshl_add_u64 v[126:127], s[8:9], 0, v[4:5]
	s_mov_b32 m0, s39
	s_nop 0
	global_load_lds_dwordx4 v[126:127], off
	s_waitcnt vmcnt(8)
	s_waitcnt lgkmcnt(0)
	s_barrier
	s_setprio 1
	s_waitcnt lgkmcnt(0)
	v_mfma_f32_16x16x32_bf16 v[20:23], v[82:85], v[194:197], v[20:23]
	v_mfma_f32_16x16x32_bf16 v[24:27], v[48:51], v[194:197], v[24:27]
	v_mfma_f32_16x16x32_bf16 v[98:101], v[82:85], v[154:157], v[98:101]
	v_mfma_f32_16x16x32_bf16 v[102:105], v[48:51], v[154:157], v[102:105]
	v_mfma_f32_16x16x32_bf16 v[106:109], v[82:85], v[162:165], v[106:109]
	v_mfma_f32_16x16x32_bf16 v[110:113], v[48:51], v[162:165], v[110:113]
	v_mfma_f32_16x16x32_bf16 v[114:117], v[82:85], v[170:173], v[114:117]
	v_mfma_f32_16x16x32_bf16 v[118:121], v[48:51], v[170:173], v[118:121]
	v_mfma_f32_16x16x32_bf16 v[20:23], v[44:47], v[198:201], v[20:23]
	v_mfma_f32_16x16x32_bf16 v[24:27], v[90:93], v[198:201], v[24:27]
	v_mfma_f32_16x16x32_bf16 v[98:101], v[44:47], v[158:161], v[98:101]
	v_mfma_f32_16x16x32_bf16 v[102:105], v[90:93], v[158:161], v[102:105]
	v_mfma_f32_16x16x32_bf16 v[106:109], v[44:47], v[166:169], v[106:109]
	v_mfma_f32_16x16x32_bf16 v[110:113], v[90:93], v[166:169], v[110:113]
	v_mfma_f32_16x16x32_bf16 v[114:117], v[44:47], v[174:177], v[114:117]
	v_mfma_f32_16x16x32_bf16 v[118:121], v[90:93], v[174:177], v[118:121]
	s_setprio 0
	s_setprio 1
	v_mfma_f32_16x16x32_bf16 v[28:31], v[86:89], v[154:157], v[28:31]
	v_mfma_f32_16x16x32_bf16 v[36:39], v[122:125], v[154:157], v[36:39]
	v_mfma_f32_16x16x32_bf16 v[44:47], v[86:89], v[162:165], v[52:55]
	v_mfma_f32_16x16x32_bf16 v[48:51], v[122:125], v[162:165], v[56:59]
	v_mfma_f32_16x16x32_bf16 v[52:55], v[86:89], v[170:173], v[60:63]
	v_mfma_f32_16x16x32_bf16 v[56:59], v[122:125], v[170:173], v[78:81]
	v_mfma_f32_16x16x32_bf16 v[32:35], v[86:89], v[194:197], v[32:35]
	v_mfma_f32_16x16x32_bf16 v[40:43], v[122:125], v[194:197], v[40:43]
	v_mfma_f32_16x16x32_bf16 v[28:31], v[94:97], v[158:161], v[28:31]
	v_mfma_f32_16x16x32_bf16 v[36:39], v[150:153], v[158:161], v[36:39]
	v_mfma_f32_16x16x32_bf16 v[44:47], v[94:97], v[166:169], v[44:47]
	v_mfma_f32_16x16x32_bf16 v[48:51], v[150:153], v[166:169], v[48:51]
	v_mfma_f32_16x16x32_bf16 v[52:55], v[94:97], v[174:177], v[52:55]
	v_mfma_f32_16x16x32_bf16 v[56:59], v[150:153], v[174:177], v[56:59]
	v_mfma_f32_16x16x32_bf16 v[32:35], v[94:97], v[198:201], v[32:35]
	v_mfma_f32_16x16x32_bf16 v[40:43], v[150:153], v[198:201], v[40:43]
	s_setprio 0
	s_barrier
	s_mov_b64 s[8:9], 0x180
	s_mov_b32 m0, s41
	v_lshl_add_u64 v[60:61], v[0:1], 0, s[8:9]
	global_load_lds_dwordx4 v[60:61], off
	v_lshl_add_u64 v[60:61], v[2:3], 0, s[8:9]
	s_mov_b32 m0, s42
	s_nop 0
	global_load_lds_dwordx4 v[60:61], off
	v_lshl_add_u64 v[60:61], s[4:5], 0, v[16:17]
	s_mov_b32 m0, s45
	s_nop 0
	global_load_lds_dwordx4 v[60:61], off
	v_lshl_add_u64 v[60:61], s[4:5], 0, v[4:5]
	s_mov_b32 m0, s46
	s_nop 0
	global_load_lds_dwordx4 v[60:61], off
	v_lshl_add_u64 v[60:61], s[2:3], 0, v[16:17]
	s_mov_b32 m0, s43
	s_nop 0
	global_load_lds_dwordx4 v[60:61], off
	v_lshl_add_u64 v[60:61], s[2:3], 0, v[4:5]
	s_mov_b32 m0, s44
	s_nop 0
	global_load_lds_dwordx4 v[60:61], off
	s_waitcnt vmcnt(8)
	s_waitcnt lgkmcnt(0)
	s_barrier
	s_setprio 1
	s_setprio 0
	s_setprio 1
	s_setprio 0
	s_barrier
	ds_read_b128 v[60:63], v202
	ds_read_b128 v[78:81], v203
	ds_read_b128 v[82:85], v178
	ds_read_b128 v[86:89], v179
	ds_read_b128 v[90:93], v204
	ds_read_b128 v[94:97], v205
	ds_read_b128 v[122:125], v206
	ds_read_b128 v[150:153], v207
	s_mov_b32 m0, s63
	v_lshl_add_u64 v[16:17], s[0:1], 0, v[16:17]
	ds_read_b128 v[154:157], v131
	ds_read_b128 v[158:161], v131 offset:1024
	ds_read_b128 v[162:165], v131 offset:2048
	ds_read_b128 v[166:169], v131 offset:3072
	ds_read_b128 v[170:173], v131 offset:4096
	ds_read_b128 v[174:177], v131 offset:5120
	ds_read_b128 v[194:197], v131 offset:6144
	ds_read_b128 v[198:201], v131 offset:7168
	global_load_lds_dwordx4 v[16:17], off
	v_lshl_add_u64 v[4:5], s[0:1], 0, v[4:5]
	s_mov_b32 m0, s62
	s_nop 0
	global_load_lds_dwordx4 v[4:5], off
	s_waitcnt vmcnt(8)
	s_waitcnt lgkmcnt(0)
	s_barrier
; #define PG8_STAGE(bufoff, gbase, voff) do { _Pragma("unroll") for (int _i = 0; _i < 2; ++_i) \
;         __builtin_amdgcn_global_load_lds((const unsigned*)((const char*)(gbase) + (voff)[_i]), (PG8_LAS unsigned*)(lds + (bufoff) + ldsw + _i * 8192), 16, 0, 0); } while (0)
; #define PG8_LDA(dst, b, h) do { _Pragma("unroll") for (int m = 0; m < 4; ++m) _Pragma("unroll") for (int k = 0; k < 2; ++k) dst[m][k] = *(const PG8_LAS bf16x8*)(lds + PG8_SA(b, h) + aoff + m * 2048 + k * 1024); } while (0)
; #define PG8_LDB(dst, b, h) do { _Pragma("unroll") for (int n = 0; n < 2; ++n) _Pragma("unroll") for (int k = 0; k < 2; ++k) dst[n][k] = *(const PG8_LAS bf16x8*)(lds + PG8_SB(b, h) + boff + n * 2048 + k * 1024); } while (0)
; #define PG8_MMA(ai, bj, At, Bt) do { __builtin_amdgcn_s_setprio(1); _Pragma("unroll") for (int m = 0; m < 4; ++m) _Pragma("unroll") for (int n = 0; n < 2; ++n) _Pragma("unroll") for (int k = 0; k < 2; ++k) \
;         acc[ai][bj][m][n] = __builtin_amdgcn_mfma_f32_16x16x32_bf16(Bt[n][k], At[m][k], acc[ai][bj][m][n], 0, 0, 0); __builtin_amdgcn_s_setprio(0); } while (0)
; #define PG8_WAIT_V(n) asm volatile("s_waitcnt vmcnt(" #n ")" ::: "memory")
; #define PG8_WAIT_L(n) asm volatile("s_waitcnt lgkmcnt(" #n ")" ::: "memory")
; #define PG8_BAR __builtin_amdgcn_s_barrier()
; template <class Epi, class Sched, bool ALIGN_EPI = false, bool SP2 = false>
; __device__ __forceinline__ void gemm_phase(PG8_LAS unsigned char* lds, const Gemm g, const Sched& S, const Epi& E) {
;     ...
;             PG8_WAIT_V(8); PG8_WAIT_L(0); PG8_BAR; PG8_MMA(0, 0, At, B0); PG8_MMA(0, 1, At, B1); PG8_BAR; PG8_SCHED;
;             PG8_LDA(At, 0, 1); PG8_STAGE(PG8_SB(0, 0), b2, voffB); PG8_STAGE(PG8_SB(0, 1), b2 + hstepB, voffB); PG8_STAGE(PG8_SA(0, 0), a2, voffA);
;             PG8_WAIT_V(8); PG8_WAIT_L(0); PG8_BAR; PG8_MMA(1, 0, At, B0); PG8_MMA(1, 1, At, B1); PG8_BAR; PG8_SCHED;
;             PG8_LDB(B0, 1, 0); PG8_LDB(B1, 1, 1); PG8_SCHED; PG8_LDA(At, 1, 0); PG8_STAGE(PG8_SA(0, 1), a2 + hstepA, voffA);
;             PG8_WAIT_V(8); PG8_WAIT_L(0); PG8_BAR; PG8_MMA(0, 0, At, B0); PG8_MMA(0, 1, At, B1); PG8_BAR; PG8_SCHED;
;             PG8_LDA(At, 1, 1); PG8_STAGE(PG8_SB(1, 0), b3, voffB); PG8_STAGE(PG8_SB(1, 1), b3 + hstepB, voffB); PG8_STAGE(PG8_SA(1, 0), a3, voffA);
;             PG8_WAIT_V(8); PG8_WAIT_L(0); PG8_BAR; PG8_MMA(1, 0, At, B0); PG8_MMA(1, 1, At, B1); PG8_BAR; PG8_SCHED;
	s_setprio 1
	s_waitcnt lgkmcnt(0)
	v_mfma_f32_16x16x32_bf16 v[98:101], v[82:85], v[154:157], v[98:101]
	v_mfma_f32_16x16x32_bf16 v[106:109], v[82:85], v[162:165], v[106:109]
	v_mfma_f32_16x16x32_bf16 v[114:117], v[82:85], v[170:173], v[114:117]
	v_mfma_f32_16x16x32_bf16 v[20:23], v[82:85], v[194:197], v[20:23]
	v_mfma_f32_16x16x32_bf16 v[98:101], v[60:63], v[158:161], v[98:101]
	v_mfma_f32_16x16x32_bf16 v[102:105], v[78:81], v[154:157], v[102:105]
	v_mfma_f32_16x16x32_bf16 v[106:109], v[60:63], v[166:169], v[106:109]
	v_mfma_f32_16x16x32_bf16 v[110:113], v[78:81], v[162:165], v[110:113]
	v_mfma_f32_16x16x32_bf16 v[114:117], v[60:63], v[174:177], v[114:117]
	v_mfma_f32_16x16x32_bf16 v[118:121], v[78:81], v[170:173], v[118:121]
	v_mfma_f32_16x16x32_bf16 v[60:63], v[60:63], v[198:201], v[20:23]
	v_mfma_f32_16x16x32_bf16 v[20:23], v[78:81], v[194:197], v[24:27]
	v_mfma_f32_16x16x32_bf16 v[102:105], v[90:93], v[158:161], v[102:105]
	v_mfma_f32_16x16x32_bf16 v[110:113], v[90:93], v[166:169], v[110:113]
	v_mfma_f32_16x16x32_bf16 v[118:121], v[90:93], v[174:177], v[118:121]
	v_mfma_f32_16x16x32_bf16 v[78:81], v[90:93], v[198:201], v[20:23]
	s_setprio 0
	s_setprio 1
	v_mfma_f32_16x16x32_bf16 v[20:23], v[86:89], v[154:157], v[28:31]
	v_mfma_f32_16x16x32_bf16 v[82:85], v[94:97], v[158:161], v[20:23]
	v_mfma_f32_16x16x32_bf16 v[20:23], v[122:125], v[154:157], v[36:39]
	v_mfma_f32_16x16x32_bf16 v[36:39], v[150:153], v[158:161], v[20:23]
	v_mfma_f32_16x16x32_bf16 v[20:23], v[86:89], v[162:165], v[44:47]
	v_mfma_f32_16x16x32_bf16 v[44:47], v[94:97], v[166:169], v[20:23]
	v_mfma_f32_16x16x32_bf16 v[20:23], v[122:125], v[162:165], v[48:51]
	v_mfma_f32_16x16x32_bf16 v[48:51], v[150:153], v[166:169], v[20:23]
	v_mfma_f32_16x16x32_bf16 v[20:23], v[86:89], v[170:173], v[52:55]
	v_mfma_f32_16x16x32_bf16 v[90:93], v[94:97], v[174:177], v[20:23]
	v_mfma_f32_16x16x32_bf16 v[20:23], v[122:125], v[170:173], v[56:59]
	v_mfma_f32_16x16x32_bf16 v[154:157], v[150:153], v[174:177], v[20:23]
	v_mfma_f32_16x16x32_bf16 v[20:23], v[86:89], v[194:197], v[32:35]
	v_mfma_f32_16x16x32_bf16 v[32:35], v[94:97], v[198:201], v[20:23]
	v_mfma_f32_16x16x32_bf16 v[20:23], v[122:125], v[194:197], v[40:43]
	v_mfma_f32_16x16x32_bf16 v[40:43], v[150:153], v[198:201], v[20:23]
	s_setprio 0
	s_barrier
	s_mov_b32 m0, s25
	s_nop 0
	global_load_lds_dwordx4 v[0:1], off
	s_mov_b32 m0, s35
	s_nop 0
	global_load_lds_dwordx4 v[2:3], off
	s_mov_b32 m0, s36
	s_nop 0
	global_load_lds_dwordx4 v[6:7], off
	s_mov_b32 m0, s38
	s_nop 0
	global_load_lds_dwordx4 v[10:11], off
	s_mov_b32 m0, s21
	s_nop 0
	global_load_lds_dwordx4 v[14:15], off
	s_mov_b32 m0, s40
	s_nop 0
	global_load_lds_dwordx4 v[18:19], off
	s_waitcnt vmcnt(8)
	s_waitcnt lgkmcnt(0)
	s_barrier
	s_setprio 1
	s_setprio 0
	s_setprio 1
	s_setprio 0
	s_barrier
	ds_read_b128 v[0:3], v208
	ds_read_b128 v[52:55], v209
	ds_read_b128 v[56:59], v188
	ds_read_b128 v[86:89], v189
	ds_read_b128 v[94:97], v210
	ds_read_b128 v[122:125], v211
	ds_read_b128 v[150:153], v212
	ds_read_b128 v[158:161], v213
	s_mov_b32 m0, s37
	ds_read_b128 v[162:165], v131 offset:32768
	ds_read_b128 v[166:169], v131 offset:33792
	ds_read_b128 v[170:173], v131 offset:34816
	ds_read_b128 v[174:177], v131 offset:35840
	ds_read_b128 v[194:197], v131 offset:36864
	ds_read_b128 v[198:201], v131 offset:37888
	ds_read_b128 v[202:205], v131 offset:38912
	ds_read_b128 v[206:209], v131 offset:39936
	global_load_lds_dwordx4 v[8:9], off
	s_mov_b32 m0, s39
	s_nop 0
	global_load_lds_dwordx4 v[12:13], off
	s_waitcnt vmcnt(8)
	s_waitcnt lgkmcnt(0)
	s_barrier
	s_setprio 1
	s_waitcnt lgkmcnt(0)
	v_mfma_f32_16x16x32_bf16 v[4:7], v[56:59], v[162:165], v[98:101]
	v_mfma_f32_16x16x32_bf16 v[20:23], v[0:3], v[166:169], v[4:7]
	v_mfma_f32_16x16x32_bf16 v[4:7], v[52:55], v[162:165], v[102:105]
	v_mfma_f32_16x16x32_bf16 v[28:31], v[94:97], v[166:169], v[4:7]
	v_mfma_f32_16x16x32_bf16 v[4:7], v[56:59], v[170:173], v[106:109]
	v_mfma_f32_16x16x32_bf16 v[12:15], v[0:3], v[174:177], v[4:7]
	v_mfma_f32_16x16x32_bf16 v[4:7], v[52:55], v[170:173], v[110:113]
	v_mfma_f32_16x16x32_bf16 v[8:11], v[52:55], v[194:197], v[118:121]
	v_mfma_f32_16x16x32_bf16 v[24:27], v[94:97], v[174:177], v[4:7]
	v_mfma_f32_16x16x32_bf16 v[4:7], v[56:59], v[194:197], v[114:117]
	v_mfma_f32_16x16x32_bf16 v[16:19], v[94:97], v[198:201], v[8:11]
	v_mfma_f32_16x16x32_bf16 v[8:11], v[56:59], v[202:205], v[60:63]
	v_mfma_f32_16x16x32_bf16 v[4:7], v[0:3], v[198:201], v[4:7]
	v_mfma_f32_16x16x32_bf16 v[0:3], v[0:3], v[206:209], v[8:11]
	v_mfma_f32_16x16x32_bf16 v[8:11], v[52:55], v[202:205], v[78:81]
	v_mfma_f32_16x16x32_bf16 v[8:11], v[94:97], v[206:209], v[8:11]
	s_setprio 0
	s_setprio 1
	v_mfma_f32_16x16x32_bf16 v[36:39], v[150:153], v[162:165], v[36:39]
	v_mfma_f32_16x16x32_bf16 v[60:63], v[158:161], v[166:169], v[36:39]
	v_mfma_f32_16x16x32_bf16 v[36:39], v[86:89], v[170:173], v[44:47]
	v_mfma_f32_16x16x32_bf16 v[44:47], v[122:125], v[174:177], v[36:39]
	v_mfma_f32_16x16x32_bf16 v[36:39], v[150:153], v[170:173], v[48:51]
	v_mfma_f32_16x16x32_bf16 v[52:55], v[86:89], v[162:165], v[82:85]
	v_mfma_f32_16x16x32_bf16 v[56:59], v[158:161], v[174:177], v[36:39]
	v_mfma_f32_16x16x32_bf16 v[36:39], v[86:89], v[194:197], v[90:93]
	v_mfma_f32_16x16x32_bf16 v[48:51], v[150:153], v[194:197], v[154:157]
	v_mfma_f32_16x16x32_bf16 v[32:35], v[86:89], v[202:205], v[32:35]
	v_mfma_f32_16x16x32_bf16 v[40:43], v[150:153], v[202:205], v[40:43]
	v_mfma_f32_16x16x32_bf16 v[52:55], v[122:125], v[166:169], v[52:55]
	v_mfma_f32_16x16x32_bf16 v[36:39], v[122:125], v[198:201], v[36:39]
	v_mfma_f32_16x16x32_bf16 v[48:51], v[158:161], v[198:201], v[48:51]
	v_mfma_f32_16x16x32_bf16 v[32:35], v[122:125], v[206:209], v[32:35]
	v_mfma_f32_16x16x32_bf16 v[40:43], v[158:161], v[206:209], v[40:43]
	s_setprio 0
	s_barrier
	s_mov_b32 m0, s41
	s_nop 0
	global_load_lds_dwordx4 v[64:65], off
	s_mov_b32 m0, s42
	s_nop 0
	global_load_lds_dwordx4 v[66:67], off
	s_mov_b32 m0, s45
	s_nop 0
	global_load_lds_dwordx4 v[72:73], off
	s_mov_b32 m0, s46
	s_nop 0
	global_load_lds_dwordx4 v[74:75], off
	s_mov_b32 m0, s43
	s_nop 0
	global_load_lds_dwordx4 v[68:69], off
	s_mov_b32 m0, s44
	s_nop 0
	global_load_lds_dwordx4 v[70:71], off
	s_waitcnt vmcnt(8)
	s_waitcnt lgkmcnt(0)
	s_barrier
	s_setprio 1
	s_setprio 0
	s_setprio 1
	s_setprio 0
	s_barrier
	s_cbranch_scc1 .LBB0_2411
	s_barrier
